# in-proj pair tiles: first A/B K-step of the next pair tile is requested (LDS-DMA into the two buffers above the epilogue image) right after the K loop, so both epilogues hide its latency; DMA issue sp
# speedup vs baseline: 1.3068x; 1.0028x over previous
.LBB0_193:
.LBB0_194:
	v_readlane_b32 s0, v254, 8
	v_readlane_b32 s1, v254, 9
	s_andn2_b64 vcc, exec, s[0:1]
	s_cbranch_vccnz .LBB0_292
	v_mov_b32_e32 v0, v151
	s_mul_i32 s11, s80, 0x700000
	v_readlane_b32 s0, v253, 30
	s_mul_hi_i32 s10, s80, 0x700000
	s_add_u32 s12, s0, s11
	v_readlane_b32 s0, v253, 31
	s_addc_u32 s13, s0, s10
	v_mov_b32_e32 v2, 0x13ff0
	ds_read_b64 v[2:3], v2
	s_waitcnt lgkmcnt(0)
	v_readfirstlane_b32 s101, v2
	v_readfirstlane_b32 s0, v3
	s_lshl_b32 s0, s0, 16
	s_or_b32 s101, s101, s0
	v_readlane_b32 s0, v254, 7
	s_movk_i32 s100, 0x100
	s_branch .Lip_j0
.LBB0_196:
	s_bfe_u32 s0, s100, 0x20008
	s_cmp_eq_u32 s0, 1
	s_cbranch_scc0 .Lip_next
	s_add_i32 s42, s42, 7
	s_and_b32 s100, s100, 0x10ff
	s_or_b32 s100, s100, 0x200
	s_branch .LBB0_197
.Lip_next:
	s_and_b32 s4, s100, 0x1000
	s_and_b32 s100, s100, 0xff
	s_add_i32 s100, s100, 1
	v_readlane_b32 s1, v254, 7
	s_cmp_lt_u32 s100, 5
	s_cbranch_scc0 .Lip_last
	s_lshl_b32 s0, s100, 6
	s_add_i32 s0, s0, s1
	s_or_b32 s100, s100, 0x100
	s_or_b32 s100, s100, s4
	s_branch .Lip_j0

.LBB0_203:
	s_lshl_b32 s0, s4, 7
	s_cmpk_lt_i32 s5, 0x700
	s_cselect_b64 s[44:45], -1, 0
	s_ashr_i32 s1, s0, 31
	s_lshl_b64 s[46:47], s[0:1], 11
	s_add_u32 s28, s94, s46
	s_addc_u32 s29, s95, s47
	s_ashr_i32 s41, s40, 31
	s_lshl_b64 s[38:39], s[40:41], 18
	s_add_u32 s48, s12, s38
	s_addc_u32 s49, s13, s39
	s_and_b32 s4, s4, -2
	s_add_i32 s4, s4, s80
	s_ashr_i32 s5, s4, 31
	s_and_b32 s6, s0, 0x80
	s_lshl_b64 s[14:15], s[4:5], 8
	s_andn2_b64 vcc, exec, s[86:87]
	s_or_b32 s14, s14, s6
	s_cbranch_vccz .LBB0_255
	s_bfe_u32 s4, s100, 0x20008
	s_cmp_eq_u32 s4, 0
	s_cbranch_scc1 .Lpk_sw_orig
	s_cmp_eq_u32 s4, 2
	s_cbranch_scc1 .Lpk_sw_unpark
	v_lshrrev_b32_e32 v0, 6, v151
	v_and_b32_e32 v218, 63, v151
	s_nop 0
	v_readfirstlane_b32 s5, v0
	v_lshrrev_b32_e32 v219, 4, v218
	v_and_b32_e32 v220, 7, v218
	v_xor_b32_e32 v220, v220, v219
	v_lshlrev_b32_e32 v220, 4, v220
	v_lshrrev_b32_e32 v219, 3, v218
	v_lshl_or_b32 v98, v219, 11, v220
	s_lshl_b32 s4, s5, 16
	v_add_u32_e32 v98, s4, v98
	v_xor_b32_e32 v99, 64, v98
	v_add_u32_e32 v99, 0x4000, v99
	v_add_u32_e32 v100, 0x8000, v98
	v_add_u32_e32 v101, 0x8000, v99
	v_and_b32_e32 v219, 15, v218
	v_lshrrev_b32_e32 v220, 4, v218
	v_bfe_u32 v218, v219, 1, 3
	v_xor_b32_e32 v220, v220, v218
	v_lshlrev_b32_e32 v220, 4, v220
	v_lshl_or_b32 v220, v219, 7, v220
	s_lshr_b32 s4, s5, 1
	s_lshl_b32 s4, s4, 13
	v_add_u32_e32 v102, s4, v220
	v_xor_b32_e32 v103, 64, v102
	s_and_b32 s4, s5, 1
	s_lshl_b32 s4, s4, 13
	v_add_u32_e32 v104, s4, v220
	v_xor_b32_e32 v105, 64, v104
	v_add_u32_e32 v250, 0x4000, v104
	v_add_u32_e32 v251, 0x4000, v105
	s_lshl_b32 s4, s5, 12
	s_add_u32 s6, s28, 0x40000
	s_addc_u32 s7, s29, 0
	s_barrier
	s_and_b32 s5, s100, 0x1000
	s_cmp_lg_u32 s5, 0
	s_cbranch_scc1 .Lpk_sw_pf
	s_add_u32 m0, s4, 0xc000
	s_nop 0
	global_load_lds_dwordx4 v98, s[28:29]
	s_add_u32 m0, s4, 0xc400
	s_nop 0
	global_load_lds_dwordx4 v99, s[28:29]
	s_add_u32 m0, s4, 0xc800
	s_nop 0
	global_load_lds_dwordx4 v100, s[28:29]
	s_add_u32 m0, s4, 0xcc00
	s_nop 0
	global_load_lds_dwordx4 v101, s[28:29]
	s_add_u32 m0, s4, 0x10000
	s_nop 0
	global_load_lds_dwordx4 v98, s[48:49]
	s_add_u32 m0, s4, 0x10400
	s_nop 0
	global_load_lds_dwordx4 v99, s[48:49]
	s_add_u32 m0, s4, 0x10800
	s_nop 0
	global_load_lds_dwordx4 v100, s[48:49]
	s_add_u32 m0, s4, 0x10c00
	s_nop 0
	global_load_lds_dwordx4 v101, s[48:49]
.Lpk_sw_pf:
	s_and_b32 s100, s100, 0xffffefff
	s_add_u32 m0, s4, 0x0
	s_nop 0
	global_load_lds_dwordx4 v98, s[6:7]
	s_add_u32 m0, s4, 0x400
	s_nop 0
	global_load_lds_dwordx4 v99, s[6:7]
	s_add_u32 m0, s4, 0x800
	s_nop 0
	global_load_lds_dwordx4 v100, s[6:7]
	s_add_u32 m0, s4, 0xc00
	s_nop 0
	global_load_lds_dwordx4 v101, s[6:7]
	v_add_u32_e32 v98, 0x80, v98
	v_add_u32_e32 v99, 0x80, v99
	v_add_u32_e32 v100, 0x80, v100
	v_add_u32_e32 v101, 0x80, v101
	v_mov_b32_e32 v62, 0
	v_mov_b32_e32 v106, 0
	v_mov_b32_e32 v63, 0
	v_mov_b32_e32 v107, 0
	v_mov_b32_e32 v64, 0
	v_mov_b32_e32 v108, 0
	v_mov_b32_e32 v65, 0
	v_mov_b32_e32 v109, 0
	v_mov_b32_e32 v58, 0
	v_mov_b32_e32 v110, 0
	v_mov_b32_e32 v59, 0
	v_mov_b32_e32 v111, 0
	v_mov_b32_e32 v60, 0
	v_mov_b32_e32 v112, 0
	v_mov_b32_e32 v61, 0
	v_mov_b32_e32 v113, 0
	v_mov_b32_e32 v54, 0
	v_mov_b32_e32 v114, 0
	v_mov_b32_e32 v55, 0
	v_mov_b32_e32 v115, 0
	v_mov_b32_e32 v56, 0
	v_mov_b32_e32 v116, 0
	v_mov_b32_e32 v57, 0
	v_mov_b32_e32 v117, 0
	v_mov_b32_e32 v50, 0
	v_mov_b32_e32 v118, 0
	v_mov_b32_e32 v51, 0
	v_mov_b32_e32 v119, 0
	v_mov_b32_e32 v52, 0
	v_mov_b32_e32 v120, 0
	v_mov_b32_e32 v53, 0
	v_mov_b32_e32 v121, 0
	v_mov_b32_e32 v46, 0
	v_mov_b32_e32 v122, 0
	v_mov_b32_e32 v47, 0
	v_mov_b32_e32 v123, 0
	v_mov_b32_e32 v48, 0
	v_mov_b32_e32 v124, 0
	v_mov_b32_e32 v49, 0
	v_mov_b32_e32 v125, 0
	v_mov_b32_e32 v42, 0
	v_mov_b32_e32 v126, 0
	v_mov_b32_e32 v43, 0
	v_mov_b32_e32 v127, 0
	v_mov_b32_e32 v44, 0
	v_mov_b32_e32 v128, 0
	v_mov_b32_e32 v45, 0
	v_mov_b32_e32 v129, 0
	v_mov_b32_e32 v38, 0
	v_mov_b32_e32 v130, 0
	v_mov_b32_e32 v39, 0
	v_mov_b32_e32 v131, 0
	v_mov_b32_e32 v40, 0
	v_mov_b32_e32 v132, 0
	v_mov_b32_e32 v41, 0
	v_mov_b32_e32 v133, 0
	v_mov_b32_e32 v34, 0
	v_mov_b32_e32 v134, 0
	v_mov_b32_e32 v35, 0
	v_mov_b32_e32 v135, 0
	v_mov_b32_e32 v36, 0
	v_mov_b32_e32 v136, 0
	v_mov_b32_e32 v37, 0
	v_mov_b32_e32 v137, 0
	v_mov_b32_e32 v30, 0
	v_mov_b32_e32 v138, 0
	v_mov_b32_e32 v31, 0
	v_mov_b32_e32 v139, 0
	v_mov_b32_e32 v32, 0
	v_mov_b32_e32 v140, 0
	v_mov_b32_e32 v33, 0
	v_mov_b32_e32 v141, 0
	v_mov_b32_e32 v26, 0
	v_mov_b32_e32 v142, 0
	v_mov_b32_e32 v27, 0
	v_mov_b32_e32 v143, 0
	v_mov_b32_e32 v28, 0
	v_mov_b32_e32 v144, 0
	v_mov_b32_e32 v29, 0
	v_mov_b32_e32 v145, 0
	v_mov_b32_e32 v22, 0
	v_mov_b32_e32 v154, 0
	v_mov_b32_e32 v23, 0
	v_mov_b32_e32 v155, 0
	v_mov_b32_e32 v24, 0
	v_mov_b32_e32 v156, 0
	v_mov_b32_e32 v25, 0
	v_mov_b32_e32 v157, 0
	v_mov_b32_e32 v18, 0
	v_mov_b32_e32 v158, 0
	v_mov_b32_e32 v19, 0
	v_mov_b32_e32 v159, 0
	v_mov_b32_e32 v20, 0
	v_mov_b32_e32 v160, 0
	v_mov_b32_e32 v21, 0
	v_mov_b32_e32 v161, 0
	v_mov_b32_e32 v14, 0
	v_mov_b32_e32 v162, 0
	v_mov_b32_e32 v15, 0
	v_mov_b32_e32 v163, 0
	v_mov_b32_e32 v16, 0
	v_mov_b32_e32 v164, 0
	v_mov_b32_e32 v17, 0
	v_mov_b32_e32 v165, 0
	v_mov_b32_e32 v10, 0
	v_mov_b32_e32 v166, 0
	v_mov_b32_e32 v11, 0
	v_mov_b32_e32 v167, 0
	v_mov_b32_e32 v12, 0
	v_mov_b32_e32 v168, 0
	v_mov_b32_e32 v13, 0
	v_mov_b32_e32 v169, 0
	v_mov_b32_e32 v6, 0
	v_mov_b32_e32 v170, 0
	v_mov_b32_e32 v7, 0
	v_mov_b32_e32 v171, 0
	v_mov_b32_e32 v8, 0
	v_mov_b32_e32 v172, 0
	v_mov_b32_e32 v9, 0
	v_mov_b32_e32 v173, 0
	v_mov_b32_e32 v2, 0
	v_mov_b32_e32 v174, 0
	v_mov_b32_e32 v3, 0
	v_mov_b32_e32 v175, 0
	v_mov_b32_e32 v4, 0
	v_mov_b32_e32 v176, 0
	v_mov_b32_e32 v5, 0
	v_mov_b32_e32 v177, 0
	s_waitcnt vmcnt(4)
	s_barrier
	ds_read_b128 v[218:221], v102 offset:49152
	ds_read_b128 v[222:225], v102 offset:51200
	ds_read_b128 v[226:229], v102 offset:53248
	ds_read_b128 v[230:233], v102 offset:55296
	ds_read_b128 v[66:69], v250 offset:49152
	ds_read_b128 v[70:73], v250 offset:51200
	ds_read_b128 v[74:77], v250 offset:53248
	ds_read_b128 v[78:81], v250 offset:55296
	ds_read_b128 v[234:237], v103 offset:49152
	ds_read_b128 v[238:241], v103 offset:51200
	ds_read_b128 v[242:245], v103 offset:53248
	ds_read_b128 v[246:249], v103 offset:55296
	ds_read_b128 v[82:85], v251 offset:49152
	ds_read_b128 v[86:89], v251 offset:51200
	ds_read_b128 v[90:93], v251 offset:53248
	ds_read_b128 v[94:97], v251 offset:55296
	s_waitcnt lgkmcnt(8)
	v_mfma_f32_16x16x32_bf16 v[62:65], v[66:69], v[218:221], v[62:65]
	s_add_u32 m0, s4, 0x4000
	v_mfma_f32_16x16x32_bf16 v[46:49], v[66:69], v[222:225], v[46:49]
	global_load_lds_dwordx4 v98, s[28:29]
	v_mfma_f32_16x16x32_bf16 v[30:33], v[66:69], v[226:229], v[30:33]
	v_mfma_f32_16x16x32_bf16 v[14:17], v[66:69], v[230:233], v[14:17]
	v_mfma_f32_16x16x32_bf16 v[58:61], v[70:73], v[218:221], v[58:61]
	s_add_u32 m0, s4, 0x4400
	v_mfma_f32_16x16x32_bf16 v[42:45], v[70:73], v[222:225], v[42:45]
	global_load_lds_dwordx4 v99, s[28:29]
	v_mfma_f32_16x16x32_bf16 v[26:29], v[70:73], v[226:229], v[26:29]
	v_mfma_f32_16x16x32_bf16 v[10:13], v[70:73], v[230:233], v[10:13]
	v_mfma_f32_16x16x32_bf16 v[54:57], v[74:77], v[218:221], v[54:57]
	s_add_u32 m0, s4, 0x4800
	v_mfma_f32_16x16x32_bf16 v[38:41], v[74:77], v[222:225], v[38:41]
	global_load_lds_dwordx4 v100, s[28:29]
	v_mfma_f32_16x16x32_bf16 v[22:25], v[74:77], v[226:229], v[22:25]
	v_mfma_f32_16x16x32_bf16 v[6:9], v[74:77], v[230:233], v[6:9]
	v_mfma_f32_16x16x32_bf16 v[50:53], v[78:81], v[218:221], v[50:53]
	s_add_u32 m0, s4, 0x4c00
	v_mfma_f32_16x16x32_bf16 v[34:37], v[78:81], v[222:225], v[34:37]
	global_load_lds_dwordx4 v101, s[28:29]
	v_mfma_f32_16x16x32_bf16 v[18:21], v[78:81], v[226:229], v[18:21]
	v_mfma_f32_16x16x32_bf16 v[2:5], v[78:81], v[230:233], v[2:5]
	s_waitcnt lgkmcnt(0)
	v_mfma_f32_16x16x32_bf16 v[62:65], v[82:85], v[234:237], v[62:65]
	s_add_u32 m0, s4, 0x8000
	v_mfma_f32_16x16x32_bf16 v[46:49], v[82:85], v[238:241], v[46:49]
	global_load_lds_dwordx4 v98, s[48:49]
	v_mfma_f32_16x16x32_bf16 v[30:33], v[82:85], v[242:245], v[30:33]
	v_mfma_f32_16x16x32_bf16 v[14:17], v[82:85], v[246:249], v[14:17]
	v_mfma_f32_16x16x32_bf16 v[58:61], v[86:89], v[234:237], v[58:61]
	s_add_u32 m0, s4, 0x8400
	v_mfma_f32_16x16x32_bf16 v[42:45], v[86:89], v[238:241], v[42:45]
	global_load_lds_dwordx4 v99, s[48:49]
	v_mfma_f32_16x16x32_bf16 v[26:29], v[86:89], v[242:245], v[26:29]
	v_mfma_f32_16x16x32_bf16 v[10:13], v[86:89], v[246:249], v[10:13]
	v_mfma_f32_16x16x32_bf16 v[54:57], v[90:93], v[234:237], v[54:57]
	s_add_u32 m0, s4, 0x8800
	v_mfma_f32_16x16x32_bf16 v[38:41], v[90:93], v[238:241], v[38:41]
	global_load_lds_dwordx4 v100, s[48:49]
	v_mfma_f32_16x16x32_bf16 v[22:25], v[90:93], v[242:245], v[22:25]
	v_mfma_f32_16x16x32_bf16 v[6:9], v[90:93], v[246:249], v[6:9]
	v_mfma_f32_16x16x32_bf16 v[50:53], v[94:97], v[234:237], v[50:53]
	s_add_u32 m0, s4, 0x8c00
	v_mfma_f32_16x16x32_bf16 v[34:37], v[94:97], v[238:241], v[34:37]
	global_load_lds_dwordx4 v101, s[48:49]
	v_mfma_f32_16x16x32_bf16 v[18:21], v[94:97], v[242:245], v[18:21]
	v_mfma_f32_16x16x32_bf16 v[2:5], v[94:97], v[246:249], v[2:5]
	s_waitcnt vmcnt(8)
	s_barrier
	ds_read_b128 v[218:221], v102 offset:0
	ds_read_b128 v[222:225], v102 offset:2048
	ds_read_b128 v[226:229], v102 offset:4096
	ds_read_b128 v[230:233], v102 offset:6144
	ds_read_b128 v[234:237], v103 offset:0
	ds_read_b128 v[238:241], v103 offset:2048
	ds_read_b128 v[242:245], v103 offset:4096
	ds_read_b128 v[246:249], v103 offset:6144
	s_waitcnt lgkmcnt(4)
	v_mfma_f32_16x16x32_bf16 v[106:109], v[66:69], v[218:221], v[106:109]
	s_add_u32 m0, s4, 0xc000
	v_mfma_f32_16x16x32_bf16 v[122:125], v[66:69], v[222:225], v[122:125]
	global_load_lds_dwordx4 v98, s[6:7]
	v_mfma_f32_16x16x32_bf16 v[138:141], v[66:69], v[226:229], v[138:141]
	v_mfma_f32_16x16x32_bf16 v[162:165], v[66:69], v[230:233], v[162:165]
	v_mfma_f32_16x16x32_bf16 v[110:113], v[70:73], v[218:221], v[110:113]
	s_add_u32 m0, s4, 0xc400
	v_mfma_f32_16x16x32_bf16 v[126:129], v[70:73], v[222:225], v[126:129]
	global_load_lds_dwordx4 v99, s[6:7]
	v_mfma_f32_16x16x32_bf16 v[142:145], v[70:73], v[226:229], v[142:145]
	v_mfma_f32_16x16x32_bf16 v[166:169], v[70:73], v[230:233], v[166:169]
	v_mfma_f32_16x16x32_bf16 v[114:117], v[74:77], v[218:221], v[114:117]
	s_add_u32 m0, s4, 0xc800
	v_mfma_f32_16x16x32_bf16 v[130:133], v[74:77], v[222:225], v[130:133]
	global_load_lds_dwordx4 v100, s[6:7]
	v_mfma_f32_16x16x32_bf16 v[154:157], v[74:77], v[226:229], v[154:157]
	v_mfma_f32_16x16x32_bf16 v[170:173], v[74:77], v[230:233], v[170:173]
	v_mfma_f32_16x16x32_bf16 v[118:121], v[78:81], v[218:221], v[118:121]
	s_add_u32 m0, s4, 0xcc00
	v_mfma_f32_16x16x32_bf16 v[134:137], v[78:81], v[222:225], v[134:137]
	global_load_lds_dwordx4 v101, s[6:7]
	v_mfma_f32_16x16x32_bf16 v[158:161], v[78:81], v[226:229], v[158:161]
	v_mfma_f32_16x16x32_bf16 v[174:177], v[78:81], v[230:233], v[174:177]
	v_add_u32_e32 v98, 0x80, v98
	v_add_u32_e32 v99, 0x80, v99
	v_add_u32_e32 v100, 0x80, v100
	v_add_u32_e32 v101, 0x80, v101
	s_waitcnt lgkmcnt(0)
	v_mfma_f32_16x16x32_bf16 v[106:109], v[82:85], v[234:237], v[106:109]
	v_mfma_f32_16x16x32_bf16 v[122:125], v[82:85], v[238:241], v[122:125]
	v_mfma_f32_16x16x32_bf16 v[138:141], v[82:85], v[242:245], v[138:141]
	v_mfma_f32_16x16x32_bf16 v[162:165], v[82:85], v[246:249], v[162:165]
	v_mfma_f32_16x16x32_bf16 v[110:113], v[86:89], v[234:237], v[110:113]
	v_mfma_f32_16x16x32_bf16 v[126:129], v[86:89], v[238:241], v[126:129]
	v_mfma_f32_16x16x32_bf16 v[142:145], v[86:89], v[242:245], v[142:145]
	v_mfma_f32_16x16x32_bf16 v[166:169], v[86:89], v[246:249], v[166:169]
	v_mfma_f32_16x16x32_bf16 v[114:117], v[90:93], v[234:237], v[114:117]
	v_mfma_f32_16x16x32_bf16 v[130:133], v[90:93], v[238:241], v[130:133]
	v_mfma_f32_16x16x32_bf16 v[154:157], v[90:93], v[242:245], v[154:157]
	v_mfma_f32_16x16x32_bf16 v[170:173], v[90:93], v[246:249], v[170:173]
	v_mfma_f32_16x16x32_bf16 v[118:121], v[94:97], v[234:237], v[118:121]
	v_mfma_f32_16x16x32_bf16 v[134:137], v[94:97], v[238:241], v[134:137]
	v_mfma_f32_16x16x32_bf16 v[158:161], v[94:97], v[242:245], v[158:161]
	v_mfma_f32_16x16x32_bf16 v[174:177], v[94:97], v[246:249], v[174:177]
	s_waitcnt vmcnt(4)
	s_barrier
	ds_read_b128 v[218:221], v102 offset:16384
	ds_read_b128 v[222:225], v102 offset:18432
	ds_read_b128 v[226:229], v102 offset:20480
	ds_read_b128 v[230:233], v102 offset:22528
	ds_read_b128 v[66:69], v104 offset:32768
	ds_read_b128 v[70:73], v104 offset:34816
	ds_read_b128 v[74:77], v104 offset:36864
	ds_read_b128 v[78:81], v104 offset:38912
	ds_read_b128 v[234:237], v103 offset:16384
	ds_read_b128 v[238:241], v103 offset:18432
	ds_read_b128 v[242:245], v103 offset:20480
	ds_read_b128 v[246:249], v103 offset:22528
	ds_read_b128 v[82:85], v105 offset:32768
	ds_read_b128 v[86:89], v105 offset:34816
	ds_read_b128 v[90:93], v105 offset:36864
	ds_read_b128 v[94:97], v105 offset:38912
	s_waitcnt lgkmcnt(8)
	v_mfma_f32_16x16x32_bf16 v[62:65], v[66:69], v[218:221], v[62:65]
	s_add_u32 m0, s4, 0x0
	v_mfma_f32_16x16x32_bf16 v[46:49], v[66:69], v[222:225], v[46:49]
	global_load_lds_dwordx4 v98, s[28:29]
	v_mfma_f32_16x16x32_bf16 v[30:33], v[66:69], v[226:229], v[30:33]
	v_mfma_f32_16x16x32_bf16 v[14:17], v[66:69], v[230:233], v[14:17]
	v_mfma_f32_16x16x32_bf16 v[58:61], v[70:73], v[218:221], v[58:61]
	s_add_u32 m0, s4, 0x400
	v_mfma_f32_16x16x32_bf16 v[42:45], v[70:73], v[222:225], v[42:45]
	global_load_lds_dwordx4 v99, s[28:29]
	v_mfma_f32_16x16x32_bf16 v[26:29], v[70:73], v[226:229], v[26:29]
	v_mfma_f32_16x16x32_bf16 v[10:13], v[70:73], v[230:233], v[10:13]
	v_mfma_f32_16x16x32_bf16 v[54:57], v[74:77], v[218:221], v[54:57]
	s_add_u32 m0, s4, 0x800
	v_mfma_f32_16x16x32_bf16 v[38:41], v[74:77], v[222:225], v[38:41]
	global_load_lds_dwordx4 v100, s[28:29]
	v_mfma_f32_16x16x32_bf16 v[22:25], v[74:77], v[226:229], v[22:25]
	v_mfma_f32_16x16x32_bf16 v[6:9], v[74:77], v[230:233], v[6:9]
	v_mfma_f32_16x16x32_bf16 v[50:53], v[78:81], v[218:221], v[50:53]
	s_add_u32 m0, s4, 0xc00
	v_mfma_f32_16x16x32_bf16 v[34:37], v[78:81], v[222:225], v[34:37]
	global_load_lds_dwordx4 v101, s[28:29]
	v_mfma_f32_16x16x32_bf16 v[18:21], v[78:81], v[226:229], v[18:21]
	v_mfma_f32_16x16x32_bf16 v[2:5], v[78:81], v[230:233], v[2:5]
	s_waitcnt lgkmcnt(0)
	v_mfma_f32_16x16x32_bf16 v[62:65], v[82:85], v[234:237], v[62:65]
	s_add_u32 m0, s4, 0x10000
	v_mfma_f32_16x16x32_bf16 v[46:49], v[82:85], v[238:241], v[46:49]
	global_load_lds_dwordx4 v98, s[48:49]
	v_mfma_f32_16x16x32_bf16 v[30:33], v[82:85], v[242:245], v[30:33]
	v_mfma_f32_16x16x32_bf16 v[14:17], v[82:85], v[246:249], v[14:17]
	v_mfma_f32_16x16x32_bf16 v[58:61], v[86:89], v[234:237], v[58:61]
	s_add_u32 m0, s4, 0x10400
	v_mfma_f32_16x16x32_bf16 v[42:45], v[86:89], v[238:241], v[42:45]
	global_load_lds_dwordx4 v99, s[48:49]
	v_mfma_f32_16x16x32_bf16 v[26:29], v[86:89], v[242:245], v[26:29]
	v_mfma_f32_16x16x32_bf16 v[10:13], v[86:89], v[246:249], v[10:13]
	v_mfma_f32_16x16x32_bf16 v[54:57], v[90:93], v[234:237], v[54:57]
	s_add_u32 m0, s4, 0x10800
	v_mfma_f32_16x16x32_bf16 v[38:41], v[90:93], v[238:241], v[38:41]
	global_load_lds_dwordx4 v100, s[48:49]
	v_mfma_f32_16x16x32_bf16 v[22:25], v[90:93], v[242:245], v[22:25]
	v_mfma_f32_16x16x32_bf16 v[6:9], v[90:93], v[246:249], v[6:9]
	v_mfma_f32_16x16x32_bf16 v[50:53], v[94:97], v[234:237], v[50:53]
	s_add_u32 m0, s4, 0x10c00
	v_mfma_f32_16x16x32_bf16 v[34:37], v[94:97], v[238:241], v[34:37]
	global_load_lds_dwordx4 v101, s[48:49]
	v_mfma_f32_16x16x32_bf16 v[18:21], v[94:97], v[242:245], v[18:21]
	v_mfma_f32_16x16x32_bf16 v[2:5], v[94:97], v[246:249], v[2:5]
	s_waitcnt vmcnt(8)
	s_barrier
	ds_read_b128 v[218:221], v102 offset:49152
	ds_read_b128 v[222:225], v102 offset:51200
	ds_read_b128 v[226:229], v102 offset:53248
	ds_read_b128 v[230:233], v102 offset:55296
	ds_read_b128 v[234:237], v103 offset:49152
	ds_read_b128 v[238:241], v103 offset:51200
	ds_read_b128 v[242:245], v103 offset:53248
	ds_read_b128 v[246:249], v103 offset:55296
	s_waitcnt lgkmcnt(4)
	v_mfma_f32_16x16x32_bf16 v[106:109], v[66:69], v[218:221], v[106:109]
	s_add_u32 m0, s4, 0x4000
	v_mfma_f32_16x16x32_bf16 v[122:125], v[66:69], v[222:225], v[122:125]
	global_load_lds_dwordx4 v98, s[6:7]
	v_mfma_f32_16x16x32_bf16 v[138:141], v[66:69], v[226:229], v[138:141]
	v_mfma_f32_16x16x32_bf16 v[162:165], v[66:69], v[230:233], v[162:165]
	v_mfma_f32_16x16x32_bf16 v[110:113], v[70:73], v[218:221], v[110:113]
	s_add_u32 m0, s4, 0x4400
	v_mfma_f32_16x16x32_bf16 v[126:129], v[70:73], v[222:225], v[126:129]
	global_load_lds_dwordx4 v99, s[6:7]
	v_mfma_f32_16x16x32_bf16 v[142:145], v[70:73], v[226:229], v[142:145]
	v_mfma_f32_16x16x32_bf16 v[166:169], v[70:73], v[230:233], v[166:169]
	v_mfma_f32_16x16x32_bf16 v[114:117], v[74:77], v[218:221], v[114:117]
	s_add_u32 m0, s4, 0x4800
	v_mfma_f32_16x16x32_bf16 v[130:133], v[74:77], v[222:225], v[130:133]
	global_load_lds_dwordx4 v100, s[6:7]
	v_mfma_f32_16x16x32_bf16 v[154:157], v[74:77], v[226:229], v[154:157]
	v_mfma_f32_16x16x32_bf16 v[170:173], v[74:77], v[230:233], v[170:173]
	v_mfma_f32_16x16x32_bf16 v[118:121], v[78:81], v[218:221], v[118:121]
	s_add_u32 m0, s4, 0x4c00
	v_mfma_f32_16x16x32_bf16 v[134:137], v[78:81], v[222:225], v[134:137]
	global_load_lds_dwordx4 v101, s[6:7]
	v_mfma_f32_16x16x32_bf16 v[158:161], v[78:81], v[226:229], v[158:161]
	v_mfma_f32_16x16x32_bf16 v[174:177], v[78:81], v[230:233], v[174:177]
	v_add_u32_e32 v98, 0x80, v98
	v_add_u32_e32 v99, 0x80, v99
	v_add_u32_e32 v100, 0x80, v100
	v_add_u32_e32 v101, 0x80, v101
	s_waitcnt lgkmcnt(0)
	v_mfma_f32_16x16x32_bf16 v[106:109], v[82:85], v[234:237], v[106:109]
	v_mfma_f32_16x16x32_bf16 v[122:125], v[82:85], v[238:241], v[122:125]
	v_mfma_f32_16x16x32_bf16 v[138:141], v[82:85], v[242:245], v[138:141]
	v_mfma_f32_16x16x32_bf16 v[162:165], v[82:85], v[246:249], v[162:165]
	v_mfma_f32_16x16x32_bf16 v[110:113], v[86:89], v[234:237], v[110:113]
	v_mfma_f32_16x16x32_bf16 v[126:129], v[86:89], v[238:241], v[126:129]
	v_mfma_f32_16x16x32_bf16 v[142:145], v[86:89], v[242:245], v[142:145]
	v_mfma_f32_16x16x32_bf16 v[166:169], v[86:89], v[246:249], v[166:169]
	v_mfma_f32_16x16x32_bf16 v[114:117], v[90:93], v[234:237], v[114:117]
	v_mfma_f32_16x16x32_bf16 v[130:133], v[90:93], v[238:241], v[130:133]
	v_mfma_f32_16x16x32_bf16 v[154:157], v[90:93], v[242:245], v[154:157]
	v_mfma_f32_16x16x32_bf16 v[170:173], v[90:93], v[246:249], v[170:173]
	v_mfma_f32_16x16x32_bf16 v[118:121], v[94:97], v[234:237], v[118:121]
	v_mfma_f32_16x16x32_bf16 v[134:137], v[94:97], v[238:241], v[134:137]
	v_mfma_f32_16x16x32_bf16 v[158:161], v[94:97], v[242:245], v[158:161]
	v_mfma_f32_16x16x32_bf16 v[174:177], v[94:97], v[246:249], v[174:177]
	s_waitcnt vmcnt(4)
	s_barrier
	ds_read_b128 v[218:221], v102 offset:0
	ds_read_b128 v[222:225], v102 offset:2048
	ds_read_b128 v[226:229], v102 offset:4096
	ds_read_b128 v[230:233], v102 offset:6144
	ds_read_b128 v[66:69], v250 offset:49152
	ds_read_b128 v[70:73], v250 offset:51200
	ds_read_b128 v[74:77], v250 offset:53248
	ds_read_b128 v[78:81], v250 offset:55296
	ds_read_b128 v[234:237], v103 offset:0
	ds_read_b128 v[238:241], v103 offset:2048
	ds_read_b128 v[242:245], v103 offset:4096
	ds_read_b128 v[246:249], v103 offset:6144
	ds_read_b128 v[82:85], v251 offset:49152
	ds_read_b128 v[86:89], v251 offset:51200
	ds_read_b128 v[90:93], v251 offset:53248
	ds_read_b128 v[94:97], v251 offset:55296
	s_waitcnt lgkmcnt(8)
	v_mfma_f32_16x16x32_bf16 v[62:65], v[66:69], v[218:221], v[62:65]
	s_add_u32 m0, s4, 0xc000
	v_mfma_f32_16x16x32_bf16 v[46:49], v[66:69], v[222:225], v[46:49]
	global_load_lds_dwordx4 v98, s[28:29]
	v_mfma_f32_16x16x32_bf16 v[30:33], v[66:69], v[226:229], v[30:33]
	v_mfma_f32_16x16x32_bf16 v[14:17], v[66:69], v[230:233], v[14:17]
	v_mfma_f32_16x16x32_bf16 v[58:61], v[70:73], v[218:221], v[58:61]
	s_add_u32 m0, s4, 0xc400
	v_mfma_f32_16x16x32_bf16 v[42:45], v[70:73], v[222:225], v[42:45]
	global_load_lds_dwordx4 v99, s[28:29]
	v_mfma_f32_16x16x32_bf16 v[26:29], v[70:73], v[226:229], v[26:29]
	v_mfma_f32_16x16x32_bf16 v[10:13], v[70:73], v[230:233], v[10:13]
	v_mfma_f32_16x16x32_bf16 v[54:57], v[74:77], v[218:221], v[54:57]
	s_add_u32 m0, s4, 0xc800
	v_mfma_f32_16x16x32_bf16 v[38:41], v[74:77], v[222:225], v[38:41]
	global_load_lds_dwordx4 v100, s[28:29]
	v_mfma_f32_16x16x32_bf16 v[22:25], v[74:77], v[226:229], v[22:25]
	v_mfma_f32_16x16x32_bf16 v[6:9], v[74:77], v[230:233], v[6:9]
	v_mfma_f32_16x16x32_bf16 v[50:53], v[78:81], v[218:221], v[50:53]
	s_add_u32 m0, s4, 0xcc00
	v_mfma_f32_16x16x32_bf16 v[34:37], v[78:81], v[222:225], v[34:37]
	global_load_lds_dwordx4 v101, s[28:29]
	v_mfma_f32_16x16x32_bf16 v[18:21], v[78:81], v[226:229], v[18:21]
	v_mfma_f32_16x16x32_bf16 v[2:5], v[78:81], v[230:233], v[2:5]
	s_waitcnt lgkmcnt(0)
	v_mfma_f32_16x16x32_bf16 v[62:65], v[82:85], v[234:237], v[62:65]
	s_add_u32 m0, s4, 0x8000
	v_mfma_f32_16x16x32_bf16 v[46:49], v[82:85], v[238:241], v[46:49]
	global_load_lds_dwordx4 v98, s[48:49]
	v_mfma_f32_16x16x32_bf16 v[30:33], v[82:85], v[242:245], v[30:33]
	v_mfma_f32_16x16x32_bf16 v[14:17], v[82:85], v[246:249], v[14:17]
	v_mfma_f32_16x16x32_bf16 v[58:61], v[86:89], v[234:237], v[58:61]
	s_add_u32 m0, s4, 0x8400
	v_mfma_f32_16x16x32_bf16 v[42:45], v[86:89], v[238:241], v[42:45]
	global_load_lds_dwordx4 v99, s[48:49]
	v_mfma_f32_16x16x32_bf16 v[26:29], v[86:89], v[242:245], v[26:29]
	v_mfma_f32_16x16x32_bf16 v[10:13], v[86:89], v[246:249], v[10:13]
	v_mfma_f32_16x16x32_bf16 v[54:57], v[90:93], v[234:237], v[54:57]
	s_add_u32 m0, s4, 0x8800
	v_mfma_f32_16x16x32_bf16 v[38:41], v[90:93], v[238:241], v[38:41]
	global_load_lds_dwordx4 v100, s[48:49]
	v_mfma_f32_16x16x32_bf16 v[22:25], v[90:93], v[242:245], v[22:25]
	v_mfma_f32_16x16x32_bf16 v[6:9], v[90:93], v[246:249], v[6:9]
	v_mfma_f32_16x16x32_bf16 v[50:53], v[94:97], v[234:237], v[50:53]
	s_add_u32 m0, s4, 0x8c00
	v_mfma_f32_16x16x32_bf16 v[34:37], v[94:97], v[238:241], v[34:37]
	global_load_lds_dwordx4 v101, s[48:49]
	v_mfma_f32_16x16x32_bf16 v[18:21], v[94:97], v[242:245], v[18:21]
	v_mfma_f32_16x16x32_bf16 v[2:5], v[94:97], v[246:249], v[2:5]
	s_waitcnt vmcnt(8)
	s_barrier
	ds_read_b128 v[218:221], v102 offset:16384
	ds_read_b128 v[222:225], v102 offset:18432
	ds_read_b128 v[226:229], v102 offset:20480
	ds_read_b128 v[230:233], v102 offset:22528
	ds_read_b128 v[234:237], v103 offset:16384
	ds_read_b128 v[238:241], v103 offset:18432
	ds_read_b128 v[242:245], v103 offset:20480
	ds_read_b128 v[246:249], v103 offset:22528
	s_waitcnt lgkmcnt(4)
	v_mfma_f32_16x16x32_bf16 v[106:109], v[66:69], v[218:221], v[106:109]
	s_add_u32 m0, s4, 0x0
	v_mfma_f32_16x16x32_bf16 v[122:125], v[66:69], v[222:225], v[122:125]
	global_load_lds_dwordx4 v98, s[6:7]
	v_mfma_f32_16x16x32_bf16 v[138:141], v[66:69], v[226:229], v[138:141]
	v_mfma_f32_16x16x32_bf16 v[162:165], v[66:69], v[230:233], v[162:165]
	v_mfma_f32_16x16x32_bf16 v[110:113], v[70:73], v[218:221], v[110:113]
	s_add_u32 m0, s4, 0x400
	v_mfma_f32_16x16x32_bf16 v[126:129], v[70:73], v[222:225], v[126:129]
	global_load_lds_dwordx4 v99, s[6:7]
	v_mfma_f32_16x16x32_bf16 v[142:145], v[70:73], v[226:229], v[142:145]
	v_mfma_f32_16x16x32_bf16 v[166:169], v[70:73], v[230:233], v[166:169]
	v_mfma_f32_16x16x32_bf16 v[114:117], v[74:77], v[218:221], v[114:117]
	s_add_u32 m0, s4, 0x800
	v_mfma_f32_16x16x32_bf16 v[130:133], v[74:77], v[222:225], v[130:133]
	global_load_lds_dwordx4 v100, s[6:7]
	v_mfma_f32_16x16x32_bf16 v[154:157], v[74:77], v[226:229], v[154:157]
	v_mfma_f32_16x16x32_bf16 v[170:173], v[74:77], v[230:233], v[170:173]
	v_mfma_f32_16x16x32_bf16 v[118:121], v[78:81], v[218:221], v[118:121]
	s_add_u32 m0, s4, 0xc00
	v_mfma_f32_16x16x32_bf16 v[134:137], v[78:81], v[222:225], v[134:137]
	global_load_lds_dwordx4 v101, s[6:7]
	v_mfma_f32_16x16x32_bf16 v[158:161], v[78:81], v[226:229], v[158:161]
	v_mfma_f32_16x16x32_bf16 v[174:177], v[78:81], v[230:233], v[174:177]
	v_add_u32_e32 v98, 0x80, v98
	v_add_u32_e32 v99, 0x80, v99
	v_add_u32_e32 v100, 0x80, v100
	v_add_u32_e32 v101, 0x80, v101
	s_waitcnt lgkmcnt(0)
	v_mfma_f32_16x16x32_bf16 v[106:109], v[82:85], v[234:237], v[106:109]
	v_mfma_f32_16x16x32_bf16 v[122:125], v[82:85], v[238:241], v[122:125]
	v_mfma_f32_16x16x32_bf16 v[138:141], v[82:85], v[242:245], v[138:141]
	v_mfma_f32_16x16x32_bf16 v[162:165], v[82:85], v[246:249], v[162:165]
	v_mfma_f32_16x16x32_bf16 v[110:113], v[86:89], v[234:237], v[110:113]
	v_mfma_f32_16x16x32_bf16 v[126:129], v[86:89], v[238:241], v[126:129]
	v_mfma_f32_16x16x32_bf16 v[142:145], v[86:89], v[242:245], v[142:145]
	v_mfma_f32_16x16x32_bf16 v[166:169], v[86:89], v[246:249], v[166:169]
	v_mfma_f32_16x16x32_bf16 v[114:117], v[90:93], v[234:237], v[114:117]
	v_mfma_f32_16x16x32_bf16 v[130:133], v[90:93], v[238:241], v[130:133]
	v_mfma_f32_16x16x32_bf16 v[154:157], v[90:93], v[242:245], v[154:157]
	v_mfma_f32_16x16x32_bf16 v[170:173], v[90:93], v[246:249], v[170:173]
	v_mfma_f32_16x16x32_bf16 v[118:121], v[94:97], v[234:237], v[118:121]
	v_mfma_f32_16x16x32_bf16 v[134:137], v[94:97], v[238:241], v[134:137]
	v_mfma_f32_16x16x32_bf16 v[158:161], v[94:97], v[242:245], v[158:161]
	v_mfma_f32_16x16x32_bf16 v[174:177], v[94:97], v[246:249], v[174:177]
	s_waitcnt vmcnt(4)
	s_barrier
	ds_read_b128 v[218:221], v102 offset:49152
	ds_read_b128 v[222:225], v102 offset:51200
	ds_read_b128 v[226:229], v102 offset:53248
	ds_read_b128 v[230:233], v102 offset:55296
	ds_read_b128 v[66:69], v104 offset:32768
	ds_read_b128 v[70:73], v104 offset:34816
	ds_read_b128 v[74:77], v104 offset:36864
	ds_read_b128 v[78:81], v104 offset:38912
	ds_read_b128 v[234:237], v103 offset:49152
	ds_read_b128 v[238:241], v103 offset:51200
	ds_read_b128 v[242:245], v103 offset:53248
	ds_read_b128 v[246:249], v103 offset:55296
	ds_read_b128 v[82:85], v105 offset:32768
	ds_read_b128 v[86:89], v105 offset:34816
	ds_read_b128 v[90:93], v105 offset:36864
	ds_read_b128 v[94:97], v105 offset:38912
	s_waitcnt lgkmcnt(8)
	v_mfma_f32_16x16x32_bf16 v[62:65], v[66:69], v[218:221], v[62:65]
	s_add_u32 m0, s4, 0x4000
	v_mfma_f32_16x16x32_bf16 v[46:49], v[66:69], v[222:225], v[46:49]
	global_load_lds_dwordx4 v98, s[28:29]
	v_mfma_f32_16x16x32_bf16 v[30:33], v[66:69], v[226:229], v[30:33]
	v_mfma_f32_16x16x32_bf16 v[14:17], v[66:69], v[230:233], v[14:17]
	v_mfma_f32_16x16x32_bf16 v[58:61], v[70:73], v[218:221], v[58:61]
	s_add_u32 m0, s4, 0x4400
	v_mfma_f32_16x16x32_bf16 v[42:45], v[70:73], v[222:225], v[42:45]
	global_load_lds_dwordx4 v99, s[28:29]
	v_mfma_f32_16x16x32_bf16 v[26:29], v[70:73], v[226:229], v[26:29]
	v_mfma_f32_16x16x32_bf16 v[10:13], v[70:73], v[230:233], v[10:13]
	v_mfma_f32_16x16x32_bf16 v[54:57], v[74:77], v[218:221], v[54:57]
	s_add_u32 m0, s4, 0x4800
	v_mfma_f32_16x16x32_bf16 v[38:41], v[74:77], v[222:225], v[38:41]
	global_load_lds_dwordx4 v100, s[28:29]
	v_mfma_f32_16x16x32_bf16 v[22:25], v[74:77], v[226:229], v[22:25]
	v_mfma_f32_16x16x32_bf16 v[6:9], v[74:77], v[230:233], v[6:9]
	v_mfma_f32_16x16x32_bf16 v[50:53], v[78:81], v[218:221], v[50:53]
	s_add_u32 m0, s4, 0x4c00
	v_mfma_f32_16x16x32_bf16 v[34:37], v[78:81], v[222:225], v[34:37]
	global_load_lds_dwordx4 v101, s[28:29]
	v_mfma_f32_16x16x32_bf16 v[18:21], v[78:81], v[226:229], v[18:21]
	v_mfma_f32_16x16x32_bf16 v[2:5], v[78:81], v[230:233], v[2:5]
	s_waitcnt lgkmcnt(0)
	v_mfma_f32_16x16x32_bf16 v[62:65], v[82:85], v[234:237], v[62:65]
	s_add_u32 m0, s4, 0x10000
	v_mfma_f32_16x16x32_bf16 v[46:49], v[82:85], v[238:241], v[46:49]
	global_load_lds_dwordx4 v98, s[48:49]
	v_mfma_f32_16x16x32_bf16 v[30:33], v[82:85], v[242:245], v[30:33]
	v_mfma_f32_16x16x32_bf16 v[14:17], v[82:85], v[246:249], v[14:17]
	v_mfma_f32_16x16x32_bf16 v[58:61], v[86:89], v[234:237], v[58:61]
	s_add_u32 m0, s4, 0x10400
	v_mfma_f32_16x16x32_bf16 v[42:45], v[86:89], v[238:241], v[42:45]
	global_load_lds_dwordx4 v99, s[48:49]
	v_mfma_f32_16x16x32_bf16 v[26:29], v[86:89], v[242:245], v[26:29]
	v_mfma_f32_16x16x32_bf16 v[10:13], v[86:89], v[246:249], v[10:13]
	v_mfma_f32_16x16x32_bf16 v[54:57], v[90:93], v[234:237], v[54:57]
	s_add_u32 m0, s4, 0x10800
	v_mfma_f32_16x16x32_bf16 v[38:41], v[90:93], v[238:241], v[38:41]
	global_load_lds_dwordx4 v100, s[48:49]
	v_mfma_f32_16x16x32_bf16 v[22:25], v[90:93], v[242:245], v[22:25]
	v_mfma_f32_16x16x32_bf16 v[6:9], v[90:93], v[246:249], v[6:9]
	v_mfma_f32_16x16x32_bf16 v[50:53], v[94:97], v[234:237], v[50:53]
	s_add_u32 m0, s4, 0x10c00
	v_mfma_f32_16x16x32_bf16 v[34:37], v[94:97], v[238:241], v[34:37]
	global_load_lds_dwordx4 v101, s[48:49]
	v_mfma_f32_16x16x32_bf16 v[18:21], v[94:97], v[242:245], v[18:21]
	v_mfma_f32_16x16x32_bf16 v[2:5], v[94:97], v[246:249], v[2:5]
	s_waitcnt vmcnt(8)
	s_barrier
	ds_read_b128 v[218:221], v102 offset:0
	ds_read_b128 v[222:225], v102 offset:2048
	ds_read_b128 v[226:229], v102 offset:4096
	ds_read_b128 v[230:233], v102 offset:6144
	ds_read_b128 v[234:237], v103 offset:0
	ds_read_b128 v[238:241], v103 offset:2048
	ds_read_b128 v[242:245], v103 offset:4096
	ds_read_b128 v[246:249], v103 offset:6144
	s_waitcnt lgkmcnt(4)
	v_mfma_f32_16x16x32_bf16 v[106:109], v[66:69], v[218:221], v[106:109]
	s_add_u32 m0, s4, 0xc000
	v_mfma_f32_16x16x32_bf16 v[122:125], v[66:69], v[222:225], v[122:125]
	global_load_lds_dwordx4 v98, s[6:7]
	v_mfma_f32_16x16x32_bf16 v[138:141], v[66:69], v[226:229], v[138:141]
	v_mfma_f32_16x16x32_bf16 v[162:165], v[66:69], v[230:233], v[162:165]
	v_mfma_f32_16x16x32_bf16 v[110:113], v[70:73], v[218:221], v[110:113]
	s_add_u32 m0, s4, 0xc400
	v_mfma_f32_16x16x32_bf16 v[126:129], v[70:73], v[222:225], v[126:129]
	global_load_lds_dwordx4 v99, s[6:7]
	v_mfma_f32_16x16x32_bf16 v[142:145], v[70:73], v[226:229], v[142:145]
	v_mfma_f32_16x16x32_bf16 v[166:169], v[70:73], v[230:233], v[166:169]
	v_mfma_f32_16x16x32_bf16 v[114:117], v[74:77], v[218:221], v[114:117]
	s_add_u32 m0, s4, 0xc800
	v_mfma_f32_16x16x32_bf16 v[130:133], v[74:77], v[222:225], v[130:133]
	global_load_lds_dwordx4 v100, s[6:7]
	v_mfma_f32_16x16x32_bf16 v[154:157], v[74:77], v[226:229], v[154:157]
	v_mfma_f32_16x16x32_bf16 v[170:173], v[74:77], v[230:233], v[170:173]
	v_mfma_f32_16x16x32_bf16 v[118:121], v[78:81], v[218:221], v[118:121]
	s_add_u32 m0, s4, 0xcc00
	v_mfma_f32_16x16x32_bf16 v[134:137], v[78:81], v[222:225], v[134:137]
	global_load_lds_dwordx4 v101, s[6:7]
	v_mfma_f32_16x16x32_bf16 v[158:161], v[78:81], v[226:229], v[158:161]
	v_mfma_f32_16x16x32_bf16 v[174:177], v[78:81], v[230:233], v[174:177]
	v_add_u32_e32 v98, 0x80, v98
	v_add_u32_e32 v99, 0x80, v99
	v_add_u32_e32 v100, 0x80, v100
	v_add_u32_e32 v101, 0x80, v101
	s_waitcnt lgkmcnt(0)
	v_mfma_f32_16x16x32_bf16 v[106:109], v[82:85], v[234:237], v[106:109]
	v_mfma_f32_16x16x32_bf16 v[122:125], v[82:85], v[238:241], v[122:125]
	v_mfma_f32_16x16x32_bf16 v[138:141], v[82:85], v[242:245], v[138:141]
	v_mfma_f32_16x16x32_bf16 v[162:165], v[82:85], v[246:249], v[162:165]
	v_mfma_f32_16x16x32_bf16 v[110:113], v[86:89], v[234:237], v[110:113]
	v_mfma_f32_16x16x32_bf16 v[126:129], v[86:89], v[238:241], v[126:129]
	v_mfma_f32_16x16x32_bf16 v[142:145], v[86:89], v[242:245], v[142:145]
	v_mfma_f32_16x16x32_bf16 v[166:169], v[86:89], v[246:249], v[166:169]
	v_mfma_f32_16x16x32_bf16 v[114:117], v[90:93], v[234:237], v[114:117]
	v_mfma_f32_16x16x32_bf16 v[130:133], v[90:93], v[238:241], v[130:133]
	v_mfma_f32_16x16x32_bf16 v[154:157], v[90:93], v[242:245], v[154:157]
	v_mfma_f32_16x16x32_bf16 v[170:173], v[90:93], v[246:249], v[170:173]
	v_mfma_f32_16x16x32_bf16 v[118:121], v[94:97], v[234:237], v[118:121]
	v_mfma_f32_16x16x32_bf16 v[134:137], v[94:97], v[238:241], v[134:137]
	v_mfma_f32_16x16x32_bf16 v[158:161], v[94:97], v[242:245], v[158:161]
	v_mfma_f32_16x16x32_bf16 v[174:177], v[94:97], v[246:249], v[174:177]
	s_waitcnt vmcnt(4)
	s_barrier
	ds_read_b128 v[218:221], v102 offset:16384
	ds_read_b128 v[222:225], v102 offset:18432
	ds_read_b128 v[226:229], v102 offset:20480
	ds_read_b128 v[230:233], v102 offset:22528
	ds_read_b128 v[66:69], v250 offset:49152
	ds_read_b128 v[70:73], v250 offset:51200
	ds_read_b128 v[74:77], v250 offset:53248
	ds_read_b128 v[78:81], v250 offset:55296
	ds_read_b128 v[234:237], v103 offset:16384
	ds_read_b128 v[238:241], v103 offset:18432
	ds_read_b128 v[242:245], v103 offset:20480
	ds_read_b128 v[246:249], v103 offset:22528
	ds_read_b128 v[82:85], v251 offset:49152
	ds_read_b128 v[86:89], v251 offset:51200
	ds_read_b128 v[90:93], v251 offset:53248
	ds_read_b128 v[94:97], v251 offset:55296
	s_waitcnt lgkmcnt(8)
	v_mfma_f32_16x16x32_bf16 v[62:65], v[66:69], v[218:221], v[62:65]
	s_add_u32 m0, s4, 0x0
	v_mfma_f32_16x16x32_bf16 v[46:49], v[66:69], v[222:225], v[46:49]
	global_load_lds_dwordx4 v98, s[28:29]
	v_mfma_f32_16x16x32_bf16 v[30:33], v[66:69], v[226:229], v[30:33]
	v_mfma_f32_16x16x32_bf16 v[14:17], v[66:69], v[230:233], v[14:17]
	v_mfma_f32_16x16x32_bf16 v[58:61], v[70:73], v[218:221], v[58:61]
	s_add_u32 m0, s4, 0x400
	v_mfma_f32_16x16x32_bf16 v[42:45], v[70:73], v[222:225], v[42:45]
	global_load_lds_dwordx4 v99, s[28:29]
	v_mfma_f32_16x16x32_bf16 v[26:29], v[70:73], v[226:229], v[26:29]
	v_mfma_f32_16x16x32_bf16 v[10:13], v[70:73], v[230:233], v[10:13]
	v_mfma_f32_16x16x32_bf16 v[54:57], v[74:77], v[218:221], v[54:57]
	s_add_u32 m0, s4, 0x800
	v_mfma_f32_16x16x32_bf16 v[38:41], v[74:77], v[222:225], v[38:41]
	global_load_lds_dwordx4 v100, s[28:29]
	v_mfma_f32_16x16x32_bf16 v[22:25], v[74:77], v[226:229], v[22:25]
	v_mfma_f32_16x16x32_bf16 v[6:9], v[74:77], v[230:233], v[6:9]
	v_mfma_f32_16x16x32_bf16 v[50:53], v[78:81], v[218:221], v[50:53]
	s_add_u32 m0, s4, 0xc00
	v_mfma_f32_16x16x32_bf16 v[34:37], v[78:81], v[222:225], v[34:37]
	global_load_lds_dwordx4 v101, s[28:29]
	v_mfma_f32_16x16x32_bf16 v[18:21], v[78:81], v[226:229], v[18:21]
	v_mfma_f32_16x16x32_bf16 v[2:5], v[78:81], v[230:233], v[2:5]
	s_waitcnt lgkmcnt(0)
	v_mfma_f32_16x16x32_bf16 v[62:65], v[82:85], v[234:237], v[62:65]
	s_add_u32 m0, s4, 0x8000
	v_mfma_f32_16x16x32_bf16 v[46:49], v[82:85], v[238:241], v[46:49]
	global_load_lds_dwordx4 v98, s[48:49]
	v_mfma_f32_16x16x32_bf16 v[30:33], v[82:85], v[242:245], v[30:33]
	v_mfma_f32_16x16x32_bf16 v[14:17], v[82:85], v[246:249], v[14:17]
	v_mfma_f32_16x16x32_bf16 v[58:61], v[86:89], v[234:237], v[58:61]
	s_add_u32 m0, s4, 0x8400
	v_mfma_f32_16x16x32_bf16 v[42:45], v[86:89], v[238:241], v[42:45]
	global_load_lds_dwordx4 v99, s[48:49]
	v_mfma_f32_16x16x32_bf16 v[26:29], v[86:89], v[242:245], v[26:29]
	v_mfma_f32_16x16x32_bf16 v[10:13], v[86:89], v[246:249], v[10:13]
	v_mfma_f32_16x16x32_bf16 v[54:57], v[90:93], v[234:237], v[54:57]
	s_add_u32 m0, s4, 0x8800
	v_mfma_f32_16x16x32_bf16 v[38:41], v[90:93], v[238:241], v[38:41]
	global_load_lds_dwordx4 v100, s[48:49]
	v_mfma_f32_16x16x32_bf16 v[22:25], v[90:93], v[242:245], v[22:25]
	v_mfma_f32_16x16x32_bf16 v[6:9], v[90:93], v[246:249], v[6:9]
	v_mfma_f32_16x16x32_bf16 v[50:53], v[94:97], v[234:237], v[50:53]
	s_add_u32 m0, s4, 0x8c00
	v_mfma_f32_16x16x32_bf16 v[34:37], v[94:97], v[238:241], v[34:37]
	global_load_lds_dwordx4 v101, s[48:49]
	v_mfma_f32_16x16x32_bf16 v[18:21], v[94:97], v[242:245], v[18:21]
	v_mfma_f32_16x16x32_bf16 v[2:5], v[94:97], v[246:249], v[2:5]
	s_waitcnt vmcnt(8)
	s_barrier
	ds_read_b128 v[218:221], v102 offset:49152
	ds_read_b128 v[222:225], v102 offset:51200
	ds_read_b128 v[226:229], v102 offset:53248
	ds_read_b128 v[230:233], v102 offset:55296
	ds_read_b128 v[234:237], v103 offset:49152
	ds_read_b128 v[238:241], v103 offset:51200
	ds_read_b128 v[242:245], v103 offset:53248
	ds_read_b128 v[246:249], v103 offset:55296
	s_waitcnt lgkmcnt(4)
	v_mfma_f32_16x16x32_bf16 v[106:109], v[66:69], v[218:221], v[106:109]
	s_add_u32 m0, s4, 0x4000
	v_mfma_f32_16x16x32_bf16 v[122:125], v[66:69], v[222:225], v[122:125]
	global_load_lds_dwordx4 v98, s[6:7]
	v_mfma_f32_16x16x32_bf16 v[138:141], v[66:69], v[226:229], v[138:141]
	v_mfma_f32_16x16x32_bf16 v[162:165], v[66:69], v[230:233], v[162:165]
	v_mfma_f32_16x16x32_bf16 v[110:113], v[70:73], v[218:221], v[110:113]
	s_add_u32 m0, s4, 0x4400
	v_mfma_f32_16x16x32_bf16 v[126:129], v[70:73], v[222:225], v[126:129]
	global_load_lds_dwordx4 v99, s[6:7]
	v_mfma_f32_16x16x32_bf16 v[142:145], v[70:73], v[226:229], v[142:145]
	v_mfma_f32_16x16x32_bf16 v[166:169], v[70:73], v[230:233], v[166:169]
	v_mfma_f32_16x16x32_bf16 v[114:117], v[74:77], v[218:221], v[114:117]
	s_add_u32 m0, s4, 0x4800
	v_mfma_f32_16x16x32_bf16 v[130:133], v[74:77], v[222:225], v[130:133]
	global_load_lds_dwordx4 v100, s[6:7]
	v_mfma_f32_16x16x32_bf16 v[154:157], v[74:77], v[226:229], v[154:157]
	v_mfma_f32_16x16x32_bf16 v[170:173], v[74:77], v[230:233], v[170:173]
	v_mfma_f32_16x16x32_bf16 v[118:121], v[78:81], v[218:221], v[118:121]
	s_add_u32 m0, s4, 0x4c00
	v_mfma_f32_16x16x32_bf16 v[134:137], v[78:81], v[222:225], v[134:137]
	global_load_lds_dwordx4 v101, s[6:7]
	v_mfma_f32_16x16x32_bf16 v[158:161], v[78:81], v[226:229], v[158:161]
	v_mfma_f32_16x16x32_bf16 v[174:177], v[78:81], v[230:233], v[174:177]
	v_add_u32_e32 v98, 0x80, v98
	v_add_u32_e32 v99, 0x80, v99
	v_add_u32_e32 v100, 0x80, v100
	v_add_u32_e32 v101, 0x80, v101
	s_waitcnt lgkmcnt(0)
	v_mfma_f32_16x16x32_bf16 v[106:109], v[82:85], v[234:237], v[106:109]
	v_mfma_f32_16x16x32_bf16 v[122:125], v[82:85], v[238:241], v[122:125]
	v_mfma_f32_16x16x32_bf16 v[138:141], v[82:85], v[242:245], v[138:141]
	v_mfma_f32_16x16x32_bf16 v[162:165], v[82:85], v[246:249], v[162:165]
	v_mfma_f32_16x16x32_bf16 v[110:113], v[86:89], v[234:237], v[110:113]
	v_mfma_f32_16x16x32_bf16 v[126:129], v[86:89], v[238:241], v[126:129]
	v_mfma_f32_16x16x32_bf16 v[142:145], v[86:89], v[242:245], v[142:145]
	v_mfma_f32_16x16x32_bf16 v[166:169], v[86:89], v[246:249], v[166:169]
	v_mfma_f32_16x16x32_bf16 v[114:117], v[90:93], v[234:237], v[114:117]
	v_mfma_f32_16x16x32_bf16 v[130:133], v[90:93], v[238:241], v[130:133]
	v_mfma_f32_16x16x32_bf16 v[154:157], v[90:93], v[242:245], v[154:157]
	v_mfma_f32_16x16x32_bf16 v[170:173], v[90:93], v[246:249], v[170:173]
	v_mfma_f32_16x16x32_bf16 v[118:121], v[94:97], v[234:237], v[118:121]
	v_mfma_f32_16x16x32_bf16 v[134:137], v[94:97], v[238:241], v[134:137]
	v_mfma_f32_16x16x32_bf16 v[158:161], v[94:97], v[242:245], v[158:161]
	v_mfma_f32_16x16x32_bf16 v[174:177], v[94:97], v[246:249], v[174:177]
	s_waitcnt vmcnt(4)
	s_barrier
	ds_read_b128 v[218:221], v102 offset:0
	ds_read_b128 v[222:225], v102 offset:2048
	ds_read_b128 v[226:229], v102 offset:4096
	ds_read_b128 v[230:233], v102 offset:6144
	ds_read_b128 v[66:69], v104 offset:32768
	ds_read_b128 v[70:73], v104 offset:34816
	ds_read_b128 v[74:77], v104 offset:36864
	ds_read_b128 v[78:81], v104 offset:38912
	ds_read_b128 v[234:237], v103 offset:0
	ds_read_b128 v[238:241], v103 offset:2048
	ds_read_b128 v[242:245], v103 offset:4096
	ds_read_b128 v[246:249], v103 offset:6144
	ds_read_b128 v[82:85], v105 offset:32768
	ds_read_b128 v[86:89], v105 offset:34816
	ds_read_b128 v[90:93], v105 offset:36864
	ds_read_b128 v[94:97], v105 offset:38912
	s_waitcnt lgkmcnt(8)
	v_mfma_f32_16x16x32_bf16 v[62:65], v[66:69], v[218:221], v[62:65]
	s_add_u32 m0, s4, 0xc000
	v_mfma_f32_16x16x32_bf16 v[46:49], v[66:69], v[222:225], v[46:49]
	global_load_lds_dwordx4 v98, s[28:29]
	v_mfma_f32_16x16x32_bf16 v[30:33], v[66:69], v[226:229], v[30:33]
	v_mfma_f32_16x16x32_bf16 v[14:17], v[66:69], v[230:233], v[14:17]
	v_mfma_f32_16x16x32_bf16 v[58:61], v[70:73], v[218:221], v[58:61]
	s_add_u32 m0, s4, 0xc400
	v_mfma_f32_16x16x32_bf16 v[42:45], v[70:73], v[222:225], v[42:45]
	global_load_lds_dwordx4 v99, s[28:29]
	v_mfma_f32_16x16x32_bf16 v[26:29], v[70:73], v[226:229], v[26:29]
	v_mfma_f32_16x16x32_bf16 v[10:13], v[70:73], v[230:233], v[10:13]
	v_mfma_f32_16x16x32_bf16 v[54:57], v[74:77], v[218:221], v[54:57]
	s_add_u32 m0, s4, 0xc800
	v_mfma_f32_16x16x32_bf16 v[38:41], v[74:77], v[222:225], v[38:41]
	global_load_lds_dwordx4 v100, s[28:29]
	v_mfma_f32_16x16x32_bf16 v[22:25], v[74:77], v[226:229], v[22:25]
	v_mfma_f32_16x16x32_bf16 v[6:9], v[74:77], v[230:233], v[6:9]
	v_mfma_f32_16x16x32_bf16 v[50:53], v[78:81], v[218:221], v[50:53]
	s_add_u32 m0, s4, 0xcc00
	v_mfma_f32_16x16x32_bf16 v[34:37], v[78:81], v[222:225], v[34:37]
	global_load_lds_dwordx4 v101, s[28:29]
	v_mfma_f32_16x16x32_bf16 v[18:21], v[78:81], v[226:229], v[18:21]
	v_mfma_f32_16x16x32_bf16 v[2:5], v[78:81], v[230:233], v[2:5]
	s_waitcnt lgkmcnt(0)
	v_mfma_f32_16x16x32_bf16 v[62:65], v[82:85], v[234:237], v[62:65]
	s_add_u32 m0, s4, 0x10000
	v_mfma_f32_16x16x32_bf16 v[46:49], v[82:85], v[238:241], v[46:49]
	global_load_lds_dwordx4 v98, s[48:49]
	v_mfma_f32_16x16x32_bf16 v[30:33], v[82:85], v[242:245], v[30:33]
	v_mfma_f32_16x16x32_bf16 v[14:17], v[82:85], v[246:249], v[14:17]
	v_mfma_f32_16x16x32_bf16 v[58:61], v[86:89], v[234:237], v[58:61]
	s_add_u32 m0, s4, 0x10400
	v_mfma_f32_16x16x32_bf16 v[42:45], v[86:89], v[238:241], v[42:45]
	global_load_lds_dwordx4 v99, s[48:49]
	v_mfma_f32_16x16x32_bf16 v[26:29], v[86:89], v[242:245], v[26:29]
	v_mfma_f32_16x16x32_bf16 v[10:13], v[86:89], v[246:249], v[10:13]
	v_mfma_f32_16x16x32_bf16 v[54:57], v[90:93], v[234:237], v[54:57]
	s_add_u32 m0, s4, 0x10800
	v_mfma_f32_16x16x32_bf16 v[38:41], v[90:93], v[238:241], v[38:41]
	global_load_lds_dwordx4 v100, s[48:49]
	v_mfma_f32_16x16x32_bf16 v[22:25], v[90:93], v[242:245], v[22:25]
	v_mfma_f32_16x16x32_bf16 v[6:9], v[90:93], v[246:249], v[6:9]
	v_mfma_f32_16x16x32_bf16 v[50:53], v[94:97], v[234:237], v[50:53]
	s_add_u32 m0, s4, 0x10c00
	v_mfma_f32_16x16x32_bf16 v[34:37], v[94:97], v[238:241], v[34:37]
	global_load_lds_dwordx4 v101, s[48:49]
	v_mfma_f32_16x16x32_bf16 v[18:21], v[94:97], v[242:245], v[18:21]
	v_mfma_f32_16x16x32_bf16 v[2:5], v[94:97], v[246:249], v[2:5]
	s_waitcnt vmcnt(8)
	s_barrier
	ds_read_b128 v[218:221], v102 offset:16384
	ds_read_b128 v[222:225], v102 offset:18432
	ds_read_b128 v[226:229], v102 offset:20480
	ds_read_b128 v[230:233], v102 offset:22528
	ds_read_b128 v[234:237], v103 offset:16384
	ds_read_b128 v[238:241], v103 offset:18432
	ds_read_b128 v[242:245], v103 offset:20480
	ds_read_b128 v[246:249], v103 offset:22528
	s_waitcnt lgkmcnt(4)
	v_mfma_f32_16x16x32_bf16 v[106:109], v[66:69], v[218:221], v[106:109]
	s_add_u32 m0, s4, 0x0
	v_mfma_f32_16x16x32_bf16 v[122:125], v[66:69], v[222:225], v[122:125]
	global_load_lds_dwordx4 v98, s[6:7]
	v_mfma_f32_16x16x32_bf16 v[138:141], v[66:69], v[226:229], v[138:141]
	v_mfma_f32_16x16x32_bf16 v[162:165], v[66:69], v[230:233], v[162:165]
	v_mfma_f32_16x16x32_bf16 v[110:113], v[70:73], v[218:221], v[110:113]
	s_add_u32 m0, s4, 0x400
	v_mfma_f32_16x16x32_bf16 v[126:129], v[70:73], v[222:225], v[126:129]
	global_load_lds_dwordx4 v99, s[6:7]
	v_mfma_f32_16x16x32_bf16 v[142:145], v[70:73], v[226:229], v[142:145]
	v_mfma_f32_16x16x32_bf16 v[166:169], v[70:73], v[230:233], v[166:169]
	v_mfma_f32_16x16x32_bf16 v[114:117], v[74:77], v[218:221], v[114:117]
	s_add_u32 m0, s4, 0x800
	v_mfma_f32_16x16x32_bf16 v[130:133], v[74:77], v[222:225], v[130:133]
	global_load_lds_dwordx4 v100, s[6:7]
	v_mfma_f32_16x16x32_bf16 v[154:157], v[74:77], v[226:229], v[154:157]
	v_mfma_f32_16x16x32_bf16 v[170:173], v[74:77], v[230:233], v[170:173]
	v_mfma_f32_16x16x32_bf16 v[118:121], v[78:81], v[218:221], v[118:121]
	s_add_u32 m0, s4, 0xc00
	v_mfma_f32_16x16x32_bf16 v[134:137], v[78:81], v[222:225], v[134:137]
	global_load_lds_dwordx4 v101, s[6:7]
	v_mfma_f32_16x16x32_bf16 v[158:161], v[78:81], v[226:229], v[158:161]
	v_mfma_f32_16x16x32_bf16 v[174:177], v[78:81], v[230:233], v[174:177]
	v_add_u32_e32 v98, 0x80, v98
	v_add_u32_e32 v99, 0x80, v99
	v_add_u32_e32 v100, 0x80, v100
	v_add_u32_e32 v101, 0x80, v101
	s_waitcnt lgkmcnt(0)
	v_mfma_f32_16x16x32_bf16 v[106:109], v[82:85], v[234:237], v[106:109]
	v_mfma_f32_16x16x32_bf16 v[122:125], v[82:85], v[238:241], v[122:125]
	v_mfma_f32_16x16x32_bf16 v[138:141], v[82:85], v[242:245], v[138:141]
	v_mfma_f32_16x16x32_bf16 v[162:165], v[82:85], v[246:249], v[162:165]
	v_mfma_f32_16x16x32_bf16 v[110:113], v[86:89], v[234:237], v[110:113]
	v_mfma_f32_16x16x32_bf16 v[126:129], v[86:89], v[238:241], v[126:129]
	v_mfma_f32_16x16x32_bf16 v[142:145], v[86:89], v[242:245], v[142:145]
	v_mfma_f32_16x16x32_bf16 v[166:169], v[86:89], v[246:249], v[166:169]
	v_mfma_f32_16x16x32_bf16 v[114:117], v[90:93], v[234:237], v[114:117]
	v_mfma_f32_16x16x32_bf16 v[130:133], v[90:93], v[238:241], v[130:133]
	v_mfma_f32_16x16x32_bf16 v[154:157], v[90:93], v[242:245], v[154:157]
	v_mfma_f32_16x16x32_bf16 v[170:173], v[90:93], v[246:249], v[170:173]
	v_mfma_f32_16x16x32_bf16 v[118:121], v[94:97], v[234:237], v[118:121]
	v_mfma_f32_16x16x32_bf16 v[134:137], v[94:97], v[238:241], v[134:137]
	v_mfma_f32_16x16x32_bf16 v[158:161], v[94:97], v[242:245], v[158:161]
	v_mfma_f32_16x16x32_bf16 v[174:177], v[94:97], v[246:249], v[174:177]
	s_waitcnt vmcnt(4)
	s_barrier
	ds_read_b128 v[218:221], v102 offset:49152
	ds_read_b128 v[222:225], v102 offset:51200
	ds_read_b128 v[226:229], v102 offset:53248
	ds_read_b128 v[230:233], v102 offset:55296
	ds_read_b128 v[66:69], v250 offset:49152
	ds_read_b128 v[70:73], v250 offset:51200
	ds_read_b128 v[74:77], v250 offset:53248
	ds_read_b128 v[78:81], v250 offset:55296
	ds_read_b128 v[234:237], v103 offset:49152
	ds_read_b128 v[238:241], v103 offset:51200
	ds_read_b128 v[242:245], v103 offset:53248
	ds_read_b128 v[246:249], v103 offset:55296
	ds_read_b128 v[82:85], v251 offset:49152
	ds_read_b128 v[86:89], v251 offset:51200
	ds_read_b128 v[90:93], v251 offset:53248
	ds_read_b128 v[94:97], v251 offset:55296
	s_waitcnt lgkmcnt(8)
	v_mfma_f32_16x16x32_bf16 v[62:65], v[66:69], v[218:221], v[62:65]
	s_add_u32 m0, s4, 0x4000
	v_mfma_f32_16x16x32_bf16 v[46:49], v[66:69], v[222:225], v[46:49]
	global_load_lds_dwordx4 v98, s[28:29]
	v_mfma_f32_16x16x32_bf16 v[30:33], v[66:69], v[226:229], v[30:33]
	v_mfma_f32_16x16x32_bf16 v[14:17], v[66:69], v[230:233], v[14:17]
	v_mfma_f32_16x16x32_bf16 v[58:61], v[70:73], v[218:221], v[58:61]
	s_add_u32 m0, s4, 0x4400
	v_mfma_f32_16x16x32_bf16 v[42:45], v[70:73], v[222:225], v[42:45]
	global_load_lds_dwordx4 v99, s[28:29]
	v_mfma_f32_16x16x32_bf16 v[26:29], v[70:73], v[226:229], v[26:29]
	v_mfma_f32_16x16x32_bf16 v[10:13], v[70:73], v[230:233], v[10:13]
	v_mfma_f32_16x16x32_bf16 v[54:57], v[74:77], v[218:221], v[54:57]
	s_add_u32 m0, s4, 0x4800
	v_mfma_f32_16x16x32_bf16 v[38:41], v[74:77], v[222:225], v[38:41]
	global_load_lds_dwordx4 v100, s[28:29]
	v_mfma_f32_16x16x32_bf16 v[22:25], v[74:77], v[226:229], v[22:25]
	v_mfma_f32_16x16x32_bf16 v[6:9], v[74:77], v[230:233], v[6:9]
	v_mfma_f32_16x16x32_bf16 v[50:53], v[78:81], v[218:221], v[50:53]
	s_add_u32 m0, s4, 0x4c00
	v_mfma_f32_16x16x32_bf16 v[34:37], v[78:81], v[222:225], v[34:37]
	global_load_lds_dwordx4 v101, s[28:29]
	v_mfma_f32_16x16x32_bf16 v[18:21], v[78:81], v[226:229], v[18:21]
	v_mfma_f32_16x16x32_bf16 v[2:5], v[78:81], v[230:233], v[2:5]
	s_waitcnt lgkmcnt(0)
	v_mfma_f32_16x16x32_bf16 v[62:65], v[82:85], v[234:237], v[62:65]
	s_add_u32 m0, s4, 0x8000
	v_mfma_f32_16x16x32_bf16 v[46:49], v[82:85], v[238:241], v[46:49]
	global_load_lds_dwordx4 v98, s[48:49]
	v_mfma_f32_16x16x32_bf16 v[30:33], v[82:85], v[242:245], v[30:33]
	v_mfma_f32_16x16x32_bf16 v[14:17], v[82:85], v[246:249], v[14:17]
	v_mfma_f32_16x16x32_bf16 v[58:61], v[86:89], v[234:237], v[58:61]
	s_add_u32 m0, s4, 0x8400
	v_mfma_f32_16x16x32_bf16 v[42:45], v[86:89], v[238:241], v[42:45]
	global_load_lds_dwordx4 v99, s[48:49]
	v_mfma_f32_16x16x32_bf16 v[26:29], v[86:89], v[242:245], v[26:29]
	v_mfma_f32_16x16x32_bf16 v[10:13], v[86:89], v[246:249], v[10:13]
	v_mfma_f32_16x16x32_bf16 v[54:57], v[90:93], v[234:237], v[54:57]
	s_add_u32 m0, s4, 0x8800
	v_mfma_f32_16x16x32_bf16 v[38:41], v[90:93], v[238:241], v[38:41]
	global_load_lds_dwordx4 v100, s[48:49]
	v_mfma_f32_16x16x32_bf16 v[22:25], v[90:93], v[242:245], v[22:25]
	v_mfma_f32_16x16x32_bf16 v[6:9], v[90:93], v[246:249], v[6:9]
	v_mfma_f32_16x16x32_bf16 v[50:53], v[94:97], v[234:237], v[50:53]
	s_add_u32 m0, s4, 0x8c00
	v_mfma_f32_16x16x32_bf16 v[34:37], v[94:97], v[238:241], v[34:37]
	global_load_lds_dwordx4 v101, s[48:49]
	v_mfma_f32_16x16x32_bf16 v[18:21], v[94:97], v[242:245], v[18:21]
	v_mfma_f32_16x16x32_bf16 v[2:5], v[94:97], v[246:249], v[2:5]
	s_waitcnt vmcnt(8)
	s_barrier
	ds_read_b128 v[218:221], v102 offset:0
	ds_read_b128 v[222:225], v102 offset:2048
	ds_read_b128 v[226:229], v102 offset:4096
	ds_read_b128 v[230:233], v102 offset:6144
	ds_read_b128 v[234:237], v103 offset:0
	ds_read_b128 v[238:241], v103 offset:2048
	ds_read_b128 v[242:245], v103 offset:4096
	ds_read_b128 v[246:249], v103 offset:6144
	s_waitcnt lgkmcnt(4)
	v_mfma_f32_16x16x32_bf16 v[106:109], v[66:69], v[218:221], v[106:109]
	s_add_u32 m0, s4, 0xc000
	v_mfma_f32_16x16x32_bf16 v[122:125], v[66:69], v[222:225], v[122:125]
	global_load_lds_dwordx4 v98, s[6:7]
	v_mfma_f32_16x16x32_bf16 v[138:141], v[66:69], v[226:229], v[138:141]
	v_mfma_f32_16x16x32_bf16 v[162:165], v[66:69], v[230:233], v[162:165]
	v_mfma_f32_16x16x32_bf16 v[110:113], v[70:73], v[218:221], v[110:113]
	s_add_u32 m0, s4, 0xc400
	v_mfma_f32_16x16x32_bf16 v[126:129], v[70:73], v[222:225], v[126:129]
	global_load_lds_dwordx4 v99, s[6:7]
	v_mfma_f32_16x16x32_bf16 v[142:145], v[70:73], v[226:229], v[142:145]
	v_mfma_f32_16x16x32_bf16 v[166:169], v[70:73], v[230:233], v[166:169]
	v_mfma_f32_16x16x32_bf16 v[114:117], v[74:77], v[218:221], v[114:117]
	s_add_u32 m0, s4, 0xc800
	v_mfma_f32_16x16x32_bf16 v[130:133], v[74:77], v[222:225], v[130:133]
	global_load_lds_dwordx4 v100, s[6:7]
	v_mfma_f32_16x16x32_bf16 v[154:157], v[74:77], v[226:229], v[154:157]
	v_mfma_f32_16x16x32_bf16 v[170:173], v[74:77], v[230:233], v[170:173]
	v_mfma_f32_16x16x32_bf16 v[118:121], v[78:81], v[218:221], v[118:121]
	s_add_u32 m0, s4, 0xcc00
	v_mfma_f32_16x16x32_bf16 v[134:137], v[78:81], v[222:225], v[134:137]
	global_load_lds_dwordx4 v101, s[6:7]
	v_mfma_f32_16x16x32_bf16 v[158:161], v[78:81], v[226:229], v[158:161]
	v_mfma_f32_16x16x32_bf16 v[174:177], v[78:81], v[230:233], v[174:177]
	v_add_u32_e32 v98, 0x80, v98
	v_add_u32_e32 v99, 0x80, v99
	v_add_u32_e32 v100, 0x80, v100
	v_add_u32_e32 v101, 0x80, v101
	s_waitcnt lgkmcnt(0)
	v_mfma_f32_16x16x32_bf16 v[106:109], v[82:85], v[234:237], v[106:109]
	v_mfma_f32_16x16x32_bf16 v[122:125], v[82:85], v[238:241], v[122:125]
	v_mfma_f32_16x16x32_bf16 v[138:141], v[82:85], v[242:245], v[138:141]
	v_mfma_f32_16x16x32_bf16 v[162:165], v[82:85], v[246:249], v[162:165]
	v_mfma_f32_16x16x32_bf16 v[110:113], v[86:89], v[234:237], v[110:113]
	v_mfma_f32_16x16x32_bf16 v[126:129], v[86:89], v[238:241], v[126:129]
	v_mfma_f32_16x16x32_bf16 v[142:145], v[86:89], v[242:245], v[142:145]
	v_mfma_f32_16x16x32_bf16 v[166:169], v[86:89], v[246:249], v[166:169]
	v_mfma_f32_16x16x32_bf16 v[114:117], v[90:93], v[234:237], v[114:117]
	v_mfma_f32_16x16x32_bf16 v[130:133], v[90:93], v[238:241], v[130:133]
	v_mfma_f32_16x16x32_bf16 v[154:157], v[90:93], v[242:245], v[154:157]
	v_mfma_f32_16x16x32_bf16 v[170:173], v[90:93], v[246:249], v[170:173]
	v_mfma_f32_16x16x32_bf16 v[118:121], v[94:97], v[234:237], v[118:121]
	v_mfma_f32_16x16x32_bf16 v[134:137], v[94:97], v[238:241], v[134:137]
	v_mfma_f32_16x16x32_bf16 v[158:161], v[94:97], v[242:245], v[158:161]
	v_mfma_f32_16x16x32_bf16 v[174:177], v[94:97], v[246:249], v[174:177]
	s_waitcnt vmcnt(4)
	s_barrier
	ds_read_b128 v[218:221], v102 offset:16384
	ds_read_b128 v[222:225], v102 offset:18432
	ds_read_b128 v[226:229], v102 offset:20480
	ds_read_b128 v[230:233], v102 offset:22528
	ds_read_b128 v[66:69], v104 offset:32768
	ds_read_b128 v[70:73], v104 offset:34816
	ds_read_b128 v[74:77], v104 offset:36864
	ds_read_b128 v[78:81], v104 offset:38912
	ds_read_b128 v[234:237], v103 offset:16384
	ds_read_b128 v[238:241], v103 offset:18432
	ds_read_b128 v[242:245], v103 offset:20480
	ds_read_b128 v[246:249], v103 offset:22528
	ds_read_b128 v[82:85], v105 offset:32768
	ds_read_b128 v[86:89], v105 offset:34816
	ds_read_b128 v[90:93], v105 offset:36864
	ds_read_b128 v[94:97], v105 offset:38912
	s_waitcnt lgkmcnt(8)
	v_mfma_f32_16x16x32_bf16 v[62:65], v[66:69], v[218:221], v[62:65]
	s_add_u32 m0, s4, 0x0
	v_mfma_f32_16x16x32_bf16 v[46:49], v[66:69], v[222:225], v[46:49]
	global_load_lds_dwordx4 v98, s[28:29]
	v_mfma_f32_16x16x32_bf16 v[30:33], v[66:69], v[226:229], v[30:33]
	v_mfma_f32_16x16x32_bf16 v[14:17], v[66:69], v[230:233], v[14:17]
	v_mfma_f32_16x16x32_bf16 v[58:61], v[70:73], v[218:221], v[58:61]
	s_add_u32 m0, s4, 0x400
	v_mfma_f32_16x16x32_bf16 v[42:45], v[70:73], v[222:225], v[42:45]
	global_load_lds_dwordx4 v99, s[28:29]
	v_mfma_f32_16x16x32_bf16 v[26:29], v[70:73], v[226:229], v[26:29]
	v_mfma_f32_16x16x32_bf16 v[10:13], v[70:73], v[230:233], v[10:13]
	v_mfma_f32_16x16x32_bf16 v[54:57], v[74:77], v[218:221], v[54:57]
	s_add_u32 m0, s4, 0x800
	v_mfma_f32_16x16x32_bf16 v[38:41], v[74:77], v[222:225], v[38:41]
	global_load_lds_dwordx4 v100, s[28:29]
	v_mfma_f32_16x16x32_bf16 v[22:25], v[74:77], v[226:229], v[22:25]
	v_mfma_f32_16x16x32_bf16 v[6:9], v[74:77], v[230:233], v[6:9]
	v_mfma_f32_16x16x32_bf16 v[50:53], v[78:81], v[218:221], v[50:53]
	s_add_u32 m0, s4, 0xc00
	v_mfma_f32_16x16x32_bf16 v[34:37], v[78:81], v[222:225], v[34:37]
	global_load_lds_dwordx4 v101, s[28:29]
	v_mfma_f32_16x16x32_bf16 v[18:21], v[78:81], v[226:229], v[18:21]
	v_mfma_f32_16x16x32_bf16 v[2:5], v[78:81], v[230:233], v[2:5]
	s_waitcnt lgkmcnt(0)
	v_mfma_f32_16x16x32_bf16 v[62:65], v[82:85], v[234:237], v[62:65]
	s_add_u32 m0, s4, 0x10000
	v_mfma_f32_16x16x32_bf16 v[46:49], v[82:85], v[238:241], v[46:49]
	global_load_lds_dwordx4 v98, s[48:49]
	v_mfma_f32_16x16x32_bf16 v[30:33], v[82:85], v[242:245], v[30:33]
	v_mfma_f32_16x16x32_bf16 v[14:17], v[82:85], v[246:249], v[14:17]
	v_mfma_f32_16x16x32_bf16 v[58:61], v[86:89], v[234:237], v[58:61]
	s_add_u32 m0, s4, 0x10400
	v_mfma_f32_16x16x32_bf16 v[42:45], v[86:89], v[238:241], v[42:45]
	global_load_lds_dwordx4 v99, s[48:49]
	v_mfma_f32_16x16x32_bf16 v[26:29], v[86:89], v[242:245], v[26:29]
	v_mfma_f32_16x16x32_bf16 v[10:13], v[86:89], v[246:249], v[10:13]
	v_mfma_f32_16x16x32_bf16 v[54:57], v[90:93], v[234:237], v[54:57]
	s_add_u32 m0, s4, 0x10800
	v_mfma_f32_16x16x32_bf16 v[38:41], v[90:93], v[238:241], v[38:41]
	global_load_lds_dwordx4 v100, s[48:49]
	v_mfma_f32_16x16x32_bf16 v[22:25], v[90:93], v[242:245], v[22:25]
	v_mfma_f32_16x16x32_bf16 v[6:9], v[90:93], v[246:249], v[6:9]
	v_mfma_f32_16x16x32_bf16 v[50:53], v[94:97], v[234:237], v[50:53]
	s_add_u32 m0, s4, 0x10c00
	v_mfma_f32_16x16x32_bf16 v[34:37], v[94:97], v[238:241], v[34:37]
	global_load_lds_dwordx4 v101, s[48:49]
	v_mfma_f32_16x16x32_bf16 v[18:21], v[94:97], v[242:245], v[18:21]
	v_mfma_f32_16x16x32_bf16 v[2:5], v[94:97], v[246:249], v[2:5]
	s_waitcnt vmcnt(8)
	s_barrier
	ds_read_b128 v[218:221], v102 offset:49152
	ds_read_b128 v[222:225], v102 offset:51200
	ds_read_b128 v[226:229], v102 offset:53248
	ds_read_b128 v[230:233], v102 offset:55296
	ds_read_b128 v[234:237], v103 offset:49152
	ds_read_b128 v[238:241], v103 offset:51200
	ds_read_b128 v[242:245], v103 offset:53248
	ds_read_b128 v[246:249], v103 offset:55296
	s_waitcnt lgkmcnt(4)
	v_mfma_f32_16x16x32_bf16 v[106:109], v[66:69], v[218:221], v[106:109]
	s_add_u32 m0, s4, 0x4000
	v_mfma_f32_16x16x32_bf16 v[122:125], v[66:69], v[222:225], v[122:125]
	global_load_lds_dwordx4 v98, s[6:7]
	v_mfma_f32_16x16x32_bf16 v[138:141], v[66:69], v[226:229], v[138:141]
	v_mfma_f32_16x16x32_bf16 v[162:165], v[66:69], v[230:233], v[162:165]
	v_mfma_f32_16x16x32_bf16 v[110:113], v[70:73], v[218:221], v[110:113]
	s_add_u32 m0, s4, 0x4400
	v_mfma_f32_16x16x32_bf16 v[126:129], v[70:73], v[222:225], v[126:129]
	global_load_lds_dwordx4 v99, s[6:7]
	v_mfma_f32_16x16x32_bf16 v[142:145], v[70:73], v[226:229], v[142:145]
	v_mfma_f32_16x16x32_bf16 v[166:169], v[70:73], v[230:233], v[166:169]
	v_mfma_f32_16x16x32_bf16 v[114:117], v[74:77], v[218:221], v[114:117]
	s_add_u32 m0, s4, 0x4800
	v_mfma_f32_16x16x32_bf16 v[130:133], v[74:77], v[222:225], v[130:133]
	global_load_lds_dwordx4 v100, s[6:7]
	v_mfma_f32_16x16x32_bf16 v[154:157], v[74:77], v[226:229], v[154:157]
	v_mfma_f32_16x16x32_bf16 v[170:173], v[74:77], v[230:233], v[170:173]
	v_mfma_f32_16x16x32_bf16 v[118:121], v[78:81], v[218:221], v[118:121]
	s_add_u32 m0, s4, 0x4c00
	v_mfma_f32_16x16x32_bf16 v[134:137], v[78:81], v[222:225], v[134:137]
	global_load_lds_dwordx4 v101, s[6:7]
	v_mfma_f32_16x16x32_bf16 v[158:161], v[78:81], v[226:229], v[158:161]
	v_mfma_f32_16x16x32_bf16 v[174:177], v[78:81], v[230:233], v[174:177]
	v_add_u32_e32 v98, 0x80, v98
	v_add_u32_e32 v99, 0x80, v99
	v_add_u32_e32 v100, 0x80, v100
	v_add_u32_e32 v101, 0x80, v101
	s_waitcnt lgkmcnt(0)
	v_mfma_f32_16x16x32_bf16 v[106:109], v[82:85], v[234:237], v[106:109]
	v_mfma_f32_16x16x32_bf16 v[122:125], v[82:85], v[238:241], v[122:125]
	v_mfma_f32_16x16x32_bf16 v[138:141], v[82:85], v[242:245], v[138:141]
	v_mfma_f32_16x16x32_bf16 v[162:165], v[82:85], v[246:249], v[162:165]
	v_mfma_f32_16x16x32_bf16 v[110:113], v[86:89], v[234:237], v[110:113]
	v_mfma_f32_16x16x32_bf16 v[126:129], v[86:89], v[238:241], v[126:129]
	v_mfma_f32_16x16x32_bf16 v[142:145], v[86:89], v[242:245], v[142:145]
	v_mfma_f32_16x16x32_bf16 v[166:169], v[86:89], v[246:249], v[166:169]
	v_mfma_f32_16x16x32_bf16 v[114:117], v[90:93], v[234:237], v[114:117]
	v_mfma_f32_16x16x32_bf16 v[130:133], v[90:93], v[238:241], v[130:133]
	v_mfma_f32_16x16x32_bf16 v[154:157], v[90:93], v[242:245], v[154:157]
	v_mfma_f32_16x16x32_bf16 v[170:173], v[90:93], v[246:249], v[170:173]
	v_mfma_f32_16x16x32_bf16 v[118:121], v[94:97], v[234:237], v[118:121]
	v_mfma_f32_16x16x32_bf16 v[134:137], v[94:97], v[238:241], v[134:137]
	v_mfma_f32_16x16x32_bf16 v[158:161], v[94:97], v[242:245], v[158:161]
	v_mfma_f32_16x16x32_bf16 v[174:177], v[94:97], v[246:249], v[174:177]
	s_waitcnt vmcnt(4)
	s_barrier
	ds_read_b128 v[218:221], v102 offset:0
	ds_read_b128 v[222:225], v102 offset:2048
	ds_read_b128 v[226:229], v102 offset:4096
	ds_read_b128 v[230:233], v102 offset:6144
	ds_read_b128 v[66:69], v250 offset:49152
	ds_read_b128 v[70:73], v250 offset:51200
	ds_read_b128 v[74:77], v250 offset:53248
	ds_read_b128 v[78:81], v250 offset:55296
	ds_read_b128 v[234:237], v103 offset:0
	ds_read_b128 v[238:241], v103 offset:2048
	ds_read_b128 v[242:245], v103 offset:4096
	ds_read_b128 v[246:249], v103 offset:6144
	ds_read_b128 v[82:85], v251 offset:49152
	ds_read_b128 v[86:89], v251 offset:51200
	ds_read_b128 v[90:93], v251 offset:53248
	ds_read_b128 v[94:97], v251 offset:55296
	s_waitcnt lgkmcnt(8)
	v_mfma_f32_16x16x32_bf16 v[62:65], v[66:69], v[218:221], v[62:65]
	s_add_u32 m0, s4, 0xc000
	v_mfma_f32_16x16x32_bf16 v[46:49], v[66:69], v[222:225], v[46:49]
	global_load_lds_dwordx4 v98, s[28:29]
	v_mfma_f32_16x16x32_bf16 v[30:33], v[66:69], v[226:229], v[30:33]
	v_mfma_f32_16x16x32_bf16 v[14:17], v[66:69], v[230:233], v[14:17]
	v_mfma_f32_16x16x32_bf16 v[58:61], v[70:73], v[218:221], v[58:61]
	s_add_u32 m0, s4, 0xc400
	v_mfma_f32_16x16x32_bf16 v[42:45], v[70:73], v[222:225], v[42:45]
	global_load_lds_dwordx4 v99, s[28:29]
	v_mfma_f32_16x16x32_bf16 v[26:29], v[70:73], v[226:229], v[26:29]
	v_mfma_f32_16x16x32_bf16 v[10:13], v[70:73], v[230:233], v[10:13]
	v_mfma_f32_16x16x32_bf16 v[54:57], v[74:77], v[218:221], v[54:57]
	s_add_u32 m0, s4, 0xc800
	v_mfma_f32_16x16x32_bf16 v[38:41], v[74:77], v[222:225], v[38:41]
	global_load_lds_dwordx4 v100, s[28:29]
	v_mfma_f32_16x16x32_bf16 v[22:25], v[74:77], v[226:229], v[22:25]
	v_mfma_f32_16x16x32_bf16 v[6:9], v[74:77], v[230:233], v[6:9]
	v_mfma_f32_16x16x32_bf16 v[50:53], v[78:81], v[218:221], v[50:53]
	s_add_u32 m0, s4, 0xcc00
	v_mfma_f32_16x16x32_bf16 v[34:37], v[78:81], v[222:225], v[34:37]
	global_load_lds_dwordx4 v101, s[28:29]
	v_mfma_f32_16x16x32_bf16 v[18:21], v[78:81], v[226:229], v[18:21]
	v_mfma_f32_16x16x32_bf16 v[2:5], v[78:81], v[230:233], v[2:5]
	s_waitcnt lgkmcnt(0)
	v_mfma_f32_16x16x32_bf16 v[62:65], v[82:85], v[234:237], v[62:65]
	s_add_u32 m0, s4, 0x8000
	v_mfma_f32_16x16x32_bf16 v[46:49], v[82:85], v[238:241], v[46:49]
	global_load_lds_dwordx4 v98, s[48:49]
	v_mfma_f32_16x16x32_bf16 v[30:33], v[82:85], v[242:245], v[30:33]
	v_mfma_f32_16x16x32_bf16 v[14:17], v[82:85], v[246:249], v[14:17]
	v_mfma_f32_16x16x32_bf16 v[58:61], v[86:89], v[234:237], v[58:61]
	s_add_u32 m0, s4, 0x8400
	v_mfma_f32_16x16x32_bf16 v[42:45], v[86:89], v[238:241], v[42:45]
	global_load_lds_dwordx4 v99, s[48:49]
	v_mfma_f32_16x16x32_bf16 v[26:29], v[86:89], v[242:245], v[26:29]
	v_mfma_f32_16x16x32_bf16 v[10:13], v[86:89], v[246:249], v[10:13]
	v_mfma_f32_16x16x32_bf16 v[54:57], v[90:93], v[234:237], v[54:57]
	s_add_u32 m0, s4, 0x8800
	v_mfma_f32_16x16x32_bf16 v[38:41], v[90:93], v[238:241], v[38:41]
	global_load_lds_dwordx4 v100, s[48:49]
	v_mfma_f32_16x16x32_bf16 v[22:25], v[90:93], v[242:245], v[22:25]
	v_mfma_f32_16x16x32_bf16 v[6:9], v[90:93], v[246:249], v[6:9]
	v_mfma_f32_16x16x32_bf16 v[50:53], v[94:97], v[234:237], v[50:53]
	s_add_u32 m0, s4, 0x8c00
	v_mfma_f32_16x16x32_bf16 v[34:37], v[94:97], v[238:241], v[34:37]
	global_load_lds_dwordx4 v101, s[48:49]
	v_mfma_f32_16x16x32_bf16 v[18:21], v[94:97], v[242:245], v[18:21]
	v_mfma_f32_16x16x32_bf16 v[2:5], v[94:97], v[246:249], v[2:5]
	s_waitcnt vmcnt(8)
	s_barrier
	ds_read_b128 v[218:221], v102 offset:16384
	ds_read_b128 v[222:225], v102 offset:18432
	ds_read_b128 v[226:229], v102 offset:20480
	ds_read_b128 v[230:233], v102 offset:22528
	ds_read_b128 v[234:237], v103 offset:16384
	ds_read_b128 v[238:241], v103 offset:18432
	ds_read_b128 v[242:245], v103 offset:20480
	ds_read_b128 v[246:249], v103 offset:22528
	s_waitcnt lgkmcnt(4)
	v_mfma_f32_16x16x32_bf16 v[106:109], v[66:69], v[218:221], v[106:109]
	s_add_u32 m0, s4, 0x0
	v_mfma_f32_16x16x32_bf16 v[122:125], v[66:69], v[222:225], v[122:125]
	global_load_lds_dwordx4 v98, s[6:7]
	v_mfma_f32_16x16x32_bf16 v[138:141], v[66:69], v[226:229], v[138:141]
	v_mfma_f32_16x16x32_bf16 v[162:165], v[66:69], v[230:233], v[162:165]
	v_mfma_f32_16x16x32_bf16 v[110:113], v[70:73], v[218:221], v[110:113]
	s_add_u32 m0, s4, 0x400
	v_mfma_f32_16x16x32_bf16 v[126:129], v[70:73], v[222:225], v[126:129]
	global_load_lds_dwordx4 v99, s[6:7]
	v_mfma_f32_16x16x32_bf16 v[142:145], v[70:73], v[226:229], v[142:145]
	v_mfma_f32_16x16x32_bf16 v[166:169], v[70:73], v[230:233], v[166:169]
	v_mfma_f32_16x16x32_bf16 v[114:117], v[74:77], v[218:221], v[114:117]
	s_add_u32 m0, s4, 0x800
	v_mfma_f32_16x16x32_bf16 v[130:133], v[74:77], v[222:225], v[130:133]
	global_load_lds_dwordx4 v100, s[6:7]
	v_mfma_f32_16x16x32_bf16 v[154:157], v[74:77], v[226:229], v[154:157]
	v_mfma_f32_16x16x32_bf16 v[170:173], v[74:77], v[230:233], v[170:173]
	v_mfma_f32_16x16x32_bf16 v[118:121], v[78:81], v[218:221], v[118:121]
	s_add_u32 m0, s4, 0xc00
	v_mfma_f32_16x16x32_bf16 v[134:137], v[78:81], v[222:225], v[134:137]
	global_load_lds_dwordx4 v101, s[6:7]
	v_mfma_f32_16x16x32_bf16 v[158:161], v[78:81], v[226:229], v[158:161]
	v_mfma_f32_16x16x32_bf16 v[174:177], v[78:81], v[230:233], v[174:177]
	v_add_u32_e32 v98, 0x80, v98
	v_add_u32_e32 v99, 0x80, v99
	v_add_u32_e32 v100, 0x80, v100
	v_add_u32_e32 v101, 0x80, v101
	s_waitcnt lgkmcnt(0)
	v_mfma_f32_16x16x32_bf16 v[106:109], v[82:85], v[234:237], v[106:109]
	v_mfma_f32_16x16x32_bf16 v[122:125], v[82:85], v[238:241], v[122:125]
	v_mfma_f32_16x16x32_bf16 v[138:141], v[82:85], v[242:245], v[138:141]
	v_mfma_f32_16x16x32_bf16 v[162:165], v[82:85], v[246:249], v[162:165]
	v_mfma_f32_16x16x32_bf16 v[110:113], v[86:89], v[234:237], v[110:113]
	v_mfma_f32_16x16x32_bf16 v[126:129], v[86:89], v[238:241], v[126:129]
	v_mfma_f32_16x16x32_bf16 v[142:145], v[86:89], v[242:245], v[142:145]
	v_mfma_f32_16x16x32_bf16 v[166:169], v[86:89], v[246:249], v[166:169]
	v_mfma_f32_16x16x32_bf16 v[114:117], v[90:93], v[234:237], v[114:117]
	v_mfma_f32_16x16x32_bf16 v[130:133], v[90:93], v[238:241], v[130:133]
	v_mfma_f32_16x16x32_bf16 v[154:157], v[90:93], v[242:245], v[154:157]
	v_mfma_f32_16x16x32_bf16 v[170:173], v[90:93], v[246:249], v[170:173]
	v_mfma_f32_16x16x32_bf16 v[118:121], v[94:97], v[234:237], v[118:121]
	v_mfma_f32_16x16x32_bf16 v[134:137], v[94:97], v[238:241], v[134:137]
	v_mfma_f32_16x16x32_bf16 v[158:161], v[94:97], v[242:245], v[158:161]
	v_mfma_f32_16x16x32_bf16 v[174:177], v[94:97], v[246:249], v[174:177]
	s_waitcnt vmcnt(4)
	s_barrier
	ds_read_b128 v[218:221], v102 offset:49152
	ds_read_b128 v[222:225], v102 offset:51200
	ds_read_b128 v[226:229], v102 offset:53248
	ds_read_b128 v[230:233], v102 offset:55296
	ds_read_b128 v[66:69], v104 offset:32768
	ds_read_b128 v[70:73], v104 offset:34816
	ds_read_b128 v[74:77], v104 offset:36864
	ds_read_b128 v[78:81], v104 offset:38912
	ds_read_b128 v[234:237], v103 offset:49152
	ds_read_b128 v[238:241], v103 offset:51200
	ds_read_b128 v[242:245], v103 offset:53248
	ds_read_b128 v[246:249], v103 offset:55296
	ds_read_b128 v[82:85], v105 offset:32768
	ds_read_b128 v[86:89], v105 offset:34816
	ds_read_b128 v[90:93], v105 offset:36864
	ds_read_b128 v[94:97], v105 offset:38912
	s_waitcnt lgkmcnt(8)
	v_mfma_f32_16x16x32_bf16 v[62:65], v[66:69], v[218:221], v[62:65]
	s_add_u32 m0, s4, 0x4000
	v_mfma_f32_16x16x32_bf16 v[46:49], v[66:69], v[222:225], v[46:49]
	global_load_lds_dwordx4 v98, s[28:29]
	v_mfma_f32_16x16x32_bf16 v[30:33], v[66:69], v[226:229], v[30:33]
	v_mfma_f32_16x16x32_bf16 v[14:17], v[66:69], v[230:233], v[14:17]
	v_mfma_f32_16x16x32_bf16 v[58:61], v[70:73], v[218:221], v[58:61]
	s_add_u32 m0, s4, 0x4400
	v_mfma_f32_16x16x32_bf16 v[42:45], v[70:73], v[222:225], v[42:45]
	global_load_lds_dwordx4 v99, s[28:29]
	v_mfma_f32_16x16x32_bf16 v[26:29], v[70:73], v[226:229], v[26:29]
	v_mfma_f32_16x16x32_bf16 v[10:13], v[70:73], v[230:233], v[10:13]
	v_mfma_f32_16x16x32_bf16 v[54:57], v[74:77], v[218:221], v[54:57]
	s_add_u32 m0, s4, 0x4800
	v_mfma_f32_16x16x32_bf16 v[38:41], v[74:77], v[222:225], v[38:41]
	global_load_lds_dwordx4 v100, s[28:29]
	v_mfma_f32_16x16x32_bf16 v[22:25], v[74:77], v[226:229], v[22:25]
	v_mfma_f32_16x16x32_bf16 v[6:9], v[74:77], v[230:233], v[6:9]
	v_mfma_f32_16x16x32_bf16 v[50:53], v[78:81], v[218:221], v[50:53]
	s_add_u32 m0, s4, 0x4c00
	v_mfma_f32_16x16x32_bf16 v[34:37], v[78:81], v[222:225], v[34:37]
	global_load_lds_dwordx4 v101, s[28:29]
	v_mfma_f32_16x16x32_bf16 v[18:21], v[78:81], v[226:229], v[18:21]
	v_mfma_f32_16x16x32_bf16 v[2:5], v[78:81], v[230:233], v[2:5]
	s_waitcnt lgkmcnt(0)
	v_mfma_f32_16x16x32_bf16 v[62:65], v[82:85], v[234:237], v[62:65]
	s_add_u32 m0, s4, 0x10000
	v_mfma_f32_16x16x32_bf16 v[46:49], v[82:85], v[238:241], v[46:49]
	global_load_lds_dwordx4 v98, s[48:49]
	v_mfma_f32_16x16x32_bf16 v[30:33], v[82:85], v[242:245], v[30:33]
	v_mfma_f32_16x16x32_bf16 v[14:17], v[82:85], v[246:249], v[14:17]
	v_mfma_f32_16x16x32_bf16 v[58:61], v[86:89], v[234:237], v[58:61]
	s_add_u32 m0, s4, 0x10400
	v_mfma_f32_16x16x32_bf16 v[42:45], v[86:89], v[238:241], v[42:45]
	global_load_lds_dwordx4 v99, s[48:49]
	v_mfma_f32_16x16x32_bf16 v[26:29], v[86:89], v[242:245], v[26:29]
	v_mfma_f32_16x16x32_bf16 v[10:13], v[86:89], v[246:249], v[10:13]
	v_mfma_f32_16x16x32_bf16 v[54:57], v[90:93], v[234:237], v[54:57]
	s_add_u32 m0, s4, 0x10800
	v_mfma_f32_16x16x32_bf16 v[38:41], v[90:93], v[238:241], v[38:41]
	global_load_lds_dwordx4 v100, s[48:49]
	v_mfma_f32_16x16x32_bf16 v[22:25], v[90:93], v[242:245], v[22:25]
	v_mfma_f32_16x16x32_bf16 v[6:9], v[90:93], v[246:249], v[6:9]
	v_mfma_f32_16x16x32_bf16 v[50:53], v[94:97], v[234:237], v[50:53]
	s_add_u32 m0, s4, 0x10c00
	v_mfma_f32_16x16x32_bf16 v[34:37], v[94:97], v[238:241], v[34:37]
	global_load_lds_dwordx4 v101, s[48:49]
	v_mfma_f32_16x16x32_bf16 v[18:21], v[94:97], v[242:245], v[18:21]
	v_mfma_f32_16x16x32_bf16 v[2:5], v[94:97], v[246:249], v[2:5]
	s_waitcnt vmcnt(8)
	s_barrier
	ds_read_b128 v[218:221], v102 offset:0
	ds_read_b128 v[222:225], v102 offset:2048
	ds_read_b128 v[226:229], v102 offset:4096
	ds_read_b128 v[230:233], v102 offset:6144
	ds_read_b128 v[234:237], v103 offset:0
	ds_read_b128 v[238:241], v103 offset:2048
	ds_read_b128 v[242:245], v103 offset:4096
	ds_read_b128 v[246:249], v103 offset:6144
	s_waitcnt lgkmcnt(4)
	v_mfma_f32_16x16x32_bf16 v[106:109], v[66:69], v[218:221], v[106:109]
	s_add_u32 m0, s4, 0xc000
	v_mfma_f32_16x16x32_bf16 v[122:125], v[66:69], v[222:225], v[122:125]
	global_load_lds_dwordx4 v98, s[6:7]
	v_mfma_f32_16x16x32_bf16 v[138:141], v[66:69], v[226:229], v[138:141]
	v_mfma_f32_16x16x32_bf16 v[162:165], v[66:69], v[230:233], v[162:165]
	v_mfma_f32_16x16x32_bf16 v[110:113], v[70:73], v[218:221], v[110:113]
	s_add_u32 m0, s4, 0xc400
	v_mfma_f32_16x16x32_bf16 v[126:129], v[70:73], v[222:225], v[126:129]
	global_load_lds_dwordx4 v99, s[6:7]
	v_mfma_f32_16x16x32_bf16 v[142:145], v[70:73], v[226:229], v[142:145]
	v_mfma_f32_16x16x32_bf16 v[166:169], v[70:73], v[230:233], v[166:169]
	v_mfma_f32_16x16x32_bf16 v[114:117], v[74:77], v[218:221], v[114:117]
	s_add_u32 m0, s4, 0xc800
	v_mfma_f32_16x16x32_bf16 v[130:133], v[74:77], v[222:225], v[130:133]
	global_load_lds_dwordx4 v100, s[6:7]
	v_mfma_f32_16x16x32_bf16 v[154:157], v[74:77], v[226:229], v[154:157]
	v_mfma_f32_16x16x32_bf16 v[170:173], v[74:77], v[230:233], v[170:173]
	v_mfma_f32_16x16x32_bf16 v[118:121], v[78:81], v[218:221], v[118:121]
	s_add_u32 m0, s4, 0xcc00
	v_mfma_f32_16x16x32_bf16 v[134:137], v[78:81], v[222:225], v[134:137]
	global_load_lds_dwordx4 v101, s[6:7]
	v_mfma_f32_16x16x32_bf16 v[158:161], v[78:81], v[226:229], v[158:161]
	v_mfma_f32_16x16x32_bf16 v[174:177], v[78:81], v[230:233], v[174:177]
	v_add_u32_e32 v98, 0x80, v98
	v_add_u32_e32 v99, 0x80, v99
	v_add_u32_e32 v100, 0x80, v100
	v_add_u32_e32 v101, 0x80, v101
	s_waitcnt lgkmcnt(0)
	v_mfma_f32_16x16x32_bf16 v[106:109], v[82:85], v[234:237], v[106:109]
	v_mfma_f32_16x16x32_bf16 v[122:125], v[82:85], v[238:241], v[122:125]
	v_mfma_f32_16x16x32_bf16 v[138:141], v[82:85], v[242:245], v[138:141]
	v_mfma_f32_16x16x32_bf16 v[162:165], v[82:85], v[246:249], v[162:165]
	v_mfma_f32_16x16x32_bf16 v[110:113], v[86:89], v[234:237], v[110:113]
	v_mfma_f32_16x16x32_bf16 v[126:129], v[86:89], v[238:241], v[126:129]
	v_mfma_f32_16x16x32_bf16 v[142:145], v[86:89], v[242:245], v[142:145]
	v_mfma_f32_16x16x32_bf16 v[166:169], v[86:89], v[246:249], v[166:169]
	v_mfma_f32_16x16x32_bf16 v[114:117], v[90:93], v[234:237], v[114:117]
	v_mfma_f32_16x16x32_bf16 v[130:133], v[90:93], v[238:241], v[130:133]
	v_mfma_f32_16x16x32_bf16 v[154:157], v[90:93], v[242:245], v[154:157]
	v_mfma_f32_16x16x32_bf16 v[170:173], v[90:93], v[246:249], v[170:173]
	v_mfma_f32_16x16x32_bf16 v[118:121], v[94:97], v[234:237], v[118:121]
	v_mfma_f32_16x16x32_bf16 v[134:137], v[94:97], v[238:241], v[134:137]
	v_mfma_f32_16x16x32_bf16 v[158:161], v[94:97], v[242:245], v[158:161]
	v_mfma_f32_16x16x32_bf16 v[174:177], v[94:97], v[246:249], v[174:177]
	s_waitcnt vmcnt(4)
	s_barrier
	ds_read_b128 v[218:221], v102 offset:16384
	ds_read_b128 v[222:225], v102 offset:18432
	ds_read_b128 v[226:229], v102 offset:20480
	ds_read_b128 v[230:233], v102 offset:22528
	ds_read_b128 v[66:69], v250 offset:49152
	ds_read_b128 v[70:73], v250 offset:51200
	ds_read_b128 v[74:77], v250 offset:53248
	ds_read_b128 v[78:81], v250 offset:55296
	ds_read_b128 v[234:237], v103 offset:16384
	ds_read_b128 v[238:241], v103 offset:18432
	ds_read_b128 v[242:245], v103 offset:20480
	ds_read_b128 v[246:249], v103 offset:22528
	ds_read_b128 v[82:85], v251 offset:49152
	ds_read_b128 v[86:89], v251 offset:51200
	ds_read_b128 v[90:93], v251 offset:53248
	ds_read_b128 v[94:97], v251 offset:55296
	s_waitcnt lgkmcnt(8)
	v_mfma_f32_16x16x32_bf16 v[62:65], v[66:69], v[218:221], v[62:65]
	s_add_u32 m0, s4, 0x0
	v_mfma_f32_16x16x32_bf16 v[46:49], v[66:69], v[222:225], v[46:49]
	global_load_lds_dwordx4 v98, s[28:29]
	v_mfma_f32_16x16x32_bf16 v[30:33], v[66:69], v[226:229], v[30:33]
	v_mfma_f32_16x16x32_bf16 v[14:17], v[66:69], v[230:233], v[14:17]
	v_mfma_f32_16x16x32_bf16 v[58:61], v[70:73], v[218:221], v[58:61]
	s_add_u32 m0, s4, 0x400
	v_mfma_f32_16x16x32_bf16 v[42:45], v[70:73], v[222:225], v[42:45]
	global_load_lds_dwordx4 v99, s[28:29]
	v_mfma_f32_16x16x32_bf16 v[26:29], v[70:73], v[226:229], v[26:29]
	v_mfma_f32_16x16x32_bf16 v[10:13], v[70:73], v[230:233], v[10:13]
	v_mfma_f32_16x16x32_bf16 v[54:57], v[74:77], v[218:221], v[54:57]
	s_add_u32 m0, s4, 0x800
	v_mfma_f32_16x16x32_bf16 v[38:41], v[74:77], v[222:225], v[38:41]
	global_load_lds_dwordx4 v100, s[28:29]
	v_mfma_f32_16x16x32_bf16 v[22:25], v[74:77], v[226:229], v[22:25]
	v_mfma_f32_16x16x32_bf16 v[6:9], v[74:77], v[230:233], v[6:9]
	v_mfma_f32_16x16x32_bf16 v[50:53], v[78:81], v[218:221], v[50:53]
	s_add_u32 m0, s4, 0xc00
	v_mfma_f32_16x16x32_bf16 v[34:37], v[78:81], v[222:225], v[34:37]
	global_load_lds_dwordx4 v101, s[28:29]
	v_mfma_f32_16x16x32_bf16 v[18:21], v[78:81], v[226:229], v[18:21]
	v_mfma_f32_16x16x32_bf16 v[2:5], v[78:81], v[230:233], v[2:5]
	s_waitcnt lgkmcnt(0)
	v_mfma_f32_16x16x32_bf16 v[62:65], v[82:85], v[234:237], v[62:65]
	s_add_u32 m0, s4, 0x8000
	v_mfma_f32_16x16x32_bf16 v[46:49], v[82:85], v[238:241], v[46:49]
	global_load_lds_dwordx4 v98, s[48:49]
	v_mfma_f32_16x16x32_bf16 v[30:33], v[82:85], v[242:245], v[30:33]
	v_mfma_f32_16x16x32_bf16 v[14:17], v[82:85], v[246:249], v[14:17]
	v_mfma_f32_16x16x32_bf16 v[58:61], v[86:89], v[234:237], v[58:61]
	s_add_u32 m0, s4, 0x8400
	v_mfma_f32_16x16x32_bf16 v[42:45], v[86:89], v[238:241], v[42:45]
	global_load_lds_dwordx4 v99, s[48:49]
	v_mfma_f32_16x16x32_bf16 v[26:29], v[86:89], v[242:245], v[26:29]
	v_mfma_f32_16x16x32_bf16 v[10:13], v[86:89], v[246:249], v[10:13]
	v_mfma_f32_16x16x32_bf16 v[54:57], v[90:93], v[234:237], v[54:57]
	s_add_u32 m0, s4, 0x8800
	v_mfma_f32_16x16x32_bf16 v[38:41], v[90:93], v[238:241], v[38:41]
	global_load_lds_dwordx4 v100, s[48:49]
	v_mfma_f32_16x16x32_bf16 v[22:25], v[90:93], v[242:245], v[22:25]
	v_mfma_f32_16x16x32_bf16 v[6:9], v[90:93], v[246:249], v[6:9]
	v_mfma_f32_16x16x32_bf16 v[50:53], v[94:97], v[234:237], v[50:53]
	s_add_u32 m0, s4, 0x8c00
	v_mfma_f32_16x16x32_bf16 v[34:37], v[94:97], v[238:241], v[34:37]
	global_load_lds_dwordx4 v101, s[48:49]
	v_mfma_f32_16x16x32_bf16 v[18:21], v[94:97], v[242:245], v[18:21]
	v_mfma_f32_16x16x32_bf16 v[2:5], v[94:97], v[246:249], v[2:5]
	s_waitcnt vmcnt(8)
	s_barrier
	ds_read_b128 v[218:221], v102 offset:49152
	ds_read_b128 v[222:225], v102 offset:51200
	ds_read_b128 v[226:229], v102 offset:53248
	ds_read_b128 v[230:233], v102 offset:55296
	ds_read_b128 v[234:237], v103 offset:49152
	ds_read_b128 v[238:241], v103 offset:51200
	ds_read_b128 v[242:245], v103 offset:53248
	ds_read_b128 v[246:249], v103 offset:55296
	s_waitcnt lgkmcnt(4)
	v_mfma_f32_16x16x32_bf16 v[106:109], v[66:69], v[218:221], v[106:109]
	s_add_u32 m0, s4, 0x4000
	v_mfma_f32_16x16x32_bf16 v[122:125], v[66:69], v[222:225], v[122:125]
	global_load_lds_dwordx4 v98, s[6:7]
	v_mfma_f32_16x16x32_bf16 v[138:141], v[66:69], v[226:229], v[138:141]
	v_mfma_f32_16x16x32_bf16 v[162:165], v[66:69], v[230:233], v[162:165]
	v_mfma_f32_16x16x32_bf16 v[110:113], v[70:73], v[218:221], v[110:113]
	s_add_u32 m0, s4, 0x4400
	v_mfma_f32_16x16x32_bf16 v[126:129], v[70:73], v[222:225], v[126:129]
	global_load_lds_dwordx4 v99, s[6:7]
	v_mfma_f32_16x16x32_bf16 v[142:145], v[70:73], v[226:229], v[142:145]
	v_mfma_f32_16x16x32_bf16 v[166:169], v[70:73], v[230:233], v[166:169]
	v_mfma_f32_16x16x32_bf16 v[114:117], v[74:77], v[218:221], v[114:117]
	s_add_u32 m0, s4, 0x4800
	v_mfma_f32_16x16x32_bf16 v[130:133], v[74:77], v[222:225], v[130:133]
	global_load_lds_dwordx4 v100, s[6:7]
	v_mfma_f32_16x16x32_bf16 v[154:157], v[74:77], v[226:229], v[154:157]
	v_mfma_f32_16x16x32_bf16 v[170:173], v[74:77], v[230:233], v[170:173]
	v_mfma_f32_16x16x32_bf16 v[118:121], v[78:81], v[218:221], v[118:121]
	s_add_u32 m0, s4, 0x4c00
	v_mfma_f32_16x16x32_bf16 v[134:137], v[78:81], v[222:225], v[134:137]
	global_load_lds_dwordx4 v101, s[6:7]
	v_mfma_f32_16x16x32_bf16 v[158:161], v[78:81], v[226:229], v[158:161]
	v_mfma_f32_16x16x32_bf16 v[174:177], v[78:81], v[230:233], v[174:177]
	v_add_u32_e32 v98, 0x80, v98
	v_add_u32_e32 v99, 0x80, v99
	v_add_u32_e32 v100, 0x80, v100
	v_add_u32_e32 v101, 0x80, v101
	s_waitcnt lgkmcnt(0)
	v_mfma_f32_16x16x32_bf16 v[106:109], v[82:85], v[234:237], v[106:109]
	v_mfma_f32_16x16x32_bf16 v[122:125], v[82:85], v[238:241], v[122:125]
	v_mfma_f32_16x16x32_bf16 v[138:141], v[82:85], v[242:245], v[138:141]
	v_mfma_f32_16x16x32_bf16 v[162:165], v[82:85], v[246:249], v[162:165]
	v_mfma_f32_16x16x32_bf16 v[110:113], v[86:89], v[234:237], v[110:113]
	v_mfma_f32_16x16x32_bf16 v[126:129], v[86:89], v[238:241], v[126:129]
	v_mfma_f32_16x16x32_bf16 v[142:145], v[86:89], v[242:245], v[142:145]
	v_mfma_f32_16x16x32_bf16 v[166:169], v[86:89], v[246:249], v[166:169]
	v_mfma_f32_16x16x32_bf16 v[114:117], v[90:93], v[234:237], v[114:117]
	v_mfma_f32_16x16x32_bf16 v[130:133], v[90:93], v[238:241], v[130:133]
	v_mfma_f32_16x16x32_bf16 v[154:157], v[90:93], v[242:245], v[154:157]
	v_mfma_f32_16x16x32_bf16 v[170:173], v[90:93], v[246:249], v[170:173]
	v_mfma_f32_16x16x32_bf16 v[118:121], v[94:97], v[234:237], v[118:121]
	v_mfma_f32_16x16x32_bf16 v[134:137], v[94:97], v[238:241], v[134:137]
	v_mfma_f32_16x16x32_bf16 v[158:161], v[94:97], v[242:245], v[158:161]
	v_mfma_f32_16x16x32_bf16 v[174:177], v[94:97], v[246:249], v[174:177]
	s_waitcnt vmcnt(4)
	s_barrier
	ds_read_b128 v[218:221], v102 offset:0
	ds_read_b128 v[222:225], v102 offset:2048
	ds_read_b128 v[226:229], v102 offset:4096
	ds_read_b128 v[230:233], v102 offset:6144
	ds_read_b128 v[66:69], v104 offset:32768
	ds_read_b128 v[70:73], v104 offset:34816
	ds_read_b128 v[74:77], v104 offset:36864
	ds_read_b128 v[78:81], v104 offset:38912
	ds_read_b128 v[234:237], v103 offset:0
	ds_read_b128 v[238:241], v103 offset:2048
	ds_read_b128 v[242:245], v103 offset:4096
	ds_read_b128 v[246:249], v103 offset:6144
	ds_read_b128 v[82:85], v105 offset:32768
	ds_read_b128 v[86:89], v105 offset:34816
	ds_read_b128 v[90:93], v105 offset:36864
	ds_read_b128 v[94:97], v105 offset:38912
	s_waitcnt lgkmcnt(8)
	v_mfma_f32_16x16x32_bf16 v[62:65], v[66:69], v[218:221], v[62:65]
	s_add_u32 m0, s4, 0xc000
	v_mfma_f32_16x16x32_bf16 v[46:49], v[66:69], v[222:225], v[46:49]
	global_load_lds_dwordx4 v98, s[28:29]
	v_mfma_f32_16x16x32_bf16 v[30:33], v[66:69], v[226:229], v[30:33]
	v_mfma_f32_16x16x32_bf16 v[14:17], v[66:69], v[230:233], v[14:17]
	v_mfma_f32_16x16x32_bf16 v[58:61], v[70:73], v[218:221], v[58:61]
	s_add_u32 m0, s4, 0xc400
	v_mfma_f32_16x16x32_bf16 v[42:45], v[70:73], v[222:225], v[42:45]
	global_load_lds_dwordx4 v99, s[28:29]
	v_mfma_f32_16x16x32_bf16 v[26:29], v[70:73], v[226:229], v[26:29]
	v_mfma_f32_16x16x32_bf16 v[10:13], v[70:73], v[230:233], v[10:13]
	v_mfma_f32_16x16x32_bf16 v[54:57], v[74:77], v[218:221], v[54:57]
	s_add_u32 m0, s4, 0xc800
	v_mfma_f32_16x16x32_bf16 v[38:41], v[74:77], v[222:225], v[38:41]
	global_load_lds_dwordx4 v100, s[28:29]
	v_mfma_f32_16x16x32_bf16 v[22:25], v[74:77], v[226:229], v[22:25]
	v_mfma_f32_16x16x32_bf16 v[6:9], v[74:77], v[230:233], v[6:9]
	v_mfma_f32_16x16x32_bf16 v[50:53], v[78:81], v[218:221], v[50:53]
	s_add_u32 m0, s4, 0xcc00
	v_mfma_f32_16x16x32_bf16 v[34:37], v[78:81], v[222:225], v[34:37]
	global_load_lds_dwordx4 v101, s[28:29]
	v_mfma_f32_16x16x32_bf16 v[18:21], v[78:81], v[226:229], v[18:21]
	v_mfma_f32_16x16x32_bf16 v[2:5], v[78:81], v[230:233], v[2:5]
	s_waitcnt lgkmcnt(0)
	v_mfma_f32_16x16x32_bf16 v[62:65], v[82:85], v[234:237], v[62:65]
	s_add_u32 m0, s4, 0x10000
	v_mfma_f32_16x16x32_bf16 v[46:49], v[82:85], v[238:241], v[46:49]
	global_load_lds_dwordx4 v98, s[48:49]
	v_mfma_f32_16x16x32_bf16 v[30:33], v[82:85], v[242:245], v[30:33]
	v_mfma_f32_16x16x32_bf16 v[14:17], v[82:85], v[246:249], v[14:17]
	v_mfma_f32_16x16x32_bf16 v[58:61], v[86:89], v[234:237], v[58:61]
	s_add_u32 m0, s4, 0x10400
	v_mfma_f32_16x16x32_bf16 v[42:45], v[86:89], v[238:241], v[42:45]
	global_load_lds_dwordx4 v99, s[48:49]
	v_mfma_f32_16x16x32_bf16 v[26:29], v[86:89], v[242:245], v[26:29]
	v_mfma_f32_16x16x32_bf16 v[10:13], v[86:89], v[246:249], v[10:13]
	v_mfma_f32_16x16x32_bf16 v[54:57], v[90:93], v[234:237], v[54:57]
	s_add_u32 m0, s4, 0x10800
	v_mfma_f32_16x16x32_bf16 v[38:41], v[90:93], v[238:241], v[38:41]
	global_load_lds_dwordx4 v100, s[48:49]
	v_mfma_f32_16x16x32_bf16 v[22:25], v[90:93], v[242:245], v[22:25]
	v_mfma_f32_16x16x32_bf16 v[6:9], v[90:93], v[246:249], v[6:9]
	v_mfma_f32_16x16x32_bf16 v[50:53], v[94:97], v[234:237], v[50:53]
	s_add_u32 m0, s4, 0x10c00
	v_mfma_f32_16x16x32_bf16 v[34:37], v[94:97], v[238:241], v[34:37]
	global_load_lds_dwordx4 v101, s[48:49]
	v_mfma_f32_16x16x32_bf16 v[18:21], v[94:97], v[242:245], v[18:21]
	v_mfma_f32_16x16x32_bf16 v[2:5], v[94:97], v[246:249], v[2:5]
	s_waitcnt vmcnt(8)
	s_barrier
	ds_read_b128 v[218:221], v102 offset:16384
	ds_read_b128 v[222:225], v102 offset:18432
	ds_read_b128 v[226:229], v102 offset:20480
	ds_read_b128 v[230:233], v102 offset:22528
	ds_read_b128 v[234:237], v103 offset:16384
	ds_read_b128 v[238:241], v103 offset:18432
	ds_read_b128 v[242:245], v103 offset:20480
	ds_read_b128 v[246:249], v103 offset:22528
	s_waitcnt lgkmcnt(4)
	v_mfma_f32_16x16x32_bf16 v[106:109], v[66:69], v[218:221], v[106:109]
	s_add_u32 m0, s4, 0x0
	v_mfma_f32_16x16x32_bf16 v[122:125], v[66:69], v[222:225], v[122:125]
	global_load_lds_dwordx4 v98, s[6:7]
	v_mfma_f32_16x16x32_bf16 v[138:141], v[66:69], v[226:229], v[138:141]
	v_mfma_f32_16x16x32_bf16 v[162:165], v[66:69], v[230:233], v[162:165]
	v_mfma_f32_16x16x32_bf16 v[110:113], v[70:73], v[218:221], v[110:113]
	s_add_u32 m0, s4, 0x400
	v_mfma_f32_16x16x32_bf16 v[126:129], v[70:73], v[222:225], v[126:129]
	global_load_lds_dwordx4 v99, s[6:7]
	v_mfma_f32_16x16x32_bf16 v[142:145], v[70:73], v[226:229], v[142:145]
	v_mfma_f32_16x16x32_bf16 v[166:169], v[70:73], v[230:233], v[166:169]
	v_mfma_f32_16x16x32_bf16 v[114:117], v[74:77], v[218:221], v[114:117]
	s_add_u32 m0, s4, 0x800
	v_mfma_f32_16x16x32_bf16 v[130:133], v[74:77], v[222:225], v[130:133]
	global_load_lds_dwordx4 v100, s[6:7]
	v_mfma_f32_16x16x32_bf16 v[154:157], v[74:77], v[226:229], v[154:157]
	v_mfma_f32_16x16x32_bf16 v[170:173], v[74:77], v[230:233], v[170:173]
	v_mfma_f32_16x16x32_bf16 v[118:121], v[78:81], v[218:221], v[118:121]
	s_add_u32 m0, s4, 0xc00
	v_mfma_f32_16x16x32_bf16 v[134:137], v[78:81], v[222:225], v[134:137]
	global_load_lds_dwordx4 v101, s[6:7]
	v_mfma_f32_16x16x32_bf16 v[158:161], v[78:81], v[226:229], v[158:161]
	v_mfma_f32_16x16x32_bf16 v[174:177], v[78:81], v[230:233], v[174:177]
	v_add_u32_e32 v98, 0x80, v98
	v_add_u32_e32 v99, 0x80, v99
	v_add_u32_e32 v100, 0x80, v100
	v_add_u32_e32 v101, 0x80, v101
	s_waitcnt lgkmcnt(0)
	v_mfma_f32_16x16x32_bf16 v[106:109], v[82:85], v[234:237], v[106:109]
	v_mfma_f32_16x16x32_bf16 v[122:125], v[82:85], v[238:241], v[122:125]
	v_mfma_f32_16x16x32_bf16 v[138:141], v[82:85], v[242:245], v[138:141]
	v_mfma_f32_16x16x32_bf16 v[162:165], v[82:85], v[246:249], v[162:165]
	v_mfma_f32_16x16x32_bf16 v[110:113], v[86:89], v[234:237], v[110:113]
	v_mfma_f32_16x16x32_bf16 v[126:129], v[86:89], v[238:241], v[126:129]
	v_mfma_f32_16x16x32_bf16 v[142:145], v[86:89], v[242:245], v[142:145]
	v_mfma_f32_16x16x32_bf16 v[166:169], v[86:89], v[246:249], v[166:169]
	v_mfma_f32_16x16x32_bf16 v[114:117], v[90:93], v[234:237], v[114:117]
	v_mfma_f32_16x16x32_bf16 v[130:133], v[90:93], v[238:241], v[130:133]
	v_mfma_f32_16x16x32_bf16 v[154:157], v[90:93], v[242:245], v[154:157]
	v_mfma_f32_16x16x32_bf16 v[170:173], v[90:93], v[246:249], v[170:173]
	v_mfma_f32_16x16x32_bf16 v[118:121], v[94:97], v[234:237], v[118:121]
	v_mfma_f32_16x16x32_bf16 v[134:137], v[94:97], v[238:241], v[134:137]
	v_mfma_f32_16x16x32_bf16 v[158:161], v[94:97], v[242:245], v[158:161]
	v_mfma_f32_16x16x32_bf16 v[174:177], v[94:97], v[246:249], v[174:177]
	s_waitcnt vmcnt(4)
	s_barrier
	ds_read_b128 v[218:221], v102 offset:49152
	ds_read_b128 v[222:225], v102 offset:51200
	ds_read_b128 v[226:229], v102 offset:53248
	ds_read_b128 v[230:233], v102 offset:55296
	ds_read_b128 v[66:69], v250 offset:49152
	ds_read_b128 v[70:73], v250 offset:51200
	ds_read_b128 v[74:77], v250 offset:53248
	ds_read_b128 v[78:81], v250 offset:55296
	ds_read_b128 v[234:237], v103 offset:49152
	ds_read_b128 v[238:241], v103 offset:51200
	ds_read_b128 v[242:245], v103 offset:53248
	ds_read_b128 v[246:249], v103 offset:55296
	ds_read_b128 v[82:85], v251 offset:49152
	ds_read_b128 v[86:89], v251 offset:51200
	ds_read_b128 v[90:93], v251 offset:53248
	ds_read_b128 v[94:97], v251 offset:55296
	s_waitcnt lgkmcnt(8)
	v_mfma_f32_16x16x32_bf16 v[62:65], v[66:69], v[218:221], v[62:65]
	s_add_u32 m0, s4, 0x4000
	v_mfma_f32_16x16x32_bf16 v[46:49], v[66:69], v[222:225], v[46:49]
	global_load_lds_dwordx4 v98, s[28:29]
	v_mfma_f32_16x16x32_bf16 v[30:33], v[66:69], v[226:229], v[30:33]
	v_mfma_f32_16x16x32_bf16 v[14:17], v[66:69], v[230:233], v[14:17]
	v_mfma_f32_16x16x32_bf16 v[58:61], v[70:73], v[218:221], v[58:61]
	s_add_u32 m0, s4, 0x4400
	v_mfma_f32_16x16x32_bf16 v[42:45], v[70:73], v[222:225], v[42:45]
	global_load_lds_dwordx4 v99, s[28:29]
	v_mfma_f32_16x16x32_bf16 v[26:29], v[70:73], v[226:229], v[26:29]
	v_mfma_f32_16x16x32_bf16 v[10:13], v[70:73], v[230:233], v[10:13]
	v_mfma_f32_16x16x32_bf16 v[54:57], v[74:77], v[218:221], v[54:57]
	s_add_u32 m0, s4, 0x4800
	v_mfma_f32_16x16x32_bf16 v[38:41], v[74:77], v[222:225], v[38:41]
	global_load_lds_dwordx4 v100, s[28:29]
	v_mfma_f32_16x16x32_bf16 v[22:25], v[74:77], v[226:229], v[22:25]
	v_mfma_f32_16x16x32_bf16 v[6:9], v[74:77], v[230:233], v[6:9]
	v_mfma_f32_16x16x32_bf16 v[50:53], v[78:81], v[218:221], v[50:53]
	s_add_u32 m0, s4, 0x4c00
	v_mfma_f32_16x16x32_bf16 v[34:37], v[78:81], v[222:225], v[34:37]
	global_load_lds_dwordx4 v101, s[28:29]
	v_mfma_f32_16x16x32_bf16 v[18:21], v[78:81], v[226:229], v[18:21]
	v_mfma_f32_16x16x32_bf16 v[2:5], v[78:81], v[230:233], v[2:5]
	s_waitcnt lgkmcnt(0)
	v_mfma_f32_16x16x32_bf16 v[62:65], v[82:85], v[234:237], v[62:65]
	s_add_u32 m0, s4, 0x8000
	v_mfma_f32_16x16x32_bf16 v[46:49], v[82:85], v[238:241], v[46:49]
	global_load_lds_dwordx4 v98, s[48:49]
	v_mfma_f32_16x16x32_bf16 v[30:33], v[82:85], v[242:245], v[30:33]
	v_mfma_f32_16x16x32_bf16 v[14:17], v[82:85], v[246:249], v[14:17]
	v_mfma_f32_16x16x32_bf16 v[58:61], v[86:89], v[234:237], v[58:61]
	s_add_u32 m0, s4, 0x8400
	v_mfma_f32_16x16x32_bf16 v[42:45], v[86:89], v[238:241], v[42:45]
	global_load_lds_dwordx4 v99, s[48:49]
	v_mfma_f32_16x16x32_bf16 v[26:29], v[86:89], v[242:245], v[26:29]
	v_mfma_f32_16x16x32_bf16 v[10:13], v[86:89], v[246:249], v[10:13]
	v_mfma_f32_16x16x32_bf16 v[54:57], v[90:93], v[234:237], v[54:57]
	s_add_u32 m0, s4, 0x8800
	v_mfma_f32_16x16x32_bf16 v[38:41], v[90:93], v[238:241], v[38:41]
	global_load_lds_dwordx4 v100, s[48:49]
	v_mfma_f32_16x16x32_bf16 v[22:25], v[90:93], v[242:245], v[22:25]
	v_mfma_f32_16x16x32_bf16 v[6:9], v[90:93], v[246:249], v[6:9]
	v_mfma_f32_16x16x32_bf16 v[50:53], v[94:97], v[234:237], v[50:53]
	s_add_u32 m0, s4, 0x8c00
	v_mfma_f32_16x16x32_bf16 v[34:37], v[94:97], v[238:241], v[34:37]
	global_load_lds_dwordx4 v101, s[48:49]
	v_mfma_f32_16x16x32_bf16 v[18:21], v[94:97], v[242:245], v[18:21]
	v_mfma_f32_16x16x32_bf16 v[2:5], v[94:97], v[246:249], v[2:5]
	s_waitcnt vmcnt(8)
	s_barrier
	ds_read_b128 v[218:221], v102 offset:0
	ds_read_b128 v[222:225], v102 offset:2048
	ds_read_b128 v[226:229], v102 offset:4096
	ds_read_b128 v[230:233], v102 offset:6144
	ds_read_b128 v[234:237], v103 offset:0
	ds_read_b128 v[238:241], v103 offset:2048
	ds_read_b128 v[242:245], v103 offset:4096
	ds_read_b128 v[246:249], v103 offset:6144
	s_waitcnt lgkmcnt(4)
	v_mfma_f32_16x16x32_bf16 v[106:109], v[66:69], v[218:221], v[106:109]
	s_add_u32 m0, s4, 0xc000
	v_mfma_f32_16x16x32_bf16 v[122:125], v[66:69], v[222:225], v[122:125]
	global_load_lds_dwordx4 v98, s[6:7]
	v_mfma_f32_16x16x32_bf16 v[138:141], v[66:69], v[226:229], v[138:141]
	v_mfma_f32_16x16x32_bf16 v[162:165], v[66:69], v[230:233], v[162:165]
	v_mfma_f32_16x16x32_bf16 v[110:113], v[70:73], v[218:221], v[110:113]
	s_add_u32 m0, s4, 0xc400
	v_mfma_f32_16x16x32_bf16 v[126:129], v[70:73], v[222:225], v[126:129]
	global_load_lds_dwordx4 v99, s[6:7]
	v_mfma_f32_16x16x32_bf16 v[142:145], v[70:73], v[226:229], v[142:145]
	v_mfma_f32_16x16x32_bf16 v[166:169], v[70:73], v[230:233], v[166:169]
	v_mfma_f32_16x16x32_bf16 v[114:117], v[74:77], v[218:221], v[114:117]
	s_add_u32 m0, s4, 0xc800
	v_mfma_f32_16x16x32_bf16 v[130:133], v[74:77], v[222:225], v[130:133]
	global_load_lds_dwordx4 v100, s[6:7]
	v_mfma_f32_16x16x32_bf16 v[154:157], v[74:77], v[226:229], v[154:157]
	v_mfma_f32_16x16x32_bf16 v[170:173], v[74:77], v[230:233], v[170:173]
	v_mfma_f32_16x16x32_bf16 v[118:121], v[78:81], v[218:221], v[118:121]
	s_add_u32 m0, s4, 0xcc00
	v_mfma_f32_16x16x32_bf16 v[134:137], v[78:81], v[222:225], v[134:137]
	global_load_lds_dwordx4 v101, s[6:7]
	v_mfma_f32_16x16x32_bf16 v[158:161], v[78:81], v[226:229], v[158:161]
	v_mfma_f32_16x16x32_bf16 v[174:177], v[78:81], v[230:233], v[174:177]
	v_add_u32_e32 v98, 0x80, v98
	v_add_u32_e32 v99, 0x80, v99
	v_add_u32_e32 v100, 0x80, v100
	v_add_u32_e32 v101, 0x80, v101
	s_waitcnt lgkmcnt(0)
	v_mfma_f32_16x16x32_bf16 v[106:109], v[82:85], v[234:237], v[106:109]
	v_mfma_f32_16x16x32_bf16 v[122:125], v[82:85], v[238:241], v[122:125]
	v_mfma_f32_16x16x32_bf16 v[138:141], v[82:85], v[242:245], v[138:141]
	v_mfma_f32_16x16x32_bf16 v[162:165], v[82:85], v[246:249], v[162:165]
	v_mfma_f32_16x16x32_bf16 v[110:113], v[86:89], v[234:237], v[110:113]
	v_mfma_f32_16x16x32_bf16 v[126:129], v[86:89], v[238:241], v[126:129]
	v_mfma_f32_16x16x32_bf16 v[142:145], v[86:89], v[242:245], v[142:145]
	v_mfma_f32_16x16x32_bf16 v[166:169], v[86:89], v[246:249], v[166:169]
	v_mfma_f32_16x16x32_bf16 v[114:117], v[90:93], v[234:237], v[114:117]
	v_mfma_f32_16x16x32_bf16 v[130:133], v[90:93], v[238:241], v[130:133]
	v_mfma_f32_16x16x32_bf16 v[154:157], v[90:93], v[242:245], v[154:157]
	v_mfma_f32_16x16x32_bf16 v[170:173], v[90:93], v[246:249], v[170:173]
	v_mfma_f32_16x16x32_bf16 v[118:121], v[94:97], v[234:237], v[118:121]
	v_mfma_f32_16x16x32_bf16 v[134:137], v[94:97], v[238:241], v[134:137]
	v_mfma_f32_16x16x32_bf16 v[158:161], v[94:97], v[242:245], v[158:161]
	v_mfma_f32_16x16x32_bf16 v[174:177], v[94:97], v[246:249], v[174:177]
	s_waitcnt vmcnt(4)
	s_barrier
	ds_read_b128 v[218:221], v102 offset:16384
	ds_read_b128 v[222:225], v102 offset:18432
	ds_read_b128 v[226:229], v102 offset:20480
	ds_read_b128 v[230:233], v102 offset:22528
	ds_read_b128 v[66:69], v104 offset:32768
	ds_read_b128 v[70:73], v104 offset:34816
	ds_read_b128 v[74:77], v104 offset:36864
	ds_read_b128 v[78:81], v104 offset:38912
	ds_read_b128 v[234:237], v103 offset:16384
	ds_read_b128 v[238:241], v103 offset:18432
	ds_read_b128 v[242:245], v103 offset:20480
	ds_read_b128 v[246:249], v103 offset:22528
	ds_read_b128 v[82:85], v105 offset:32768
	ds_read_b128 v[86:89], v105 offset:34816
	ds_read_b128 v[90:93], v105 offset:36864
	ds_read_b128 v[94:97], v105 offset:38912
	s_waitcnt lgkmcnt(8)
	v_mfma_f32_16x16x32_bf16 v[62:65], v[66:69], v[218:221], v[62:65]
	s_add_u32 m0, s4, 0x0
	v_mfma_f32_16x16x32_bf16 v[46:49], v[66:69], v[222:225], v[46:49]
	global_load_lds_dwordx4 v98, s[28:29]
	v_mfma_f32_16x16x32_bf16 v[30:33], v[66:69], v[226:229], v[30:33]
	v_mfma_f32_16x16x32_bf16 v[14:17], v[66:69], v[230:233], v[14:17]
	v_mfma_f32_16x16x32_bf16 v[58:61], v[70:73], v[218:221], v[58:61]
	s_add_u32 m0, s4, 0x400
	v_mfma_f32_16x16x32_bf16 v[42:45], v[70:73], v[222:225], v[42:45]
	global_load_lds_dwordx4 v99, s[28:29]
	v_mfma_f32_16x16x32_bf16 v[26:29], v[70:73], v[226:229], v[26:29]
	v_mfma_f32_16x16x32_bf16 v[10:13], v[70:73], v[230:233], v[10:13]
	v_mfma_f32_16x16x32_bf16 v[54:57], v[74:77], v[218:221], v[54:57]
	s_add_u32 m0, s4, 0x800
	v_mfma_f32_16x16x32_bf16 v[38:41], v[74:77], v[222:225], v[38:41]
	global_load_lds_dwordx4 v100, s[28:29]
	v_mfma_f32_16x16x32_bf16 v[22:25], v[74:77], v[226:229], v[22:25]
	v_mfma_f32_16x16x32_bf16 v[6:9], v[74:77], v[230:233], v[6:9]
	v_mfma_f32_16x16x32_bf16 v[50:53], v[78:81], v[218:221], v[50:53]
	s_add_u32 m0, s4, 0xc00
	v_mfma_f32_16x16x32_bf16 v[34:37], v[78:81], v[222:225], v[34:37]
	global_load_lds_dwordx4 v101, s[28:29]
	v_mfma_f32_16x16x32_bf16 v[18:21], v[78:81], v[226:229], v[18:21]
	v_mfma_f32_16x16x32_bf16 v[2:5], v[78:81], v[230:233], v[2:5]
	s_waitcnt lgkmcnt(0)
	v_mfma_f32_16x16x32_bf16 v[62:65], v[82:85], v[234:237], v[62:65]
	s_add_u32 m0, s4, 0x10000
	v_mfma_f32_16x16x32_bf16 v[46:49], v[82:85], v[238:241], v[46:49]
	global_load_lds_dwordx4 v98, s[48:49]
	v_mfma_f32_16x16x32_bf16 v[30:33], v[82:85], v[242:245], v[30:33]
	v_mfma_f32_16x16x32_bf16 v[14:17], v[82:85], v[246:249], v[14:17]
	v_mfma_f32_16x16x32_bf16 v[58:61], v[86:89], v[234:237], v[58:61]
	s_add_u32 m0, s4, 0x10400
	v_mfma_f32_16x16x32_bf16 v[42:45], v[86:89], v[238:241], v[42:45]
	global_load_lds_dwordx4 v99, s[48:49]
	v_mfma_f32_16x16x32_bf16 v[26:29], v[86:89], v[242:245], v[26:29]
	v_mfma_f32_16x16x32_bf16 v[10:13], v[86:89], v[246:249], v[10:13]
	v_mfma_f32_16x16x32_bf16 v[54:57], v[90:93], v[234:237], v[54:57]
	s_add_u32 m0, s4, 0x10800
	v_mfma_f32_16x16x32_bf16 v[38:41], v[90:93], v[238:241], v[38:41]
	global_load_lds_dwordx4 v100, s[48:49]
	v_mfma_f32_16x16x32_bf16 v[22:25], v[90:93], v[242:245], v[22:25]
	v_mfma_f32_16x16x32_bf16 v[6:9], v[90:93], v[246:249], v[6:9]
	v_mfma_f32_16x16x32_bf16 v[50:53], v[94:97], v[234:237], v[50:53]
	s_add_u32 m0, s4, 0x10c00
	v_mfma_f32_16x16x32_bf16 v[34:37], v[94:97], v[238:241], v[34:37]
	global_load_lds_dwordx4 v101, s[48:49]
	v_mfma_f32_16x16x32_bf16 v[18:21], v[94:97], v[242:245], v[18:21]
	v_mfma_f32_16x16x32_bf16 v[2:5], v[94:97], v[246:249], v[2:5]
	s_waitcnt vmcnt(8)
	s_barrier
	ds_read_b128 v[218:221], v102 offset:49152
	ds_read_b128 v[222:225], v102 offset:51200
	ds_read_b128 v[226:229], v102 offset:53248
	ds_read_b128 v[230:233], v102 offset:55296
	ds_read_b128 v[234:237], v103 offset:49152
	ds_read_b128 v[238:241], v103 offset:51200
	ds_read_b128 v[242:245], v103 offset:53248
	ds_read_b128 v[246:249], v103 offset:55296
	s_waitcnt lgkmcnt(4)
	v_mfma_f32_16x16x32_bf16 v[106:109], v[66:69], v[218:221], v[106:109]
	s_add_u32 m0, s4, 0x4000
	v_mfma_f32_16x16x32_bf16 v[122:125], v[66:69], v[222:225], v[122:125]
	global_load_lds_dwordx4 v98, s[6:7]
	v_mfma_f32_16x16x32_bf16 v[138:141], v[66:69], v[226:229], v[138:141]
	v_mfma_f32_16x16x32_bf16 v[162:165], v[66:69], v[230:233], v[162:165]
	v_mfma_f32_16x16x32_bf16 v[110:113], v[70:73], v[218:221], v[110:113]
	s_add_u32 m0, s4, 0x4400
	v_mfma_f32_16x16x32_bf16 v[126:129], v[70:73], v[222:225], v[126:129]
	global_load_lds_dwordx4 v99, s[6:7]
	v_mfma_f32_16x16x32_bf16 v[142:145], v[70:73], v[226:229], v[142:145]
	v_mfma_f32_16x16x32_bf16 v[166:169], v[70:73], v[230:233], v[166:169]
	v_mfma_f32_16x16x32_bf16 v[114:117], v[74:77], v[218:221], v[114:117]
	s_add_u32 m0, s4, 0x4800
	v_mfma_f32_16x16x32_bf16 v[130:133], v[74:77], v[222:225], v[130:133]
	global_load_lds_dwordx4 v100, s[6:7]
	v_mfma_f32_16x16x32_bf16 v[154:157], v[74:77], v[226:229], v[154:157]
	v_mfma_f32_16x16x32_bf16 v[170:173], v[74:77], v[230:233], v[170:173]
	v_mfma_f32_16x16x32_bf16 v[118:121], v[78:81], v[218:221], v[118:121]
	s_add_u32 m0, s4, 0x4c00
	v_mfma_f32_16x16x32_bf16 v[134:137], v[78:81], v[222:225], v[134:137]
	global_load_lds_dwordx4 v101, s[6:7]
	v_mfma_f32_16x16x32_bf16 v[158:161], v[78:81], v[226:229], v[158:161]
	v_mfma_f32_16x16x32_bf16 v[174:177], v[78:81], v[230:233], v[174:177]
	v_add_u32_e32 v98, 0x80, v98
	v_add_u32_e32 v99, 0x80, v99
	v_add_u32_e32 v100, 0x80, v100
	v_add_u32_e32 v101, 0x80, v101
	s_waitcnt lgkmcnt(0)
	v_mfma_f32_16x16x32_bf16 v[106:109], v[82:85], v[234:237], v[106:109]
	v_mfma_f32_16x16x32_bf16 v[122:125], v[82:85], v[238:241], v[122:125]
	v_mfma_f32_16x16x32_bf16 v[138:141], v[82:85], v[242:245], v[138:141]
	v_mfma_f32_16x16x32_bf16 v[162:165], v[82:85], v[246:249], v[162:165]
	v_mfma_f32_16x16x32_bf16 v[110:113], v[86:89], v[234:237], v[110:113]
	v_mfma_f32_16x16x32_bf16 v[126:129], v[86:89], v[238:241], v[126:129]
	v_mfma_f32_16x16x32_bf16 v[142:145], v[86:89], v[242:245], v[142:145]
	v_mfma_f32_16x16x32_bf16 v[166:169], v[86:89], v[246:249], v[166:169]
	v_mfma_f32_16x16x32_bf16 v[114:117], v[90:93], v[234:237], v[114:117]
	v_mfma_f32_16x16x32_bf16 v[130:133], v[90:93], v[238:241], v[130:133]
	v_mfma_f32_16x16x32_bf16 v[154:157], v[90:93], v[242:245], v[154:157]
	v_mfma_f32_16x16x32_bf16 v[170:173], v[90:93], v[246:249], v[170:173]
	v_mfma_f32_16x16x32_bf16 v[118:121], v[94:97], v[234:237], v[118:121]
	v_mfma_f32_16x16x32_bf16 v[134:137], v[94:97], v[238:241], v[134:137]
	v_mfma_f32_16x16x32_bf16 v[158:161], v[94:97], v[242:245], v[158:161]
	v_mfma_f32_16x16x32_bf16 v[174:177], v[94:97], v[246:249], v[174:177]
	s_waitcnt vmcnt(4)
	s_barrier
	ds_read_b128 v[218:221], v102 offset:0
	ds_read_b128 v[222:225], v102 offset:2048
	ds_read_b128 v[226:229], v102 offset:4096
	ds_read_b128 v[230:233], v102 offset:6144
	ds_read_b128 v[66:69], v250 offset:49152
	ds_read_b128 v[70:73], v250 offset:51200
	ds_read_b128 v[74:77], v250 offset:53248
	ds_read_b128 v[78:81], v250 offset:55296
	ds_read_b128 v[234:237], v103 offset:0
	ds_read_b128 v[238:241], v103 offset:2048
	ds_read_b128 v[242:245], v103 offset:4096
	ds_read_b128 v[246:249], v103 offset:6144
	ds_read_b128 v[82:85], v251 offset:49152
	ds_read_b128 v[86:89], v251 offset:51200
	ds_read_b128 v[90:93], v251 offset:53248
	ds_read_b128 v[94:97], v251 offset:55296
	s_waitcnt lgkmcnt(8)
	v_mfma_f32_16x16x32_bf16 v[62:65], v[66:69], v[218:221], v[62:65]
	s_add_u32 m0, s4, 0xc000
	v_mfma_f32_16x16x32_bf16 v[46:49], v[66:69], v[222:225], v[46:49]
	global_load_lds_dwordx4 v98, s[28:29]
	v_mfma_f32_16x16x32_bf16 v[30:33], v[66:69], v[226:229], v[30:33]
	v_mfma_f32_16x16x32_bf16 v[14:17], v[66:69], v[230:233], v[14:17]
	v_mfma_f32_16x16x32_bf16 v[58:61], v[70:73], v[218:221], v[58:61]
	s_add_u32 m0, s4, 0xc400
	v_mfma_f32_16x16x32_bf16 v[42:45], v[70:73], v[222:225], v[42:45]
	global_load_lds_dwordx4 v99, s[28:29]
	v_mfma_f32_16x16x32_bf16 v[26:29], v[70:73], v[226:229], v[26:29]
	v_mfma_f32_16x16x32_bf16 v[10:13], v[70:73], v[230:233], v[10:13]
	v_mfma_f32_16x16x32_bf16 v[54:57], v[74:77], v[218:221], v[54:57]
	s_add_u32 m0, s4, 0xc800
	v_mfma_f32_16x16x32_bf16 v[38:41], v[74:77], v[222:225], v[38:41]
	global_load_lds_dwordx4 v100, s[28:29]
	v_mfma_f32_16x16x32_bf16 v[22:25], v[74:77], v[226:229], v[22:25]
	v_mfma_f32_16x16x32_bf16 v[6:9], v[74:77], v[230:233], v[6:9]
	v_mfma_f32_16x16x32_bf16 v[50:53], v[78:81], v[218:221], v[50:53]
	s_add_u32 m0, s4, 0xcc00
	v_mfma_f32_16x16x32_bf16 v[34:37], v[78:81], v[222:225], v[34:37]
	global_load_lds_dwordx4 v101, s[28:29]
	v_mfma_f32_16x16x32_bf16 v[18:21], v[78:81], v[226:229], v[18:21]
	v_mfma_f32_16x16x32_bf16 v[2:5], v[78:81], v[230:233], v[2:5]
	s_waitcnt lgkmcnt(0)
	v_mfma_f32_16x16x32_bf16 v[62:65], v[82:85], v[234:237], v[62:65]
	s_add_u32 m0, s4, 0x8000
	v_mfma_f32_16x16x32_bf16 v[46:49], v[82:85], v[238:241], v[46:49]
	global_load_lds_dwordx4 v98, s[48:49]
	v_mfma_f32_16x16x32_bf16 v[30:33], v[82:85], v[242:245], v[30:33]
	v_mfma_f32_16x16x32_bf16 v[14:17], v[82:85], v[246:249], v[14:17]
	v_mfma_f32_16x16x32_bf16 v[58:61], v[86:89], v[234:237], v[58:61]
	s_add_u32 m0, s4, 0x8400
	v_mfma_f32_16x16x32_bf16 v[42:45], v[86:89], v[238:241], v[42:45]
	global_load_lds_dwordx4 v99, s[48:49]
	v_mfma_f32_16x16x32_bf16 v[26:29], v[86:89], v[242:245], v[26:29]
	v_mfma_f32_16x16x32_bf16 v[10:13], v[86:89], v[246:249], v[10:13]
	v_mfma_f32_16x16x32_bf16 v[54:57], v[90:93], v[234:237], v[54:57]
	s_add_u32 m0, s4, 0x8800
	v_mfma_f32_16x16x32_bf16 v[38:41], v[90:93], v[238:241], v[38:41]
	global_load_lds_dwordx4 v100, s[48:49]
	v_mfma_f32_16x16x32_bf16 v[22:25], v[90:93], v[242:245], v[22:25]
	v_mfma_f32_16x16x32_bf16 v[6:9], v[90:93], v[246:249], v[6:9]
	v_mfma_f32_16x16x32_bf16 v[50:53], v[94:97], v[234:237], v[50:53]
	s_add_u32 m0, s4, 0x8c00
	v_mfma_f32_16x16x32_bf16 v[34:37], v[94:97], v[238:241], v[34:37]
	global_load_lds_dwordx4 v101, s[48:49]
	v_mfma_f32_16x16x32_bf16 v[18:21], v[94:97], v[242:245], v[18:21]
	v_mfma_f32_16x16x32_bf16 v[2:5], v[94:97], v[246:249], v[2:5]
	s_waitcnt vmcnt(8)
	s_barrier
	ds_read_b128 v[218:221], v102 offset:16384
	ds_read_b128 v[222:225], v102 offset:18432
	ds_read_b128 v[226:229], v102 offset:20480
	ds_read_b128 v[230:233], v102 offset:22528
	ds_read_b128 v[234:237], v103 offset:16384
	ds_read_b128 v[238:241], v103 offset:18432
	ds_read_b128 v[242:245], v103 offset:20480
	ds_read_b128 v[246:249], v103 offset:22528
	s_waitcnt lgkmcnt(4)
	v_mfma_f32_16x16x32_bf16 v[106:109], v[66:69], v[218:221], v[106:109]
	s_add_u32 m0, s4, 0x0
	v_mfma_f32_16x16x32_bf16 v[122:125], v[66:69], v[222:225], v[122:125]
	global_load_lds_dwordx4 v98, s[6:7]
	v_mfma_f32_16x16x32_bf16 v[138:141], v[66:69], v[226:229], v[138:141]
	v_mfma_f32_16x16x32_bf16 v[162:165], v[66:69], v[230:233], v[162:165]
	v_mfma_f32_16x16x32_bf16 v[110:113], v[70:73], v[218:221], v[110:113]
	s_add_u32 m0, s4, 0x400
	v_mfma_f32_16x16x32_bf16 v[126:129], v[70:73], v[222:225], v[126:129]
	global_load_lds_dwordx4 v99, s[6:7]
	v_mfma_f32_16x16x32_bf16 v[142:145], v[70:73], v[226:229], v[142:145]
	v_mfma_f32_16x16x32_bf16 v[166:169], v[70:73], v[230:233], v[166:169]
	v_mfma_f32_16x16x32_bf16 v[114:117], v[74:77], v[218:221], v[114:117]
	s_add_u32 m0, s4, 0x800
	v_mfma_f32_16x16x32_bf16 v[130:133], v[74:77], v[222:225], v[130:133]
	global_load_lds_dwordx4 v100, s[6:7]
	v_mfma_f32_16x16x32_bf16 v[154:157], v[74:77], v[226:229], v[154:157]
	v_mfma_f32_16x16x32_bf16 v[170:173], v[74:77], v[230:233], v[170:173]
	v_mfma_f32_16x16x32_bf16 v[118:121], v[78:81], v[218:221], v[118:121]
	s_add_u32 m0, s4, 0xc00
	v_mfma_f32_16x16x32_bf16 v[134:137], v[78:81], v[222:225], v[134:137]
	global_load_lds_dwordx4 v101, s[6:7]
	v_mfma_f32_16x16x32_bf16 v[158:161], v[78:81], v[226:229], v[158:161]
	v_mfma_f32_16x16x32_bf16 v[174:177], v[78:81], v[230:233], v[174:177]
	v_add_u32_e32 v98, 0x80, v98
	v_add_u32_e32 v99, 0x80, v99
	v_add_u32_e32 v100, 0x80, v100
	v_add_u32_e32 v101, 0x80, v101
	s_waitcnt lgkmcnt(0)
	v_mfma_f32_16x16x32_bf16 v[106:109], v[82:85], v[234:237], v[106:109]
	v_mfma_f32_16x16x32_bf16 v[122:125], v[82:85], v[238:241], v[122:125]
	v_mfma_f32_16x16x32_bf16 v[138:141], v[82:85], v[242:245], v[138:141]
	v_mfma_f32_16x16x32_bf16 v[162:165], v[82:85], v[246:249], v[162:165]
	v_mfma_f32_16x16x32_bf16 v[110:113], v[86:89], v[234:237], v[110:113]
	v_mfma_f32_16x16x32_bf16 v[126:129], v[86:89], v[238:241], v[126:129]
	v_mfma_f32_16x16x32_bf16 v[142:145], v[86:89], v[242:245], v[142:145]
	v_mfma_f32_16x16x32_bf16 v[166:169], v[86:89], v[246:249], v[166:169]
	v_mfma_f32_16x16x32_bf16 v[114:117], v[90:93], v[234:237], v[114:117]
	v_mfma_f32_16x16x32_bf16 v[130:133], v[90:93], v[238:241], v[130:133]
	v_mfma_f32_16x16x32_bf16 v[154:157], v[90:93], v[242:245], v[154:157]
	v_mfma_f32_16x16x32_bf16 v[170:173], v[90:93], v[246:249], v[170:173]
	v_mfma_f32_16x16x32_bf16 v[118:121], v[94:97], v[234:237], v[118:121]
	v_mfma_f32_16x16x32_bf16 v[134:137], v[94:97], v[238:241], v[134:137]
	v_mfma_f32_16x16x32_bf16 v[158:161], v[94:97], v[242:245], v[158:161]
	v_mfma_f32_16x16x32_bf16 v[174:177], v[94:97], v[246:249], v[174:177]
	s_waitcnt vmcnt(4)
	s_barrier
	ds_read_b128 v[218:221], v102 offset:49152
	ds_read_b128 v[222:225], v102 offset:51200
	ds_read_b128 v[226:229], v102 offset:53248
	ds_read_b128 v[230:233], v102 offset:55296
	ds_read_b128 v[66:69], v104 offset:32768
	ds_read_b128 v[70:73], v104 offset:34816
	ds_read_b128 v[74:77], v104 offset:36864
	ds_read_b128 v[78:81], v104 offset:38912
	ds_read_b128 v[234:237], v103 offset:49152
	ds_read_b128 v[238:241], v103 offset:51200
	ds_read_b128 v[242:245], v103 offset:53248
	ds_read_b128 v[246:249], v103 offset:55296
	ds_read_b128 v[82:85], v105 offset:32768
	ds_read_b128 v[86:89], v105 offset:34816
	ds_read_b128 v[90:93], v105 offset:36864
	ds_read_b128 v[94:97], v105 offset:38912
	s_waitcnt lgkmcnt(8)
	v_mfma_f32_16x16x32_bf16 v[62:65], v[66:69], v[218:221], v[62:65]
	v_mfma_f32_16x16x32_bf16 v[46:49], v[66:69], v[222:225], v[46:49]
	v_mfma_f32_16x16x32_bf16 v[30:33], v[66:69], v[226:229], v[30:33]
	v_mfma_f32_16x16x32_bf16 v[14:17], v[66:69], v[230:233], v[14:17]
	v_mfma_f32_16x16x32_bf16 v[58:61], v[70:73], v[218:221], v[58:61]
	v_mfma_f32_16x16x32_bf16 v[42:45], v[70:73], v[222:225], v[42:45]
	v_mfma_f32_16x16x32_bf16 v[26:29], v[70:73], v[226:229], v[26:29]
	v_mfma_f32_16x16x32_bf16 v[10:13], v[70:73], v[230:233], v[10:13]
	v_mfma_f32_16x16x32_bf16 v[54:57], v[74:77], v[218:221], v[54:57]
	v_mfma_f32_16x16x32_bf16 v[38:41], v[74:77], v[222:225], v[38:41]
	v_mfma_f32_16x16x32_bf16 v[22:25], v[74:77], v[226:229], v[22:25]
	v_mfma_f32_16x16x32_bf16 v[6:9], v[74:77], v[230:233], v[6:9]
	v_mfma_f32_16x16x32_bf16 v[50:53], v[78:81], v[218:221], v[50:53]
	v_mfma_f32_16x16x32_bf16 v[34:37], v[78:81], v[222:225], v[34:37]
	v_mfma_f32_16x16x32_bf16 v[18:21], v[78:81], v[226:229], v[18:21]
	v_mfma_f32_16x16x32_bf16 v[2:5], v[78:81], v[230:233], v[2:5]
	s_waitcnt lgkmcnt(0)
	v_mfma_f32_16x16x32_bf16 v[62:65], v[82:85], v[234:237], v[62:65]
	v_mfma_f32_16x16x32_bf16 v[46:49], v[82:85], v[238:241], v[46:49]
	v_mfma_f32_16x16x32_bf16 v[30:33], v[82:85], v[242:245], v[30:33]
	v_mfma_f32_16x16x32_bf16 v[14:17], v[82:85], v[246:249], v[14:17]
	v_mfma_f32_16x16x32_bf16 v[58:61], v[86:89], v[234:237], v[58:61]
	v_mfma_f32_16x16x32_bf16 v[42:45], v[86:89], v[238:241], v[42:45]
	v_mfma_f32_16x16x32_bf16 v[26:29], v[86:89], v[242:245], v[26:29]
	v_mfma_f32_16x16x32_bf16 v[10:13], v[86:89], v[246:249], v[10:13]
	v_mfma_f32_16x16x32_bf16 v[54:57], v[90:93], v[234:237], v[54:57]
	v_mfma_f32_16x16x32_bf16 v[38:41], v[90:93], v[238:241], v[38:41]
	v_mfma_f32_16x16x32_bf16 v[22:25], v[90:93], v[242:245], v[22:25]
	v_mfma_f32_16x16x32_bf16 v[6:9], v[90:93], v[246:249], v[6:9]
	v_mfma_f32_16x16x32_bf16 v[50:53], v[94:97], v[234:237], v[50:53]
	v_mfma_f32_16x16x32_bf16 v[34:37], v[94:97], v[238:241], v[34:37]
	v_mfma_f32_16x16x32_bf16 v[18:21], v[94:97], v[242:245], v[18:21]
	v_mfma_f32_16x16x32_bf16 v[2:5], v[94:97], v[246:249], v[2:5]
	s_waitcnt vmcnt(0)
	s_barrier
	ds_read_b128 v[218:221], v102 offset:0
	ds_read_b128 v[222:225], v102 offset:2048
	ds_read_b128 v[226:229], v102 offset:4096
	ds_read_b128 v[230:233], v102 offset:6144
	ds_read_b128 v[234:237], v103 offset:0
	ds_read_b128 v[238:241], v103 offset:2048
	ds_read_b128 v[242:245], v103 offset:4096
	ds_read_b128 v[246:249], v103 offset:6144
	s_waitcnt lgkmcnt(4)
	v_mfma_f32_16x16x32_bf16 v[106:109], v[66:69], v[218:221], v[106:109]
	v_mfma_f32_16x16x32_bf16 v[122:125], v[66:69], v[222:225], v[122:125]
	v_mfma_f32_16x16x32_bf16 v[138:141], v[66:69], v[226:229], v[138:141]
	v_mfma_f32_16x16x32_bf16 v[162:165], v[66:69], v[230:233], v[162:165]
	v_mfma_f32_16x16x32_bf16 v[110:113], v[70:73], v[218:221], v[110:113]
	v_mfma_f32_16x16x32_bf16 v[126:129], v[70:73], v[222:225], v[126:129]
	v_mfma_f32_16x16x32_bf16 v[142:145], v[70:73], v[226:229], v[142:145]
	v_mfma_f32_16x16x32_bf16 v[166:169], v[70:73], v[230:233], v[166:169]
	v_mfma_f32_16x16x32_bf16 v[114:117], v[74:77], v[218:221], v[114:117]
	v_mfma_f32_16x16x32_bf16 v[130:133], v[74:77], v[222:225], v[130:133]
	v_mfma_f32_16x16x32_bf16 v[154:157], v[74:77], v[226:229], v[154:157]
	v_mfma_f32_16x16x32_bf16 v[170:173], v[74:77], v[230:233], v[170:173]
	v_mfma_f32_16x16x32_bf16 v[118:121], v[78:81], v[218:221], v[118:121]
	v_mfma_f32_16x16x32_bf16 v[134:137], v[78:81], v[222:225], v[134:137]
	v_mfma_f32_16x16x32_bf16 v[158:161], v[78:81], v[226:229], v[158:161]
	v_mfma_f32_16x16x32_bf16 v[174:177], v[78:81], v[230:233], v[174:177]
	s_waitcnt lgkmcnt(0)
	v_mfma_f32_16x16x32_bf16 v[106:109], v[82:85], v[234:237], v[106:109]
	v_mfma_f32_16x16x32_bf16 v[122:125], v[82:85], v[238:241], v[122:125]
	v_mfma_f32_16x16x32_bf16 v[138:141], v[82:85], v[242:245], v[138:141]
	v_mfma_f32_16x16x32_bf16 v[162:165], v[82:85], v[246:249], v[162:165]
	v_mfma_f32_16x16x32_bf16 v[110:113], v[86:89], v[234:237], v[110:113]
	v_mfma_f32_16x16x32_bf16 v[126:129], v[86:89], v[238:241], v[126:129]
	v_mfma_f32_16x16x32_bf16 v[142:145], v[86:89], v[242:245], v[142:145]
	v_mfma_f32_16x16x32_bf16 v[166:169], v[86:89], v[246:249], v[166:169]
	v_mfma_f32_16x16x32_bf16 v[114:117], v[90:93], v[234:237], v[114:117]
	v_mfma_f32_16x16x32_bf16 v[130:133], v[90:93], v[238:241], v[130:133]
	v_mfma_f32_16x16x32_bf16 v[154:157], v[90:93], v[242:245], v[154:157]
	v_mfma_f32_16x16x32_bf16 v[170:173], v[90:93], v[246:249], v[170:173]
	v_mfma_f32_16x16x32_bf16 v[118:121], v[94:97], v[234:237], v[118:121]
	v_mfma_f32_16x16x32_bf16 v[134:137], v[94:97], v[238:241], v[134:137]
	v_mfma_f32_16x16x32_bf16 v[158:161], v[94:97], v[242:245], v[158:161]
	v_mfma_f32_16x16x32_bf16 v[174:177], v[94:97], v[246:249], v[174:177]
	s_nop 7
	s_barrier
	s_and_b32 s5, s100, 0xff
	s_cmp_lt_u32 s5, 4
	s_cbranch_scc0 .Lpk_sw_nopf
	s_add_i32 s5, s5, 1
	s_lshl_b32 s5, s5, 6
	v_readlane_b32 s6, v254, 7
	s_add_i32 s5, s5, s6
	s_mul_hi_u32 s6, s5, 0x924924a
	s_mul_i32 s7, s6, 28
	s_sub_u32 s5, s5, s7
	s_mul_hi_u32 s7, s5, 0x24924925
	s_mul_i32 s28, s7, 7
	s_sub_u32 s5, s5, s28
	s_and_b32 s28, s6, 3
	s_mul_i32 s28, s28, 7
	s_add_i32 s28, s28, s5
	s_lshl_b32 s48, s28, 18
	s_add_u32 s48, s12, s48
	s_addc_u32 s49, s13, 0
	s_lshr_b32 s6, s6, 2
	s_lshl_b32 s6, s6, 3
	v_readlane_b32 s5, v254, 6
	s_or_b32 s6, s6, s5
	s_lshl_b32 s6, s6, 3
	s_lshl_b32 s7, s7, 1
	s_add_i32 s6, s6, s7
	s_lshl_b32 s6, s6, 18
	s_add_u32 s28, s94, s6
	s_addc_u32 s29, s95, 0
	v_add_u32_e32 v98, 0xfffff800, v98
	v_add_u32_e32 v99, 0xfffff800, v99
	v_add_u32_e32 v100, 0xfffff800, v100
	v_add_u32_e32 v101, 0xfffff800, v101
	s_add_u32 m0, s4, 0xc000
	s_nop 0
	global_load_lds_dwordx4 v98, s[28:29]
	s_add_u32 m0, s4, 0xc400
	s_nop 0
	global_load_lds_dwordx4 v99, s[28:29]
	s_add_u32 m0, s4, 0xc800
	s_nop 0
	global_load_lds_dwordx4 v100, s[28:29]
	s_add_u32 m0, s4, 0xcc00
	s_nop 0
	global_load_lds_dwordx4 v101, s[28:29]
	s_add_u32 m0, s4, 0x10000
	s_nop 0
	global_load_lds_dwordx4 v98, s[48:49]
	s_add_u32 m0, s4, 0x10400
	s_nop 0
	global_load_lds_dwordx4 v99, s[48:49]
	s_add_u32 m0, s4, 0x10800
	s_nop 0
	global_load_lds_dwordx4 v100, s[48:49]
	s_add_u32 m0, s4, 0x10c00
	s_nop 0
	global_load_lds_dwordx4 v101, s[48:49]
	s_or_b32 s100, s100, 0x1000
	s_branch .Lpk_sw_end
.Lpk_sw_nopf:
	v_mov_b32_e32 v0, 0x13ff0
	s_and_b32 s5, s101, 0xffff
	s_lshr_b32 s6, s101, 16
	v_mov_b32_e32 v218, s5
	v_mov_b32_e32 v219, s6
	ds_write_b64 v0, v[218:219]
.Lpk_sw_end:
	s_mov_b64 s[84:85], 0
	s_branch .LBB0_208

.LBB0_255:
	s_and_b64 vcc, exec, s[84:85]
	s_cbranch_vccz .LBB0_196
	s_bfe_u32 s4, s100, 0x20008
	s_cmp_eq_u32 s4, 0
	s_cbranch_scc1 .Lpk_tt_orig
	s_cmp_eq_u32 s4, 2
	s_cbranch_scc1 .Lpk_tt_unpark
	v_lshrrev_b32_e32 v0, 6, v151
	v_and_b32_e32 v218, 63, v151
	s_nop 0
	v_readfirstlane_b32 s5, v0
	v_lshrrev_b32_e32 v219, 4, v218
	v_and_b32_e32 v220, 7, v218
	v_xor_b32_e32 v220, v220, v219
	v_lshlrev_b32_e32 v220, 4, v220
	v_lshrrev_b32_e32 v219, 3, v218
	v_lshl_or_b32 v98, v219, 11, v220
	s_lshl_b32 s4, s5, 16
	v_add_u32_e32 v98, s4, v98
	v_xor_b32_e32 v99, 64, v98
	v_add_u32_e32 v99, 0x4000, v99
	v_add_u32_e32 v100, 0x8000, v98
	v_add_u32_e32 v101, 0x8000, v99
	v_and_b32_e32 v219, 15, v218
	v_lshrrev_b32_e32 v220, 4, v218
	v_bfe_u32 v218, v219, 1, 3
	v_xor_b32_e32 v220, v220, v218
	v_lshlrev_b32_e32 v220, 4, v220
	v_lshl_or_b32 v220, v219, 7, v220
	s_lshr_b32 s4, s5, 1
	s_lshl_b32 s4, s4, 13
	v_add_u32_e32 v102, s4, v220
	v_xor_b32_e32 v103, 64, v102
	s_and_b32 s4, s5, 1
	s_lshl_b32 s4, s4, 13
	v_add_u32_e32 v104, s4, v220
	v_xor_b32_e32 v105, 64, v104
	v_add_u32_e32 v250, 0x4000, v104
	v_add_u32_e32 v251, 0x4000, v105
	s_lshl_b32 s4, s5, 12
	s_add_u32 s6, s28, 0x40000
	s_addc_u32 s7, s29, 0
	s_barrier
	s_and_b32 s5, s100, 0x1000
	s_cmp_lg_u32 s5, 0
	s_cbranch_scc1 .Lpk_tt_pf
	s_add_u32 m0, s4, 0xc000
	s_nop 0
	global_load_lds_dwordx4 v98, s[28:29]
	s_add_u32 m0, s4, 0xc400
	s_nop 0
	global_load_lds_dwordx4 v99, s[28:29]
	s_add_u32 m0, s4, 0xc800
	s_nop 0
	global_load_lds_dwordx4 v100, s[28:29]
	s_add_u32 m0, s4, 0xcc00
	s_nop 0
	global_load_lds_dwordx4 v101, s[28:29]
	s_add_u32 m0, s4, 0x10000
	s_nop 0
	global_load_lds_dwordx4 v98, s[48:49]
	s_add_u32 m0, s4, 0x10400
	s_nop 0
	global_load_lds_dwordx4 v99, s[48:49]
	s_add_u32 m0, s4, 0x10800
	s_nop 0
	global_load_lds_dwordx4 v100, s[48:49]
	s_add_u32 m0, s4, 0x10c00
	s_nop 0
	global_load_lds_dwordx4 v101, s[48:49]
.Lpk_tt_pf:
	s_and_b32 s100, s100, 0xffffefff
	s_add_u32 m0, s4, 0x0
	s_nop 0
	global_load_lds_dwordx4 v98, s[6:7]
	s_add_u32 m0, s4, 0x400
	s_nop 0
	global_load_lds_dwordx4 v99, s[6:7]
	s_add_u32 m0, s4, 0x800
	s_nop 0
	global_load_lds_dwordx4 v100, s[6:7]
	s_add_u32 m0, s4, 0xc00
	s_nop 0
	global_load_lds_dwordx4 v101, s[6:7]
	v_add_u32_e32 v98, 0x80, v98
	v_add_u32_e32 v99, 0x80, v99
	v_add_u32_e32 v100, 0x80, v100
	v_add_u32_e32 v101, 0x80, v101
	v_mov_b32_e32 v62, 0
	v_mov_b32_e32 v106, 0
	v_mov_b32_e32 v63, 0
	v_mov_b32_e32 v107, 0
	v_mov_b32_e32 v64, 0
	v_mov_b32_e32 v108, 0
	v_mov_b32_e32 v65, 0
	v_mov_b32_e32 v109, 0
	v_mov_b32_e32 v58, 0
	v_mov_b32_e32 v110, 0
	v_mov_b32_e32 v59, 0
	v_mov_b32_e32 v111, 0
	v_mov_b32_e32 v60, 0
	v_mov_b32_e32 v112, 0
	v_mov_b32_e32 v61, 0
	v_mov_b32_e32 v113, 0
	v_mov_b32_e32 v54, 0
	v_mov_b32_e32 v114, 0
	v_mov_b32_e32 v55, 0
	v_mov_b32_e32 v115, 0
	v_mov_b32_e32 v56, 0
	v_mov_b32_e32 v116, 0
	v_mov_b32_e32 v57, 0
	v_mov_b32_e32 v117, 0
	v_mov_b32_e32 v50, 0
	v_mov_b32_e32 v118, 0
	v_mov_b32_e32 v51, 0
	v_mov_b32_e32 v119, 0
	v_mov_b32_e32 v52, 0
	v_mov_b32_e32 v120, 0
	v_mov_b32_e32 v53, 0
	v_mov_b32_e32 v121, 0
	v_mov_b32_e32 v46, 0
	v_mov_b32_e32 v122, 0
	v_mov_b32_e32 v47, 0
	v_mov_b32_e32 v123, 0
	v_mov_b32_e32 v48, 0
	v_mov_b32_e32 v124, 0
	v_mov_b32_e32 v49, 0
	v_mov_b32_e32 v125, 0
	v_mov_b32_e32 v42, 0
	v_mov_b32_e32 v126, 0
	v_mov_b32_e32 v43, 0
	v_mov_b32_e32 v127, 0
	v_mov_b32_e32 v44, 0
	v_mov_b32_e32 v128, 0
	v_mov_b32_e32 v45, 0
	v_mov_b32_e32 v129, 0
	v_mov_b32_e32 v38, 0
	v_mov_b32_e32 v130, 0
	v_mov_b32_e32 v39, 0
	v_mov_b32_e32 v131, 0
	v_mov_b32_e32 v40, 0
	v_mov_b32_e32 v132, 0
	v_mov_b32_e32 v41, 0
	v_mov_b32_e32 v133, 0
	v_mov_b32_e32 v34, 0
	v_mov_b32_e32 v134, 0
	v_mov_b32_e32 v35, 0
	v_mov_b32_e32 v135, 0
	v_mov_b32_e32 v36, 0
	v_mov_b32_e32 v136, 0
	v_mov_b32_e32 v37, 0
	v_mov_b32_e32 v137, 0
	v_mov_b32_e32 v30, 0
	v_mov_b32_e32 v138, 0
	v_mov_b32_e32 v31, 0
	v_mov_b32_e32 v139, 0
	v_mov_b32_e32 v32, 0
	v_mov_b32_e32 v140, 0
	v_mov_b32_e32 v33, 0
	v_mov_b32_e32 v141, 0
	v_mov_b32_e32 v26, 0
	v_mov_b32_e32 v142, 0
	v_mov_b32_e32 v27, 0
	v_mov_b32_e32 v143, 0
	v_mov_b32_e32 v28, 0
	v_mov_b32_e32 v144, 0
	v_mov_b32_e32 v29, 0
	v_mov_b32_e32 v145, 0
	v_mov_b32_e32 v22, 0
	v_mov_b32_e32 v154, 0
	v_mov_b32_e32 v23, 0
	v_mov_b32_e32 v155, 0
	v_mov_b32_e32 v24, 0
	v_mov_b32_e32 v156, 0
	v_mov_b32_e32 v25, 0
	v_mov_b32_e32 v157, 0
	v_mov_b32_e32 v18, 0
	v_mov_b32_e32 v158, 0
	v_mov_b32_e32 v19, 0
	v_mov_b32_e32 v159, 0
	v_mov_b32_e32 v20, 0
	v_mov_b32_e32 v160, 0
	v_mov_b32_e32 v21, 0
	v_mov_b32_e32 v161, 0
	v_mov_b32_e32 v14, 0
	v_mov_b32_e32 v162, 0
	v_mov_b32_e32 v15, 0
	v_mov_b32_e32 v163, 0
	v_mov_b32_e32 v16, 0
	v_mov_b32_e32 v164, 0
	v_mov_b32_e32 v17, 0
	v_mov_b32_e32 v165, 0
	v_mov_b32_e32 v10, 0
	v_mov_b32_e32 v166, 0
	v_mov_b32_e32 v11, 0
	v_mov_b32_e32 v167, 0
	v_mov_b32_e32 v12, 0
	v_mov_b32_e32 v168, 0
	v_mov_b32_e32 v13, 0
	v_mov_b32_e32 v169, 0
	v_mov_b32_e32 v6, 0
	v_mov_b32_e32 v170, 0
	v_mov_b32_e32 v7, 0
	v_mov_b32_e32 v171, 0
	v_mov_b32_e32 v8, 0
	v_mov_b32_e32 v172, 0
	v_mov_b32_e32 v9, 0
	v_mov_b32_e32 v173, 0
	v_mov_b32_e32 v2, 0
	v_mov_b32_e32 v174, 0
	v_mov_b32_e32 v3, 0
	v_mov_b32_e32 v175, 0
	v_mov_b32_e32 v4, 0
	v_mov_b32_e32 v176, 0
	v_mov_b32_e32 v5, 0
	v_mov_b32_e32 v177, 0
	s_waitcnt vmcnt(4)
	s_barrier
	ds_read_b128 v[218:221], v102 offset:49152
	ds_read_b128 v[222:225], v102 offset:51200
	ds_read_b128 v[226:229], v102 offset:53248
	ds_read_b128 v[230:233], v102 offset:55296
	ds_read_b128 v[66:69], v250 offset:49152
	ds_read_b128 v[70:73], v250 offset:51200
	ds_read_b128 v[74:77], v250 offset:53248
	ds_read_b128 v[78:81], v250 offset:55296
	ds_read_b128 v[234:237], v103 offset:49152
	ds_read_b128 v[238:241], v103 offset:51200
	ds_read_b128 v[242:245], v103 offset:53248
	ds_read_b128 v[246:249], v103 offset:55296
	ds_read_b128 v[82:85], v251 offset:49152
	ds_read_b128 v[86:89], v251 offset:51200
	ds_read_b128 v[90:93], v251 offset:53248
	ds_read_b128 v[94:97], v251 offset:55296
	s_waitcnt lgkmcnt(8)
	v_mfma_f32_16x16x32_bf16 v[62:65], v[218:221], v[66:69], v[62:65]
	s_add_u32 m0, s4, 0x4000
	v_mfma_f32_16x16x32_bf16 v[46:49], v[222:225], v[66:69], v[46:49]
	global_load_lds_dwordx4 v98, s[28:29]
	v_mfma_f32_16x16x32_bf16 v[30:33], v[226:229], v[66:69], v[30:33]
	v_mfma_f32_16x16x32_bf16 v[14:17], v[230:233], v[66:69], v[14:17]
	v_mfma_f32_16x16x32_bf16 v[58:61], v[218:221], v[70:73], v[58:61]
	s_add_u32 m0, s4, 0x4400
	v_mfma_f32_16x16x32_bf16 v[42:45], v[222:225], v[70:73], v[42:45]
	global_load_lds_dwordx4 v99, s[28:29]
	v_mfma_f32_16x16x32_bf16 v[26:29], v[226:229], v[70:73], v[26:29]
	v_mfma_f32_16x16x32_bf16 v[10:13], v[230:233], v[70:73], v[10:13]
	v_mfma_f32_16x16x32_bf16 v[54:57], v[218:221], v[74:77], v[54:57]
	s_add_u32 m0, s4, 0x4800
	v_mfma_f32_16x16x32_bf16 v[38:41], v[222:225], v[74:77], v[38:41]
	global_load_lds_dwordx4 v100, s[28:29]
	v_mfma_f32_16x16x32_bf16 v[22:25], v[226:229], v[74:77], v[22:25]
	v_mfma_f32_16x16x32_bf16 v[6:9], v[230:233], v[74:77], v[6:9]
	v_mfma_f32_16x16x32_bf16 v[50:53], v[218:221], v[78:81], v[50:53]
	s_add_u32 m0, s4, 0x4c00
	v_mfma_f32_16x16x32_bf16 v[34:37], v[222:225], v[78:81], v[34:37]
	global_load_lds_dwordx4 v101, s[28:29]
	v_mfma_f32_16x16x32_bf16 v[18:21], v[226:229], v[78:81], v[18:21]
	v_mfma_f32_16x16x32_bf16 v[2:5], v[230:233], v[78:81], v[2:5]
	s_waitcnt lgkmcnt(0)
	v_mfma_f32_16x16x32_bf16 v[62:65], v[234:237], v[82:85], v[62:65]
	s_add_u32 m0, s4, 0x8000
	v_mfma_f32_16x16x32_bf16 v[46:49], v[238:241], v[82:85], v[46:49]
	global_load_lds_dwordx4 v98, s[48:49]
	v_mfma_f32_16x16x32_bf16 v[30:33], v[242:245], v[82:85], v[30:33]
	v_mfma_f32_16x16x32_bf16 v[14:17], v[246:249], v[82:85], v[14:17]
	v_mfma_f32_16x16x32_bf16 v[58:61], v[234:237], v[86:89], v[58:61]
	s_add_u32 m0, s4, 0x8400
	v_mfma_f32_16x16x32_bf16 v[42:45], v[238:241], v[86:89], v[42:45]
	global_load_lds_dwordx4 v99, s[48:49]
	v_mfma_f32_16x16x32_bf16 v[26:29], v[242:245], v[86:89], v[26:29]
	v_mfma_f32_16x16x32_bf16 v[10:13], v[246:249], v[86:89], v[10:13]
	v_mfma_f32_16x16x32_bf16 v[54:57], v[234:237], v[90:93], v[54:57]
	s_add_u32 m0, s4, 0x8800
	v_mfma_f32_16x16x32_bf16 v[38:41], v[238:241], v[90:93], v[38:41]
	global_load_lds_dwordx4 v100, s[48:49]
	v_mfma_f32_16x16x32_bf16 v[22:25], v[242:245], v[90:93], v[22:25]
	v_mfma_f32_16x16x32_bf16 v[6:9], v[246:249], v[90:93], v[6:9]
	v_mfma_f32_16x16x32_bf16 v[50:53], v[234:237], v[94:97], v[50:53]
	s_add_u32 m0, s4, 0x8c00
	v_mfma_f32_16x16x32_bf16 v[34:37], v[238:241], v[94:97], v[34:37]
	global_load_lds_dwordx4 v101, s[48:49]
	v_mfma_f32_16x16x32_bf16 v[18:21], v[242:245], v[94:97], v[18:21]
	v_mfma_f32_16x16x32_bf16 v[2:5], v[246:249], v[94:97], v[2:5]
	s_waitcnt vmcnt(8)
	s_barrier
	ds_read_b128 v[218:221], v102 offset:0
	ds_read_b128 v[222:225], v102 offset:2048
	ds_read_b128 v[226:229], v102 offset:4096
	ds_read_b128 v[230:233], v102 offset:6144
	ds_read_b128 v[234:237], v103 offset:0
	ds_read_b128 v[238:241], v103 offset:2048
	ds_read_b128 v[242:245], v103 offset:4096
	ds_read_b128 v[246:249], v103 offset:6144
	s_waitcnt lgkmcnt(4)
	v_mfma_f32_16x16x32_bf16 v[106:109], v[218:221], v[66:69], v[106:109]
	s_add_u32 m0, s4, 0xc000
	v_mfma_f32_16x16x32_bf16 v[122:125], v[222:225], v[66:69], v[122:125]
	global_load_lds_dwordx4 v98, s[6:7]
	v_mfma_f32_16x16x32_bf16 v[138:141], v[226:229], v[66:69], v[138:141]
	v_mfma_f32_16x16x32_bf16 v[162:165], v[230:233], v[66:69], v[162:165]
	v_mfma_f32_16x16x32_bf16 v[110:113], v[218:221], v[70:73], v[110:113]
	s_add_u32 m0, s4, 0xc400
	v_mfma_f32_16x16x32_bf16 v[126:129], v[222:225], v[70:73], v[126:129]
	global_load_lds_dwordx4 v99, s[6:7]
	v_mfma_f32_16x16x32_bf16 v[142:145], v[226:229], v[70:73], v[142:145]
	v_mfma_f32_16x16x32_bf16 v[166:169], v[230:233], v[70:73], v[166:169]
	v_mfma_f32_16x16x32_bf16 v[114:117], v[218:221], v[74:77], v[114:117]
	s_add_u32 m0, s4, 0xc800
	v_mfma_f32_16x16x32_bf16 v[130:133], v[222:225], v[74:77], v[130:133]
	global_load_lds_dwordx4 v100, s[6:7]
	v_mfma_f32_16x16x32_bf16 v[154:157], v[226:229], v[74:77], v[154:157]
	v_mfma_f32_16x16x32_bf16 v[170:173], v[230:233], v[74:77], v[170:173]
	v_mfma_f32_16x16x32_bf16 v[118:121], v[218:221], v[78:81], v[118:121]
	s_add_u32 m0, s4, 0xcc00
	v_mfma_f32_16x16x32_bf16 v[134:137], v[222:225], v[78:81], v[134:137]
	global_load_lds_dwordx4 v101, s[6:7]
	v_mfma_f32_16x16x32_bf16 v[158:161], v[226:229], v[78:81], v[158:161]
	v_mfma_f32_16x16x32_bf16 v[174:177], v[230:233], v[78:81], v[174:177]
	v_add_u32_e32 v98, 0x80, v98
	v_add_u32_e32 v99, 0x80, v99
	v_add_u32_e32 v100, 0x80, v100
	v_add_u32_e32 v101, 0x80, v101
	s_waitcnt lgkmcnt(0)
	v_mfma_f32_16x16x32_bf16 v[106:109], v[234:237], v[82:85], v[106:109]
	v_mfma_f32_16x16x32_bf16 v[122:125], v[238:241], v[82:85], v[122:125]
	v_mfma_f32_16x16x32_bf16 v[138:141], v[242:245], v[82:85], v[138:141]
	v_mfma_f32_16x16x32_bf16 v[162:165], v[246:249], v[82:85], v[162:165]
	v_mfma_f32_16x16x32_bf16 v[110:113], v[234:237], v[86:89], v[110:113]
	v_mfma_f32_16x16x32_bf16 v[126:129], v[238:241], v[86:89], v[126:129]
	v_mfma_f32_16x16x32_bf16 v[142:145], v[242:245], v[86:89], v[142:145]
	v_mfma_f32_16x16x32_bf16 v[166:169], v[246:249], v[86:89], v[166:169]
	v_mfma_f32_16x16x32_bf16 v[114:117], v[234:237], v[90:93], v[114:117]
	v_mfma_f32_16x16x32_bf16 v[130:133], v[238:241], v[90:93], v[130:133]
	v_mfma_f32_16x16x32_bf16 v[154:157], v[242:245], v[90:93], v[154:157]
	v_mfma_f32_16x16x32_bf16 v[170:173], v[246:249], v[90:93], v[170:173]
	v_mfma_f32_16x16x32_bf16 v[118:121], v[234:237], v[94:97], v[118:121]
	v_mfma_f32_16x16x32_bf16 v[134:137], v[238:241], v[94:97], v[134:137]
	v_mfma_f32_16x16x32_bf16 v[158:161], v[242:245], v[94:97], v[158:161]
	v_mfma_f32_16x16x32_bf16 v[174:177], v[246:249], v[94:97], v[174:177]
	s_waitcnt vmcnt(4)
	s_barrier
	ds_read_b128 v[218:221], v102 offset:16384
	ds_read_b128 v[222:225], v102 offset:18432
	ds_read_b128 v[226:229], v102 offset:20480
	ds_read_b128 v[230:233], v102 offset:22528
	ds_read_b128 v[66:69], v104 offset:32768
	ds_read_b128 v[70:73], v104 offset:34816
	ds_read_b128 v[74:77], v104 offset:36864
	ds_read_b128 v[78:81], v104 offset:38912
	ds_read_b128 v[234:237], v103 offset:16384
	ds_read_b128 v[238:241], v103 offset:18432
	ds_read_b128 v[242:245], v103 offset:20480
	ds_read_b128 v[246:249], v103 offset:22528
	ds_read_b128 v[82:85], v105 offset:32768
	ds_read_b128 v[86:89], v105 offset:34816
	ds_read_b128 v[90:93], v105 offset:36864
	ds_read_b128 v[94:97], v105 offset:38912
	s_waitcnt lgkmcnt(8)
	v_mfma_f32_16x16x32_bf16 v[62:65], v[218:221], v[66:69], v[62:65]
	s_add_u32 m0, s4, 0x0
	v_mfma_f32_16x16x32_bf16 v[46:49], v[222:225], v[66:69], v[46:49]
	global_load_lds_dwordx4 v98, s[28:29]
	v_mfma_f32_16x16x32_bf16 v[30:33], v[226:229], v[66:69], v[30:33]
	v_mfma_f32_16x16x32_bf16 v[14:17], v[230:233], v[66:69], v[14:17]
	v_mfma_f32_16x16x32_bf16 v[58:61], v[218:221], v[70:73], v[58:61]
	s_add_u32 m0, s4, 0x400
	v_mfma_f32_16x16x32_bf16 v[42:45], v[222:225], v[70:73], v[42:45]
	global_load_lds_dwordx4 v99, s[28:29]
	v_mfma_f32_16x16x32_bf16 v[26:29], v[226:229], v[70:73], v[26:29]
	v_mfma_f32_16x16x32_bf16 v[10:13], v[230:233], v[70:73], v[10:13]
	v_mfma_f32_16x16x32_bf16 v[54:57], v[218:221], v[74:77], v[54:57]
	s_add_u32 m0, s4, 0x800
	v_mfma_f32_16x16x32_bf16 v[38:41], v[222:225], v[74:77], v[38:41]
	global_load_lds_dwordx4 v100, s[28:29]
	v_mfma_f32_16x16x32_bf16 v[22:25], v[226:229], v[74:77], v[22:25]
	v_mfma_f32_16x16x32_bf16 v[6:9], v[230:233], v[74:77], v[6:9]
	v_mfma_f32_16x16x32_bf16 v[50:53], v[218:221], v[78:81], v[50:53]
	s_add_u32 m0, s4, 0xc00
	v_mfma_f32_16x16x32_bf16 v[34:37], v[222:225], v[78:81], v[34:37]
	global_load_lds_dwordx4 v101, s[28:29]
	v_mfma_f32_16x16x32_bf16 v[18:21], v[226:229], v[78:81], v[18:21]
	v_mfma_f32_16x16x32_bf16 v[2:5], v[230:233], v[78:81], v[2:5]
	s_waitcnt lgkmcnt(0)
	v_mfma_f32_16x16x32_bf16 v[62:65], v[234:237], v[82:85], v[62:65]
	s_add_u32 m0, s4, 0x10000
	v_mfma_f32_16x16x32_bf16 v[46:49], v[238:241], v[82:85], v[46:49]
	global_load_lds_dwordx4 v98, s[48:49]
	v_mfma_f32_16x16x32_bf16 v[30:33], v[242:245], v[82:85], v[30:33]
	v_mfma_f32_16x16x32_bf16 v[14:17], v[246:249], v[82:85], v[14:17]
	v_mfma_f32_16x16x32_bf16 v[58:61], v[234:237], v[86:89], v[58:61]
	s_add_u32 m0, s4, 0x10400
	v_mfma_f32_16x16x32_bf16 v[42:45], v[238:241], v[86:89], v[42:45]
	global_load_lds_dwordx4 v99, s[48:49]
	v_mfma_f32_16x16x32_bf16 v[26:29], v[242:245], v[86:89], v[26:29]
	v_mfma_f32_16x16x32_bf16 v[10:13], v[246:249], v[86:89], v[10:13]
	v_mfma_f32_16x16x32_bf16 v[54:57], v[234:237], v[90:93], v[54:57]
	s_add_u32 m0, s4, 0x10800
	v_mfma_f32_16x16x32_bf16 v[38:41], v[238:241], v[90:93], v[38:41]
	global_load_lds_dwordx4 v100, s[48:49]
	v_mfma_f32_16x16x32_bf16 v[22:25], v[242:245], v[90:93], v[22:25]
	v_mfma_f32_16x16x32_bf16 v[6:9], v[246:249], v[90:93], v[6:9]
	v_mfma_f32_16x16x32_bf16 v[50:53], v[234:237], v[94:97], v[50:53]
	s_add_u32 m0, s4, 0x10c00
	v_mfma_f32_16x16x32_bf16 v[34:37], v[238:241], v[94:97], v[34:37]
	global_load_lds_dwordx4 v101, s[48:49]
	v_mfma_f32_16x16x32_bf16 v[18:21], v[242:245], v[94:97], v[18:21]
	v_mfma_f32_16x16x32_bf16 v[2:5], v[246:249], v[94:97], v[2:5]
	s_waitcnt vmcnt(8)
	s_barrier
	ds_read_b128 v[218:221], v102 offset:49152
	ds_read_b128 v[222:225], v102 offset:51200
	ds_read_b128 v[226:229], v102 offset:53248
	ds_read_b128 v[230:233], v102 offset:55296
	ds_read_b128 v[234:237], v103 offset:49152
	ds_read_b128 v[238:241], v103 offset:51200
	ds_read_b128 v[242:245], v103 offset:53248
	ds_read_b128 v[246:249], v103 offset:55296
	s_waitcnt lgkmcnt(4)
	v_mfma_f32_16x16x32_bf16 v[106:109], v[218:221], v[66:69], v[106:109]
	s_add_u32 m0, s4, 0x4000
	v_mfma_f32_16x16x32_bf16 v[122:125], v[222:225], v[66:69], v[122:125]
	global_load_lds_dwordx4 v98, s[6:7]
	v_mfma_f32_16x16x32_bf16 v[138:141], v[226:229], v[66:69], v[138:141]
	v_mfma_f32_16x16x32_bf16 v[162:165], v[230:233], v[66:69], v[162:165]
	v_mfma_f32_16x16x32_bf16 v[110:113], v[218:221], v[70:73], v[110:113]
	s_add_u32 m0, s4, 0x4400
	v_mfma_f32_16x16x32_bf16 v[126:129], v[222:225], v[70:73], v[126:129]
	global_load_lds_dwordx4 v99, s[6:7]
	v_mfma_f32_16x16x32_bf16 v[142:145], v[226:229], v[70:73], v[142:145]
	v_mfma_f32_16x16x32_bf16 v[166:169], v[230:233], v[70:73], v[166:169]
	v_mfma_f32_16x16x32_bf16 v[114:117], v[218:221], v[74:77], v[114:117]
	s_add_u32 m0, s4, 0x4800
	v_mfma_f32_16x16x32_bf16 v[130:133], v[222:225], v[74:77], v[130:133]
	global_load_lds_dwordx4 v100, s[6:7]
	v_mfma_f32_16x16x32_bf16 v[154:157], v[226:229], v[74:77], v[154:157]
	v_mfma_f32_16x16x32_bf16 v[170:173], v[230:233], v[74:77], v[170:173]
	v_mfma_f32_16x16x32_bf16 v[118:121], v[218:221], v[78:81], v[118:121]
	s_add_u32 m0, s4, 0x4c00
	v_mfma_f32_16x16x32_bf16 v[134:137], v[222:225], v[78:81], v[134:137]
	global_load_lds_dwordx4 v101, s[6:7]
	v_mfma_f32_16x16x32_bf16 v[158:161], v[226:229], v[78:81], v[158:161]
	v_mfma_f32_16x16x32_bf16 v[174:177], v[230:233], v[78:81], v[174:177]
	v_add_u32_e32 v98, 0x80, v98
	v_add_u32_e32 v99, 0x80, v99
	v_add_u32_e32 v100, 0x80, v100
	v_add_u32_e32 v101, 0x80, v101
	s_waitcnt lgkmcnt(0)
	v_mfma_f32_16x16x32_bf16 v[106:109], v[234:237], v[82:85], v[106:109]
	v_mfma_f32_16x16x32_bf16 v[122:125], v[238:241], v[82:85], v[122:125]
	v_mfma_f32_16x16x32_bf16 v[138:141], v[242:245], v[82:85], v[138:141]
	v_mfma_f32_16x16x32_bf16 v[162:165], v[246:249], v[82:85], v[162:165]
	v_mfma_f32_16x16x32_bf16 v[110:113], v[234:237], v[86:89], v[110:113]
	v_mfma_f32_16x16x32_bf16 v[126:129], v[238:241], v[86:89], v[126:129]
	v_mfma_f32_16x16x32_bf16 v[142:145], v[242:245], v[86:89], v[142:145]
	v_mfma_f32_16x16x32_bf16 v[166:169], v[246:249], v[86:89], v[166:169]
	v_mfma_f32_16x16x32_bf16 v[114:117], v[234:237], v[90:93], v[114:117]
	v_mfma_f32_16x16x32_bf16 v[130:133], v[238:241], v[90:93], v[130:133]
	v_mfma_f32_16x16x32_bf16 v[154:157], v[242:245], v[90:93], v[154:157]
	v_mfma_f32_16x16x32_bf16 v[170:173], v[246:249], v[90:93], v[170:173]
	v_mfma_f32_16x16x32_bf16 v[118:121], v[234:237], v[94:97], v[118:121]
	v_mfma_f32_16x16x32_bf16 v[134:137], v[238:241], v[94:97], v[134:137]
	v_mfma_f32_16x16x32_bf16 v[158:161], v[242:245], v[94:97], v[158:161]
	v_mfma_f32_16x16x32_bf16 v[174:177], v[246:249], v[94:97], v[174:177]
	s_waitcnt vmcnt(4)
	s_barrier
	ds_read_b128 v[218:221], v102 offset:0
	ds_read_b128 v[222:225], v102 offset:2048
	ds_read_b128 v[226:229], v102 offset:4096
	ds_read_b128 v[230:233], v102 offset:6144
	ds_read_b128 v[66:69], v250 offset:49152
	ds_read_b128 v[70:73], v250 offset:51200
	ds_read_b128 v[74:77], v250 offset:53248
	ds_read_b128 v[78:81], v250 offset:55296
	ds_read_b128 v[234:237], v103 offset:0
	ds_read_b128 v[238:241], v103 offset:2048
	ds_read_b128 v[242:245], v103 offset:4096
	ds_read_b128 v[246:249], v103 offset:6144
	ds_read_b128 v[82:85], v251 offset:49152
	ds_read_b128 v[86:89], v251 offset:51200
	ds_read_b128 v[90:93], v251 offset:53248
	ds_read_b128 v[94:97], v251 offset:55296
	s_waitcnt lgkmcnt(8)
	v_mfma_f32_16x16x32_bf16 v[62:65], v[218:221], v[66:69], v[62:65]
	s_add_u32 m0, s4, 0xc000
	v_mfma_f32_16x16x32_bf16 v[46:49], v[222:225], v[66:69], v[46:49]
	global_load_lds_dwordx4 v98, s[28:29]
	v_mfma_f32_16x16x32_bf16 v[30:33], v[226:229], v[66:69], v[30:33]
	v_mfma_f32_16x16x32_bf16 v[14:17], v[230:233], v[66:69], v[14:17]
	v_mfma_f32_16x16x32_bf16 v[58:61], v[218:221], v[70:73], v[58:61]
	s_add_u32 m0, s4, 0xc400
	v_mfma_f32_16x16x32_bf16 v[42:45], v[222:225], v[70:73], v[42:45]
	global_load_lds_dwordx4 v99, s[28:29]
	v_mfma_f32_16x16x32_bf16 v[26:29], v[226:229], v[70:73], v[26:29]
	v_mfma_f32_16x16x32_bf16 v[10:13], v[230:233], v[70:73], v[10:13]
	v_mfma_f32_16x16x32_bf16 v[54:57], v[218:221], v[74:77], v[54:57]
	s_add_u32 m0, s4, 0xc800
	v_mfma_f32_16x16x32_bf16 v[38:41], v[222:225], v[74:77], v[38:41]
	global_load_lds_dwordx4 v100, s[28:29]
	v_mfma_f32_16x16x32_bf16 v[22:25], v[226:229], v[74:77], v[22:25]
	v_mfma_f32_16x16x32_bf16 v[6:9], v[230:233], v[74:77], v[6:9]
	v_mfma_f32_16x16x32_bf16 v[50:53], v[218:221], v[78:81], v[50:53]
	s_add_u32 m0, s4, 0xcc00
	v_mfma_f32_16x16x32_bf16 v[34:37], v[222:225], v[78:81], v[34:37]
	global_load_lds_dwordx4 v101, s[28:29]
	v_mfma_f32_16x16x32_bf16 v[18:21], v[226:229], v[78:81], v[18:21]
	v_mfma_f32_16x16x32_bf16 v[2:5], v[230:233], v[78:81], v[2:5]
	s_waitcnt lgkmcnt(0)
	v_mfma_f32_16x16x32_bf16 v[62:65], v[234:237], v[82:85], v[62:65]
	s_add_u32 m0, s4, 0x8000
	v_mfma_f32_16x16x32_bf16 v[46:49], v[238:241], v[82:85], v[46:49]
	global_load_lds_dwordx4 v98, s[48:49]
	v_mfma_f32_16x16x32_bf16 v[30:33], v[242:245], v[82:85], v[30:33]
	v_mfma_f32_16x16x32_bf16 v[14:17], v[246:249], v[82:85], v[14:17]
	v_mfma_f32_16x16x32_bf16 v[58:61], v[234:237], v[86:89], v[58:61]
	s_add_u32 m0, s4, 0x8400
	v_mfma_f32_16x16x32_bf16 v[42:45], v[238:241], v[86:89], v[42:45]
	global_load_lds_dwordx4 v99, s[48:49]
	v_mfma_f32_16x16x32_bf16 v[26:29], v[242:245], v[86:89], v[26:29]
	v_mfma_f32_16x16x32_bf16 v[10:13], v[246:249], v[86:89], v[10:13]
	v_mfma_f32_16x16x32_bf16 v[54:57], v[234:237], v[90:93], v[54:57]
	s_add_u32 m0, s4, 0x8800
	v_mfma_f32_16x16x32_bf16 v[38:41], v[238:241], v[90:93], v[38:41]
	global_load_lds_dwordx4 v100, s[48:49]
	v_mfma_f32_16x16x32_bf16 v[22:25], v[242:245], v[90:93], v[22:25]
	v_mfma_f32_16x16x32_bf16 v[6:9], v[246:249], v[90:93], v[6:9]
	v_mfma_f32_16x16x32_bf16 v[50:53], v[234:237], v[94:97], v[50:53]
	s_add_u32 m0, s4, 0x8c00
	v_mfma_f32_16x16x32_bf16 v[34:37], v[238:241], v[94:97], v[34:37]
	global_load_lds_dwordx4 v101, s[48:49]
	v_mfma_f32_16x16x32_bf16 v[18:21], v[242:245], v[94:97], v[18:21]
	v_mfma_f32_16x16x32_bf16 v[2:5], v[246:249], v[94:97], v[2:5]
	s_waitcnt vmcnt(8)
	s_barrier
	ds_read_b128 v[218:221], v102 offset:16384
	ds_read_b128 v[222:225], v102 offset:18432
	ds_read_b128 v[226:229], v102 offset:20480
	ds_read_b128 v[230:233], v102 offset:22528
	ds_read_b128 v[234:237], v103 offset:16384
	ds_read_b128 v[238:241], v103 offset:18432
	ds_read_b128 v[242:245], v103 offset:20480
	ds_read_b128 v[246:249], v103 offset:22528
	s_waitcnt lgkmcnt(4)
	v_mfma_f32_16x16x32_bf16 v[106:109], v[218:221], v[66:69], v[106:109]
	s_add_u32 m0, s4, 0x0
	v_mfma_f32_16x16x32_bf16 v[122:125], v[222:225], v[66:69], v[122:125]
	global_load_lds_dwordx4 v98, s[6:7]
	v_mfma_f32_16x16x32_bf16 v[138:141], v[226:229], v[66:69], v[138:141]
	v_mfma_f32_16x16x32_bf16 v[162:165], v[230:233], v[66:69], v[162:165]
	v_mfma_f32_16x16x32_bf16 v[110:113], v[218:221], v[70:73], v[110:113]
	s_add_u32 m0, s4, 0x400
	v_mfma_f32_16x16x32_bf16 v[126:129], v[222:225], v[70:73], v[126:129]
	global_load_lds_dwordx4 v99, s[6:7]
	v_mfma_f32_16x16x32_bf16 v[142:145], v[226:229], v[70:73], v[142:145]
	v_mfma_f32_16x16x32_bf16 v[166:169], v[230:233], v[70:73], v[166:169]
	v_mfma_f32_16x16x32_bf16 v[114:117], v[218:221], v[74:77], v[114:117]
	s_add_u32 m0, s4, 0x800
	v_mfma_f32_16x16x32_bf16 v[130:133], v[222:225], v[74:77], v[130:133]
	global_load_lds_dwordx4 v100, s[6:7]
	v_mfma_f32_16x16x32_bf16 v[154:157], v[226:229], v[74:77], v[154:157]
	v_mfma_f32_16x16x32_bf16 v[170:173], v[230:233], v[74:77], v[170:173]
	v_mfma_f32_16x16x32_bf16 v[118:121], v[218:221], v[78:81], v[118:121]
	s_add_u32 m0, s4, 0xc00
	v_mfma_f32_16x16x32_bf16 v[134:137], v[222:225], v[78:81], v[134:137]
	global_load_lds_dwordx4 v101, s[6:7]
	v_mfma_f32_16x16x32_bf16 v[158:161], v[226:229], v[78:81], v[158:161]
	v_mfma_f32_16x16x32_bf16 v[174:177], v[230:233], v[78:81], v[174:177]
	v_add_u32_e32 v98, 0x80, v98
	v_add_u32_e32 v99, 0x80, v99
	v_add_u32_e32 v100, 0x80, v100
	v_add_u32_e32 v101, 0x80, v101
	s_waitcnt lgkmcnt(0)
	v_mfma_f32_16x16x32_bf16 v[106:109], v[234:237], v[82:85], v[106:109]
	v_mfma_f32_16x16x32_bf16 v[122:125], v[238:241], v[82:85], v[122:125]
	v_mfma_f32_16x16x32_bf16 v[138:141], v[242:245], v[82:85], v[138:141]
	v_mfma_f32_16x16x32_bf16 v[162:165], v[246:249], v[82:85], v[162:165]
	v_mfma_f32_16x16x32_bf16 v[110:113], v[234:237], v[86:89], v[110:113]
	v_mfma_f32_16x16x32_bf16 v[126:129], v[238:241], v[86:89], v[126:129]
	v_mfma_f32_16x16x32_bf16 v[142:145], v[242:245], v[86:89], v[142:145]
	v_mfma_f32_16x16x32_bf16 v[166:169], v[246:249], v[86:89], v[166:169]
	v_mfma_f32_16x16x32_bf16 v[114:117], v[234:237], v[90:93], v[114:117]
	v_mfma_f32_16x16x32_bf16 v[130:133], v[238:241], v[90:93], v[130:133]
	v_mfma_f32_16x16x32_bf16 v[154:157], v[242:245], v[90:93], v[154:157]
	v_mfma_f32_16x16x32_bf16 v[170:173], v[246:249], v[90:93], v[170:173]
	v_mfma_f32_16x16x32_bf16 v[118:121], v[234:237], v[94:97], v[118:121]
	v_mfma_f32_16x16x32_bf16 v[134:137], v[238:241], v[94:97], v[134:137]
	v_mfma_f32_16x16x32_bf16 v[158:161], v[242:245], v[94:97], v[158:161]
	v_mfma_f32_16x16x32_bf16 v[174:177], v[246:249], v[94:97], v[174:177]
	s_waitcnt vmcnt(4)
	s_barrier
	ds_read_b128 v[218:221], v102 offset:49152
	ds_read_b128 v[222:225], v102 offset:51200
	ds_read_b128 v[226:229], v102 offset:53248
	ds_read_b128 v[230:233], v102 offset:55296
	ds_read_b128 v[66:69], v104 offset:32768
	ds_read_b128 v[70:73], v104 offset:34816
	ds_read_b128 v[74:77], v104 offset:36864
	ds_read_b128 v[78:81], v104 offset:38912
	ds_read_b128 v[234:237], v103 offset:49152
	ds_read_b128 v[238:241], v103 offset:51200
	ds_read_b128 v[242:245], v103 offset:53248
	ds_read_b128 v[246:249], v103 offset:55296
	ds_read_b128 v[82:85], v105 offset:32768
	ds_read_b128 v[86:89], v105 offset:34816
	ds_read_b128 v[90:93], v105 offset:36864
	ds_read_b128 v[94:97], v105 offset:38912
	s_waitcnt lgkmcnt(8)
	v_mfma_f32_16x16x32_bf16 v[62:65], v[218:221], v[66:69], v[62:65]
	s_add_u32 m0, s4, 0x4000
	v_mfma_f32_16x16x32_bf16 v[46:49], v[222:225], v[66:69], v[46:49]
	global_load_lds_dwordx4 v98, s[28:29]
	v_mfma_f32_16x16x32_bf16 v[30:33], v[226:229], v[66:69], v[30:33]
	v_mfma_f32_16x16x32_bf16 v[14:17], v[230:233], v[66:69], v[14:17]
	v_mfma_f32_16x16x32_bf16 v[58:61], v[218:221], v[70:73], v[58:61]
	s_add_u32 m0, s4, 0x4400
	v_mfma_f32_16x16x32_bf16 v[42:45], v[222:225], v[70:73], v[42:45]
	global_load_lds_dwordx4 v99, s[28:29]
	v_mfma_f32_16x16x32_bf16 v[26:29], v[226:229], v[70:73], v[26:29]
	v_mfma_f32_16x16x32_bf16 v[10:13], v[230:233], v[70:73], v[10:13]
	v_mfma_f32_16x16x32_bf16 v[54:57], v[218:221], v[74:77], v[54:57]
	s_add_u32 m0, s4, 0x4800
	v_mfma_f32_16x16x32_bf16 v[38:41], v[222:225], v[74:77], v[38:41]
	global_load_lds_dwordx4 v100, s[28:29]
	v_mfma_f32_16x16x32_bf16 v[22:25], v[226:229], v[74:77], v[22:25]
	v_mfma_f32_16x16x32_bf16 v[6:9], v[230:233], v[74:77], v[6:9]
	v_mfma_f32_16x16x32_bf16 v[50:53], v[218:221], v[78:81], v[50:53]
	s_add_u32 m0, s4, 0x4c00
	v_mfma_f32_16x16x32_bf16 v[34:37], v[222:225], v[78:81], v[34:37]
	global_load_lds_dwordx4 v101, s[28:29]
	v_mfma_f32_16x16x32_bf16 v[18:21], v[226:229], v[78:81], v[18:21]
	v_mfma_f32_16x16x32_bf16 v[2:5], v[230:233], v[78:81], v[2:5]
	s_waitcnt lgkmcnt(0)
	v_mfma_f32_16x16x32_bf16 v[62:65], v[234:237], v[82:85], v[62:65]
	s_add_u32 m0, s4, 0x10000
	v_mfma_f32_16x16x32_bf16 v[46:49], v[238:241], v[82:85], v[46:49]
	global_load_lds_dwordx4 v98, s[48:49]
	v_mfma_f32_16x16x32_bf16 v[30:33], v[242:245], v[82:85], v[30:33]
	v_mfma_f32_16x16x32_bf16 v[14:17], v[246:249], v[82:85], v[14:17]
	v_mfma_f32_16x16x32_bf16 v[58:61], v[234:237], v[86:89], v[58:61]
	s_add_u32 m0, s4, 0x10400
	v_mfma_f32_16x16x32_bf16 v[42:45], v[238:241], v[86:89], v[42:45]
	global_load_lds_dwordx4 v99, s[48:49]
	v_mfma_f32_16x16x32_bf16 v[26:29], v[242:245], v[86:89], v[26:29]
	v_mfma_f32_16x16x32_bf16 v[10:13], v[246:249], v[86:89], v[10:13]
	v_mfma_f32_16x16x32_bf16 v[54:57], v[234:237], v[90:93], v[54:57]
	s_add_u32 m0, s4, 0x10800
	v_mfma_f32_16x16x32_bf16 v[38:41], v[238:241], v[90:93], v[38:41]
	global_load_lds_dwordx4 v100, s[48:49]
	v_mfma_f32_16x16x32_bf16 v[22:25], v[242:245], v[90:93], v[22:25]
	v_mfma_f32_16x16x32_bf16 v[6:9], v[246:249], v[90:93], v[6:9]
	v_mfma_f32_16x16x32_bf16 v[50:53], v[234:237], v[94:97], v[50:53]
	s_add_u32 m0, s4, 0x10c00
	v_mfma_f32_16x16x32_bf16 v[34:37], v[238:241], v[94:97], v[34:37]
	global_load_lds_dwordx4 v101, s[48:49]
	v_mfma_f32_16x16x32_bf16 v[18:21], v[242:245], v[94:97], v[18:21]
	v_mfma_f32_16x16x32_bf16 v[2:5], v[246:249], v[94:97], v[2:5]
	s_waitcnt vmcnt(8)
	s_barrier
	ds_read_b128 v[218:221], v102 offset:0
	ds_read_b128 v[222:225], v102 offset:2048
	ds_read_b128 v[226:229], v102 offset:4096
	ds_read_b128 v[230:233], v102 offset:6144
	ds_read_b128 v[234:237], v103 offset:0
	ds_read_b128 v[238:241], v103 offset:2048
	ds_read_b128 v[242:245], v103 offset:4096
	ds_read_b128 v[246:249], v103 offset:6144
	s_waitcnt lgkmcnt(4)
	v_mfma_f32_16x16x32_bf16 v[106:109], v[218:221], v[66:69], v[106:109]
	s_add_u32 m0, s4, 0xc000
	v_mfma_f32_16x16x32_bf16 v[122:125], v[222:225], v[66:69], v[122:125]
	global_load_lds_dwordx4 v98, s[6:7]
	v_mfma_f32_16x16x32_bf16 v[138:141], v[226:229], v[66:69], v[138:141]
	v_mfma_f32_16x16x32_bf16 v[162:165], v[230:233], v[66:69], v[162:165]
	v_mfma_f32_16x16x32_bf16 v[110:113], v[218:221], v[70:73], v[110:113]
	s_add_u32 m0, s4, 0xc400
	v_mfma_f32_16x16x32_bf16 v[126:129], v[222:225], v[70:73], v[126:129]
	global_load_lds_dwordx4 v99, s[6:7]
	v_mfma_f32_16x16x32_bf16 v[142:145], v[226:229], v[70:73], v[142:145]
	v_mfma_f32_16x16x32_bf16 v[166:169], v[230:233], v[70:73], v[166:169]
	v_mfma_f32_16x16x32_bf16 v[114:117], v[218:221], v[74:77], v[114:117]
	s_add_u32 m0, s4, 0xc800
	v_mfma_f32_16x16x32_bf16 v[130:133], v[222:225], v[74:77], v[130:133]
	global_load_lds_dwordx4 v100, s[6:7]
	v_mfma_f32_16x16x32_bf16 v[154:157], v[226:229], v[74:77], v[154:157]
	v_mfma_f32_16x16x32_bf16 v[170:173], v[230:233], v[74:77], v[170:173]
	v_mfma_f32_16x16x32_bf16 v[118:121], v[218:221], v[78:81], v[118:121]
	s_add_u32 m0, s4, 0xcc00
	v_mfma_f32_16x16x32_bf16 v[134:137], v[222:225], v[78:81], v[134:137]
	global_load_lds_dwordx4 v101, s[6:7]
	v_mfma_f32_16x16x32_bf16 v[158:161], v[226:229], v[78:81], v[158:161]
	v_mfma_f32_16x16x32_bf16 v[174:177], v[230:233], v[78:81], v[174:177]
	v_add_u32_e32 v98, 0x80, v98
	v_add_u32_e32 v99, 0x80, v99
	v_add_u32_e32 v100, 0x80, v100
	v_add_u32_e32 v101, 0x80, v101
	s_waitcnt lgkmcnt(0)
	v_mfma_f32_16x16x32_bf16 v[106:109], v[234:237], v[82:85], v[106:109]
	v_mfma_f32_16x16x32_bf16 v[122:125], v[238:241], v[82:85], v[122:125]
	v_mfma_f32_16x16x32_bf16 v[138:141], v[242:245], v[82:85], v[138:141]
	v_mfma_f32_16x16x32_bf16 v[162:165], v[246:249], v[82:85], v[162:165]
	v_mfma_f32_16x16x32_bf16 v[110:113], v[234:237], v[86:89], v[110:113]
	v_mfma_f32_16x16x32_bf16 v[126:129], v[238:241], v[86:89], v[126:129]
	v_mfma_f32_16x16x32_bf16 v[142:145], v[242:245], v[86:89], v[142:145]
	v_mfma_f32_16x16x32_bf16 v[166:169], v[246:249], v[86:89], v[166:169]
	v_mfma_f32_16x16x32_bf16 v[114:117], v[234:237], v[90:93], v[114:117]
	v_mfma_f32_16x16x32_bf16 v[130:133], v[238:241], v[90:93], v[130:133]
	v_mfma_f32_16x16x32_bf16 v[154:157], v[242:245], v[90:93], v[154:157]
	v_mfma_f32_16x16x32_bf16 v[170:173], v[246:249], v[90:93], v[170:173]
	v_mfma_f32_16x16x32_bf16 v[118:121], v[234:237], v[94:97], v[118:121]
	v_mfma_f32_16x16x32_bf16 v[134:137], v[238:241], v[94:97], v[134:137]
	v_mfma_f32_16x16x32_bf16 v[158:161], v[242:245], v[94:97], v[158:161]
	v_mfma_f32_16x16x32_bf16 v[174:177], v[246:249], v[94:97], v[174:177]
	s_waitcnt vmcnt(4)
	s_barrier
	ds_read_b128 v[218:221], v102 offset:16384
	ds_read_b128 v[222:225], v102 offset:18432
	ds_read_b128 v[226:229], v102 offset:20480
	ds_read_b128 v[230:233], v102 offset:22528
	ds_read_b128 v[66:69], v250 offset:49152
	ds_read_b128 v[70:73], v250 offset:51200
	ds_read_b128 v[74:77], v250 offset:53248
	ds_read_b128 v[78:81], v250 offset:55296
	ds_read_b128 v[234:237], v103 offset:16384
	ds_read_b128 v[238:241], v103 offset:18432
	ds_read_b128 v[242:245], v103 offset:20480
	ds_read_b128 v[246:249], v103 offset:22528
	ds_read_b128 v[82:85], v251 offset:49152
	ds_read_b128 v[86:89], v251 offset:51200
	ds_read_b128 v[90:93], v251 offset:53248
	ds_read_b128 v[94:97], v251 offset:55296
	s_waitcnt lgkmcnt(8)
	v_mfma_f32_16x16x32_bf16 v[62:65], v[218:221], v[66:69], v[62:65]
	s_add_u32 m0, s4, 0x0
	v_mfma_f32_16x16x32_bf16 v[46:49], v[222:225], v[66:69], v[46:49]
	global_load_lds_dwordx4 v98, s[28:29]
	v_mfma_f32_16x16x32_bf16 v[30:33], v[226:229], v[66:69], v[30:33]
	v_mfma_f32_16x16x32_bf16 v[14:17], v[230:233], v[66:69], v[14:17]
	v_mfma_f32_16x16x32_bf16 v[58:61], v[218:221], v[70:73], v[58:61]
	s_add_u32 m0, s4, 0x400
	v_mfma_f32_16x16x32_bf16 v[42:45], v[222:225], v[70:73], v[42:45]
	global_load_lds_dwordx4 v99, s[28:29]
	v_mfma_f32_16x16x32_bf16 v[26:29], v[226:229], v[70:73], v[26:29]
	v_mfma_f32_16x16x32_bf16 v[10:13], v[230:233], v[70:73], v[10:13]
	v_mfma_f32_16x16x32_bf16 v[54:57], v[218:221], v[74:77], v[54:57]
	s_add_u32 m0, s4, 0x800
	v_mfma_f32_16x16x32_bf16 v[38:41], v[222:225], v[74:77], v[38:41]
	global_load_lds_dwordx4 v100, s[28:29]
	v_mfma_f32_16x16x32_bf16 v[22:25], v[226:229], v[74:77], v[22:25]
	v_mfma_f32_16x16x32_bf16 v[6:9], v[230:233], v[74:77], v[6:9]
	v_mfma_f32_16x16x32_bf16 v[50:53], v[218:221], v[78:81], v[50:53]
	s_add_u32 m0, s4, 0xc00
	v_mfma_f32_16x16x32_bf16 v[34:37], v[222:225], v[78:81], v[34:37]
	global_load_lds_dwordx4 v101, s[28:29]
	v_mfma_f32_16x16x32_bf16 v[18:21], v[226:229], v[78:81], v[18:21]
	v_mfma_f32_16x16x32_bf16 v[2:5], v[230:233], v[78:81], v[2:5]
	s_waitcnt lgkmcnt(0)
	v_mfma_f32_16x16x32_bf16 v[62:65], v[234:237], v[82:85], v[62:65]
	s_add_u32 m0, s4, 0x8000
	v_mfma_f32_16x16x32_bf16 v[46:49], v[238:241], v[82:85], v[46:49]
	global_load_lds_dwordx4 v98, s[48:49]
	v_mfma_f32_16x16x32_bf16 v[30:33], v[242:245], v[82:85], v[30:33]
	v_mfma_f32_16x16x32_bf16 v[14:17], v[246:249], v[82:85], v[14:17]
	v_mfma_f32_16x16x32_bf16 v[58:61], v[234:237], v[86:89], v[58:61]
	s_add_u32 m0, s4, 0x8400
	v_mfma_f32_16x16x32_bf16 v[42:45], v[238:241], v[86:89], v[42:45]
	global_load_lds_dwordx4 v99, s[48:49]
	v_mfma_f32_16x16x32_bf16 v[26:29], v[242:245], v[86:89], v[26:29]
	v_mfma_f32_16x16x32_bf16 v[10:13], v[246:249], v[86:89], v[10:13]
	v_mfma_f32_16x16x32_bf16 v[54:57], v[234:237], v[90:93], v[54:57]
	s_add_u32 m0, s4, 0x8800
	v_mfma_f32_16x16x32_bf16 v[38:41], v[238:241], v[90:93], v[38:41]
	global_load_lds_dwordx4 v100, s[48:49]
	v_mfma_f32_16x16x32_bf16 v[22:25], v[242:245], v[90:93], v[22:25]
	v_mfma_f32_16x16x32_bf16 v[6:9], v[246:249], v[90:93], v[6:9]
	v_mfma_f32_16x16x32_bf16 v[50:53], v[234:237], v[94:97], v[50:53]
	s_add_u32 m0, s4, 0x8c00
	v_mfma_f32_16x16x32_bf16 v[34:37], v[238:241], v[94:97], v[34:37]
	global_load_lds_dwordx4 v101, s[48:49]
	v_mfma_f32_16x16x32_bf16 v[18:21], v[242:245], v[94:97], v[18:21]
	v_mfma_f32_16x16x32_bf16 v[2:5], v[246:249], v[94:97], v[2:5]
	s_waitcnt vmcnt(8)
	s_barrier
	ds_read_b128 v[218:221], v102 offset:49152
	ds_read_b128 v[222:225], v102 offset:51200
	ds_read_b128 v[226:229], v102 offset:53248
	ds_read_b128 v[230:233], v102 offset:55296
	ds_read_b128 v[234:237], v103 offset:49152
	ds_read_b128 v[238:241], v103 offset:51200
	ds_read_b128 v[242:245], v103 offset:53248
	ds_read_b128 v[246:249], v103 offset:55296
	s_waitcnt lgkmcnt(4)
	v_mfma_f32_16x16x32_bf16 v[106:109], v[218:221], v[66:69], v[106:109]
	s_add_u32 m0, s4, 0x4000
	v_mfma_f32_16x16x32_bf16 v[122:125], v[222:225], v[66:69], v[122:125]
	global_load_lds_dwordx4 v98, s[6:7]
	v_mfma_f32_16x16x32_bf16 v[138:141], v[226:229], v[66:69], v[138:141]
	v_mfma_f32_16x16x32_bf16 v[162:165], v[230:233], v[66:69], v[162:165]
	v_mfma_f32_16x16x32_bf16 v[110:113], v[218:221], v[70:73], v[110:113]
	s_add_u32 m0, s4, 0x4400
	v_mfma_f32_16x16x32_bf16 v[126:129], v[222:225], v[70:73], v[126:129]
	global_load_lds_dwordx4 v99, s[6:7]
	v_mfma_f32_16x16x32_bf16 v[142:145], v[226:229], v[70:73], v[142:145]
	v_mfma_f32_16x16x32_bf16 v[166:169], v[230:233], v[70:73], v[166:169]
	v_mfma_f32_16x16x32_bf16 v[114:117], v[218:221], v[74:77], v[114:117]
	s_add_u32 m0, s4, 0x4800
	v_mfma_f32_16x16x32_bf16 v[130:133], v[222:225], v[74:77], v[130:133]
	global_load_lds_dwordx4 v100, s[6:7]
	v_mfma_f32_16x16x32_bf16 v[154:157], v[226:229], v[74:77], v[154:157]
	v_mfma_f32_16x16x32_bf16 v[170:173], v[230:233], v[74:77], v[170:173]
	v_mfma_f32_16x16x32_bf16 v[118:121], v[218:221], v[78:81], v[118:121]
	s_add_u32 m0, s4, 0x4c00
	v_mfma_f32_16x16x32_bf16 v[134:137], v[222:225], v[78:81], v[134:137]
	global_load_lds_dwordx4 v101, s[6:7]
	v_mfma_f32_16x16x32_bf16 v[158:161], v[226:229], v[78:81], v[158:161]
	v_mfma_f32_16x16x32_bf16 v[174:177], v[230:233], v[78:81], v[174:177]
	v_add_u32_e32 v98, 0x80, v98
	v_add_u32_e32 v99, 0x80, v99
	v_add_u32_e32 v100, 0x80, v100
	v_add_u32_e32 v101, 0x80, v101
	s_waitcnt lgkmcnt(0)
	v_mfma_f32_16x16x32_bf16 v[106:109], v[234:237], v[82:85], v[106:109]
	v_mfma_f32_16x16x32_bf16 v[122:125], v[238:241], v[82:85], v[122:125]
	v_mfma_f32_16x16x32_bf16 v[138:141], v[242:245], v[82:85], v[138:141]
	v_mfma_f32_16x16x32_bf16 v[162:165], v[246:249], v[82:85], v[162:165]
	v_mfma_f32_16x16x32_bf16 v[110:113], v[234:237], v[86:89], v[110:113]
	v_mfma_f32_16x16x32_bf16 v[126:129], v[238:241], v[86:89], v[126:129]
	v_mfma_f32_16x16x32_bf16 v[142:145], v[242:245], v[86:89], v[142:145]
	v_mfma_f32_16x16x32_bf16 v[166:169], v[246:249], v[86:89], v[166:169]
	v_mfma_f32_16x16x32_bf16 v[114:117], v[234:237], v[90:93], v[114:117]
	v_mfma_f32_16x16x32_bf16 v[130:133], v[238:241], v[90:93], v[130:133]
	v_mfma_f32_16x16x32_bf16 v[154:157], v[242:245], v[90:93], v[154:157]
	v_mfma_f32_16x16x32_bf16 v[170:173], v[246:249], v[90:93], v[170:173]
	v_mfma_f32_16x16x32_bf16 v[118:121], v[234:237], v[94:97], v[118:121]
	v_mfma_f32_16x16x32_bf16 v[134:137], v[238:241], v[94:97], v[134:137]
	v_mfma_f32_16x16x32_bf16 v[158:161], v[242:245], v[94:97], v[158:161]
	v_mfma_f32_16x16x32_bf16 v[174:177], v[246:249], v[94:97], v[174:177]
	s_waitcnt vmcnt(4)
	s_barrier
	ds_read_b128 v[218:221], v102 offset:0
	ds_read_b128 v[222:225], v102 offset:2048
	ds_read_b128 v[226:229], v102 offset:4096
	ds_read_b128 v[230:233], v102 offset:6144
	ds_read_b128 v[66:69], v104 offset:32768
	ds_read_b128 v[70:73], v104 offset:34816
	ds_read_b128 v[74:77], v104 offset:36864
	ds_read_b128 v[78:81], v104 offset:38912
	ds_read_b128 v[234:237], v103 offset:0
	ds_read_b128 v[238:241], v103 offset:2048
	ds_read_b128 v[242:245], v103 offset:4096
	ds_read_b128 v[246:249], v103 offset:6144
	ds_read_b128 v[82:85], v105 offset:32768
	ds_read_b128 v[86:89], v105 offset:34816
	ds_read_b128 v[90:93], v105 offset:36864
	ds_read_b128 v[94:97], v105 offset:38912
	s_waitcnt lgkmcnt(8)
	v_mfma_f32_16x16x32_bf16 v[62:65], v[218:221], v[66:69], v[62:65]
	s_add_u32 m0, s4, 0xc000
	v_mfma_f32_16x16x32_bf16 v[46:49], v[222:225], v[66:69], v[46:49]
	global_load_lds_dwordx4 v98, s[28:29]
	v_mfma_f32_16x16x32_bf16 v[30:33], v[226:229], v[66:69], v[30:33]
	v_mfma_f32_16x16x32_bf16 v[14:17], v[230:233], v[66:69], v[14:17]
	v_mfma_f32_16x16x32_bf16 v[58:61], v[218:221], v[70:73], v[58:61]
	s_add_u32 m0, s4, 0xc400
	v_mfma_f32_16x16x32_bf16 v[42:45], v[222:225], v[70:73], v[42:45]
	global_load_lds_dwordx4 v99, s[28:29]
	v_mfma_f32_16x16x32_bf16 v[26:29], v[226:229], v[70:73], v[26:29]
	v_mfma_f32_16x16x32_bf16 v[10:13], v[230:233], v[70:73], v[10:13]
	v_mfma_f32_16x16x32_bf16 v[54:57], v[218:221], v[74:77], v[54:57]
	s_add_u32 m0, s4, 0xc800
	v_mfma_f32_16x16x32_bf16 v[38:41], v[222:225], v[74:77], v[38:41]
	global_load_lds_dwordx4 v100, s[28:29]
	v_mfma_f32_16x16x32_bf16 v[22:25], v[226:229], v[74:77], v[22:25]
	v_mfma_f32_16x16x32_bf16 v[6:9], v[230:233], v[74:77], v[6:9]
	v_mfma_f32_16x16x32_bf16 v[50:53], v[218:221], v[78:81], v[50:53]
	s_add_u32 m0, s4, 0xcc00
	v_mfma_f32_16x16x32_bf16 v[34:37], v[222:225], v[78:81], v[34:37]
	global_load_lds_dwordx4 v101, s[28:29]
	v_mfma_f32_16x16x32_bf16 v[18:21], v[226:229], v[78:81], v[18:21]
	v_mfma_f32_16x16x32_bf16 v[2:5], v[230:233], v[78:81], v[2:5]
	s_waitcnt lgkmcnt(0)
	v_mfma_f32_16x16x32_bf16 v[62:65], v[234:237], v[82:85], v[62:65]
	s_add_u32 m0, s4, 0x10000
	v_mfma_f32_16x16x32_bf16 v[46:49], v[238:241], v[82:85], v[46:49]
	global_load_lds_dwordx4 v98, s[48:49]
	v_mfma_f32_16x16x32_bf16 v[30:33], v[242:245], v[82:85], v[30:33]
	v_mfma_f32_16x16x32_bf16 v[14:17], v[246:249], v[82:85], v[14:17]
	v_mfma_f32_16x16x32_bf16 v[58:61], v[234:237], v[86:89], v[58:61]
	s_add_u32 m0, s4, 0x10400
	v_mfma_f32_16x16x32_bf16 v[42:45], v[238:241], v[86:89], v[42:45]
	global_load_lds_dwordx4 v99, s[48:49]
	v_mfma_f32_16x16x32_bf16 v[26:29], v[242:245], v[86:89], v[26:29]
	v_mfma_f32_16x16x32_bf16 v[10:13], v[246:249], v[86:89], v[10:13]
	v_mfma_f32_16x16x32_bf16 v[54:57], v[234:237], v[90:93], v[54:57]
	s_add_u32 m0, s4, 0x10800
	v_mfma_f32_16x16x32_bf16 v[38:41], v[238:241], v[90:93], v[38:41]
	global_load_lds_dwordx4 v100, s[48:49]
	v_mfma_f32_16x16x32_bf16 v[22:25], v[242:245], v[90:93], v[22:25]
	v_mfma_f32_16x16x32_bf16 v[6:9], v[246:249], v[90:93], v[6:9]
	v_mfma_f32_16x16x32_bf16 v[50:53], v[234:237], v[94:97], v[50:53]
	s_add_u32 m0, s4, 0x10c00
	v_mfma_f32_16x16x32_bf16 v[34:37], v[238:241], v[94:97], v[34:37]
	global_load_lds_dwordx4 v101, s[48:49]
	v_mfma_f32_16x16x32_bf16 v[18:21], v[242:245], v[94:97], v[18:21]
	v_mfma_f32_16x16x32_bf16 v[2:5], v[246:249], v[94:97], v[2:5]
	s_waitcnt vmcnt(8)
	s_barrier
	ds_read_b128 v[218:221], v102 offset:16384
	ds_read_b128 v[222:225], v102 offset:18432
	ds_read_b128 v[226:229], v102 offset:20480
	ds_read_b128 v[230:233], v102 offset:22528
	ds_read_b128 v[234:237], v103 offset:16384
	ds_read_b128 v[238:241], v103 offset:18432
	ds_read_b128 v[242:245], v103 offset:20480
	ds_read_b128 v[246:249], v103 offset:22528
	s_waitcnt lgkmcnt(4)
	v_mfma_f32_16x16x32_bf16 v[106:109], v[218:221], v[66:69], v[106:109]
	s_add_u32 m0, s4, 0x0
	v_mfma_f32_16x16x32_bf16 v[122:125], v[222:225], v[66:69], v[122:125]
	global_load_lds_dwordx4 v98, s[6:7]
	v_mfma_f32_16x16x32_bf16 v[138:141], v[226:229], v[66:69], v[138:141]
	v_mfma_f32_16x16x32_bf16 v[162:165], v[230:233], v[66:69], v[162:165]
	v_mfma_f32_16x16x32_bf16 v[110:113], v[218:221], v[70:73], v[110:113]
	s_add_u32 m0, s4, 0x400
	v_mfma_f32_16x16x32_bf16 v[126:129], v[222:225], v[70:73], v[126:129]
	global_load_lds_dwordx4 v99, s[6:7]
	v_mfma_f32_16x16x32_bf16 v[142:145], v[226:229], v[70:73], v[142:145]
	v_mfma_f32_16x16x32_bf16 v[166:169], v[230:233], v[70:73], v[166:169]
	v_mfma_f32_16x16x32_bf16 v[114:117], v[218:221], v[74:77], v[114:117]
	s_add_u32 m0, s4, 0x800
	v_mfma_f32_16x16x32_bf16 v[130:133], v[222:225], v[74:77], v[130:133]
	global_load_lds_dwordx4 v100, s[6:7]
	v_mfma_f32_16x16x32_bf16 v[154:157], v[226:229], v[74:77], v[154:157]
	v_mfma_f32_16x16x32_bf16 v[170:173], v[230:233], v[74:77], v[170:173]
	v_mfma_f32_16x16x32_bf16 v[118:121], v[218:221], v[78:81], v[118:121]
	s_add_u32 m0, s4, 0xc00
	v_mfma_f32_16x16x32_bf16 v[134:137], v[222:225], v[78:81], v[134:137]
	global_load_lds_dwordx4 v101, s[6:7]
	v_mfma_f32_16x16x32_bf16 v[158:161], v[226:229], v[78:81], v[158:161]
	v_mfma_f32_16x16x32_bf16 v[174:177], v[230:233], v[78:81], v[174:177]
	v_add_u32_e32 v98, 0x80, v98
	v_add_u32_e32 v99, 0x80, v99
	v_add_u32_e32 v100, 0x80, v100
	v_add_u32_e32 v101, 0x80, v101
	s_waitcnt lgkmcnt(0)
	v_mfma_f32_16x16x32_bf16 v[106:109], v[234:237], v[82:85], v[106:109]
	v_mfma_f32_16x16x32_bf16 v[122:125], v[238:241], v[82:85], v[122:125]
	v_mfma_f32_16x16x32_bf16 v[138:141], v[242:245], v[82:85], v[138:141]
	v_mfma_f32_16x16x32_bf16 v[162:165], v[246:249], v[82:85], v[162:165]
	v_mfma_f32_16x16x32_bf16 v[110:113], v[234:237], v[86:89], v[110:113]
	v_mfma_f32_16x16x32_bf16 v[126:129], v[238:241], v[86:89], v[126:129]
	v_mfma_f32_16x16x32_bf16 v[142:145], v[242:245], v[86:89], v[142:145]
	v_mfma_f32_16x16x32_bf16 v[166:169], v[246:249], v[86:89], v[166:169]
	v_mfma_f32_16x16x32_bf16 v[114:117], v[234:237], v[90:93], v[114:117]
	v_mfma_f32_16x16x32_bf16 v[130:133], v[238:241], v[90:93], v[130:133]
	v_mfma_f32_16x16x32_bf16 v[154:157], v[242:245], v[90:93], v[154:157]
	v_mfma_f32_16x16x32_bf16 v[170:173], v[246:249], v[90:93], v[170:173]
	v_mfma_f32_16x16x32_bf16 v[118:121], v[234:237], v[94:97], v[118:121]
	v_mfma_f32_16x16x32_bf16 v[134:137], v[238:241], v[94:97], v[134:137]
	v_mfma_f32_16x16x32_bf16 v[158:161], v[242:245], v[94:97], v[158:161]
	v_mfma_f32_16x16x32_bf16 v[174:177], v[246:249], v[94:97], v[174:177]
	s_waitcnt vmcnt(4)
	s_barrier
	ds_read_b128 v[218:221], v102 offset:49152
	ds_read_b128 v[222:225], v102 offset:51200
	ds_read_b128 v[226:229], v102 offset:53248
	ds_read_b128 v[230:233], v102 offset:55296
	ds_read_b128 v[66:69], v250 offset:49152
	ds_read_b128 v[70:73], v250 offset:51200
	ds_read_b128 v[74:77], v250 offset:53248
	ds_read_b128 v[78:81], v250 offset:55296
	ds_read_b128 v[234:237], v103 offset:49152
	ds_read_b128 v[238:241], v103 offset:51200
	ds_read_b128 v[242:245], v103 offset:53248
	ds_read_b128 v[246:249], v103 offset:55296
	ds_read_b128 v[82:85], v251 offset:49152
	ds_read_b128 v[86:89], v251 offset:51200
	ds_read_b128 v[90:93], v251 offset:53248
	ds_read_b128 v[94:97], v251 offset:55296
	s_waitcnt lgkmcnt(8)
	v_mfma_f32_16x16x32_bf16 v[62:65], v[218:221], v[66:69], v[62:65]
	s_add_u32 m0, s4, 0x4000
	v_mfma_f32_16x16x32_bf16 v[46:49], v[222:225], v[66:69], v[46:49]
	global_load_lds_dwordx4 v98, s[28:29]
	v_mfma_f32_16x16x32_bf16 v[30:33], v[226:229], v[66:69], v[30:33]
	v_mfma_f32_16x16x32_bf16 v[14:17], v[230:233], v[66:69], v[14:17]
	v_mfma_f32_16x16x32_bf16 v[58:61], v[218:221], v[70:73], v[58:61]
	s_add_u32 m0, s4, 0x4400
	v_mfma_f32_16x16x32_bf16 v[42:45], v[222:225], v[70:73], v[42:45]
	global_load_lds_dwordx4 v99, s[28:29]
	v_mfma_f32_16x16x32_bf16 v[26:29], v[226:229], v[70:73], v[26:29]
	v_mfma_f32_16x16x32_bf16 v[10:13], v[230:233], v[70:73], v[10:13]
	v_mfma_f32_16x16x32_bf16 v[54:57], v[218:221], v[74:77], v[54:57]
	s_add_u32 m0, s4, 0x4800
	v_mfma_f32_16x16x32_bf16 v[38:41], v[222:225], v[74:77], v[38:41]
	global_load_lds_dwordx4 v100, s[28:29]
	v_mfma_f32_16x16x32_bf16 v[22:25], v[226:229], v[74:77], v[22:25]
	v_mfma_f32_16x16x32_bf16 v[6:9], v[230:233], v[74:77], v[6:9]
	v_mfma_f32_16x16x32_bf16 v[50:53], v[218:221], v[78:81], v[50:53]
	s_add_u32 m0, s4, 0x4c00
	v_mfma_f32_16x16x32_bf16 v[34:37], v[222:225], v[78:81], v[34:37]
	global_load_lds_dwordx4 v101, s[28:29]
	v_mfma_f32_16x16x32_bf16 v[18:21], v[226:229], v[78:81], v[18:21]
	v_mfma_f32_16x16x32_bf16 v[2:5], v[230:233], v[78:81], v[2:5]
	s_waitcnt lgkmcnt(0)
	v_mfma_f32_16x16x32_bf16 v[62:65], v[234:237], v[82:85], v[62:65]
	s_add_u32 m0, s4, 0x8000
	v_mfma_f32_16x16x32_bf16 v[46:49], v[238:241], v[82:85], v[46:49]
	global_load_lds_dwordx4 v98, s[48:49]
	v_mfma_f32_16x16x32_bf16 v[30:33], v[242:245], v[82:85], v[30:33]
	v_mfma_f32_16x16x32_bf16 v[14:17], v[246:249], v[82:85], v[14:17]
	v_mfma_f32_16x16x32_bf16 v[58:61], v[234:237], v[86:89], v[58:61]
	s_add_u32 m0, s4, 0x8400
	v_mfma_f32_16x16x32_bf16 v[42:45], v[238:241], v[86:89], v[42:45]
	global_load_lds_dwordx4 v99, s[48:49]
	v_mfma_f32_16x16x32_bf16 v[26:29], v[242:245], v[86:89], v[26:29]
	v_mfma_f32_16x16x32_bf16 v[10:13], v[246:249], v[86:89], v[10:13]
	v_mfma_f32_16x16x32_bf16 v[54:57], v[234:237], v[90:93], v[54:57]
	s_add_u32 m0, s4, 0x8800
	v_mfma_f32_16x16x32_bf16 v[38:41], v[238:241], v[90:93], v[38:41]
	global_load_lds_dwordx4 v100, s[48:49]
	v_mfma_f32_16x16x32_bf16 v[22:25], v[242:245], v[90:93], v[22:25]
	v_mfma_f32_16x16x32_bf16 v[6:9], v[246:249], v[90:93], v[6:9]
	v_mfma_f32_16x16x32_bf16 v[50:53], v[234:237], v[94:97], v[50:53]
	s_add_u32 m0, s4, 0x8c00
	v_mfma_f32_16x16x32_bf16 v[34:37], v[238:241], v[94:97], v[34:37]
	global_load_lds_dwordx4 v101, s[48:49]
	v_mfma_f32_16x16x32_bf16 v[18:21], v[242:245], v[94:97], v[18:21]
	v_mfma_f32_16x16x32_bf16 v[2:5], v[246:249], v[94:97], v[2:5]
	s_waitcnt vmcnt(8)
	s_barrier
	ds_read_b128 v[218:221], v102 offset:0
	ds_read_b128 v[222:225], v102 offset:2048
	ds_read_b128 v[226:229], v102 offset:4096
	ds_read_b128 v[230:233], v102 offset:6144
	ds_read_b128 v[234:237], v103 offset:0
	ds_read_b128 v[238:241], v103 offset:2048
	ds_read_b128 v[242:245], v103 offset:4096
	ds_read_b128 v[246:249], v103 offset:6144
	s_waitcnt lgkmcnt(4)
	v_mfma_f32_16x16x32_bf16 v[106:109], v[218:221], v[66:69], v[106:109]
	s_add_u32 m0, s4, 0xc000
	v_mfma_f32_16x16x32_bf16 v[122:125], v[222:225], v[66:69], v[122:125]
	global_load_lds_dwordx4 v98, s[6:7]
	v_mfma_f32_16x16x32_bf16 v[138:141], v[226:229], v[66:69], v[138:141]
	v_mfma_f32_16x16x32_bf16 v[162:165], v[230:233], v[66:69], v[162:165]
	v_mfma_f32_16x16x32_bf16 v[110:113], v[218:221], v[70:73], v[110:113]
	s_add_u32 m0, s4, 0xc400
	v_mfma_f32_16x16x32_bf16 v[126:129], v[222:225], v[70:73], v[126:129]
	global_load_lds_dwordx4 v99, s[6:7]
	v_mfma_f32_16x16x32_bf16 v[142:145], v[226:229], v[70:73], v[142:145]
	v_mfma_f32_16x16x32_bf16 v[166:169], v[230:233], v[70:73], v[166:169]
	v_mfma_f32_16x16x32_bf16 v[114:117], v[218:221], v[74:77], v[114:117]
	s_add_u32 m0, s4, 0xc800
	v_mfma_f32_16x16x32_bf16 v[130:133], v[222:225], v[74:77], v[130:133]
	global_load_lds_dwordx4 v100, s[6:7]
	v_mfma_f32_16x16x32_bf16 v[154:157], v[226:229], v[74:77], v[154:157]
	v_mfma_f32_16x16x32_bf16 v[170:173], v[230:233], v[74:77], v[170:173]
	v_mfma_f32_16x16x32_bf16 v[118:121], v[218:221], v[78:81], v[118:121]
	s_add_u32 m0, s4, 0xcc00
	v_mfma_f32_16x16x32_bf16 v[134:137], v[222:225], v[78:81], v[134:137]
	global_load_lds_dwordx4 v101, s[6:7]
	v_mfma_f32_16x16x32_bf16 v[158:161], v[226:229], v[78:81], v[158:161]
	v_mfma_f32_16x16x32_bf16 v[174:177], v[230:233], v[78:81], v[174:177]
	v_add_u32_e32 v98, 0x80, v98
	v_add_u32_e32 v99, 0x80, v99
	v_add_u32_e32 v100, 0x80, v100
	v_add_u32_e32 v101, 0x80, v101
	s_waitcnt lgkmcnt(0)
	v_mfma_f32_16x16x32_bf16 v[106:109], v[234:237], v[82:85], v[106:109]
	v_mfma_f32_16x16x32_bf16 v[122:125], v[238:241], v[82:85], v[122:125]
	v_mfma_f32_16x16x32_bf16 v[138:141], v[242:245], v[82:85], v[138:141]
	v_mfma_f32_16x16x32_bf16 v[162:165], v[246:249], v[82:85], v[162:165]
	v_mfma_f32_16x16x32_bf16 v[110:113], v[234:237], v[86:89], v[110:113]
	v_mfma_f32_16x16x32_bf16 v[126:129], v[238:241], v[86:89], v[126:129]
	v_mfma_f32_16x16x32_bf16 v[142:145], v[242:245], v[86:89], v[142:145]
	v_mfma_f32_16x16x32_bf16 v[166:169], v[246:249], v[86:89], v[166:169]
	v_mfma_f32_16x16x32_bf16 v[114:117], v[234:237], v[90:93], v[114:117]
	v_mfma_f32_16x16x32_bf16 v[130:133], v[238:241], v[90:93], v[130:133]
	v_mfma_f32_16x16x32_bf16 v[154:157], v[242:245], v[90:93], v[154:157]
	v_mfma_f32_16x16x32_bf16 v[170:173], v[246:249], v[90:93], v[170:173]
	v_mfma_f32_16x16x32_bf16 v[118:121], v[234:237], v[94:97], v[118:121]
	v_mfma_f32_16x16x32_bf16 v[134:137], v[238:241], v[94:97], v[134:137]
	v_mfma_f32_16x16x32_bf16 v[158:161], v[242:245], v[94:97], v[158:161]
	v_mfma_f32_16x16x32_bf16 v[174:177], v[246:249], v[94:97], v[174:177]
	s_waitcnt vmcnt(4)
	s_barrier
	ds_read_b128 v[218:221], v102 offset:16384
	ds_read_b128 v[222:225], v102 offset:18432
	ds_read_b128 v[226:229], v102 offset:20480
	ds_read_b128 v[230:233], v102 offset:22528
	ds_read_b128 v[66:69], v104 offset:32768
	ds_read_b128 v[70:73], v104 offset:34816
	ds_read_b128 v[74:77], v104 offset:36864
	ds_read_b128 v[78:81], v104 offset:38912
	ds_read_b128 v[234:237], v103 offset:16384
	ds_read_b128 v[238:241], v103 offset:18432
	ds_read_b128 v[242:245], v103 offset:20480
	ds_read_b128 v[246:249], v103 offset:22528
	ds_read_b128 v[82:85], v105 offset:32768
	ds_read_b128 v[86:89], v105 offset:34816
	ds_read_b128 v[90:93], v105 offset:36864
	ds_read_b128 v[94:97], v105 offset:38912
	s_waitcnt lgkmcnt(8)
	v_mfma_f32_16x16x32_bf16 v[62:65], v[218:221], v[66:69], v[62:65]
	s_add_u32 m0, s4, 0x0
	v_mfma_f32_16x16x32_bf16 v[46:49], v[222:225], v[66:69], v[46:49]
	global_load_lds_dwordx4 v98, s[28:29]
	v_mfma_f32_16x16x32_bf16 v[30:33], v[226:229], v[66:69], v[30:33]
	v_mfma_f32_16x16x32_bf16 v[14:17], v[230:233], v[66:69], v[14:17]
	v_mfma_f32_16x16x32_bf16 v[58:61], v[218:221], v[70:73], v[58:61]
	s_add_u32 m0, s4, 0x400
	v_mfma_f32_16x16x32_bf16 v[42:45], v[222:225], v[70:73], v[42:45]
	global_load_lds_dwordx4 v99, s[28:29]
	v_mfma_f32_16x16x32_bf16 v[26:29], v[226:229], v[70:73], v[26:29]
	v_mfma_f32_16x16x32_bf16 v[10:13], v[230:233], v[70:73], v[10:13]
	v_mfma_f32_16x16x32_bf16 v[54:57], v[218:221], v[74:77], v[54:57]
	s_add_u32 m0, s4, 0x800
	v_mfma_f32_16x16x32_bf16 v[38:41], v[222:225], v[74:77], v[38:41]
	global_load_lds_dwordx4 v100, s[28:29]
	v_mfma_f32_16x16x32_bf16 v[22:25], v[226:229], v[74:77], v[22:25]
	v_mfma_f32_16x16x32_bf16 v[6:9], v[230:233], v[74:77], v[6:9]
	v_mfma_f32_16x16x32_bf16 v[50:53], v[218:221], v[78:81], v[50:53]
	s_add_u32 m0, s4, 0xc00
	v_mfma_f32_16x16x32_bf16 v[34:37], v[222:225], v[78:81], v[34:37]
	global_load_lds_dwordx4 v101, s[28:29]
	v_mfma_f32_16x16x32_bf16 v[18:21], v[226:229], v[78:81], v[18:21]
	v_mfma_f32_16x16x32_bf16 v[2:5], v[230:233], v[78:81], v[2:5]
	s_waitcnt lgkmcnt(0)
	v_mfma_f32_16x16x32_bf16 v[62:65], v[234:237], v[82:85], v[62:65]
	s_add_u32 m0, s4, 0x10000
	v_mfma_f32_16x16x32_bf16 v[46:49], v[238:241], v[82:85], v[46:49]
	global_load_lds_dwordx4 v98, s[48:49]
	v_mfma_f32_16x16x32_bf16 v[30:33], v[242:245], v[82:85], v[30:33]
	v_mfma_f32_16x16x32_bf16 v[14:17], v[246:249], v[82:85], v[14:17]
	v_mfma_f32_16x16x32_bf16 v[58:61], v[234:237], v[86:89], v[58:61]
	s_add_u32 m0, s4, 0x10400
	v_mfma_f32_16x16x32_bf16 v[42:45], v[238:241], v[86:89], v[42:45]
	global_load_lds_dwordx4 v99, s[48:49]
	v_mfma_f32_16x16x32_bf16 v[26:29], v[242:245], v[86:89], v[26:29]
	v_mfma_f32_16x16x32_bf16 v[10:13], v[246:249], v[86:89], v[10:13]
	v_mfma_f32_16x16x32_bf16 v[54:57], v[234:237], v[90:93], v[54:57]
	s_add_u32 m0, s4, 0x10800
	v_mfma_f32_16x16x32_bf16 v[38:41], v[238:241], v[90:93], v[38:41]
	global_load_lds_dwordx4 v100, s[48:49]
	v_mfma_f32_16x16x32_bf16 v[22:25], v[242:245], v[90:93], v[22:25]
	v_mfma_f32_16x16x32_bf16 v[6:9], v[246:249], v[90:93], v[6:9]
	v_mfma_f32_16x16x32_bf16 v[50:53], v[234:237], v[94:97], v[50:53]
	s_add_u32 m0, s4, 0x10c00
	v_mfma_f32_16x16x32_bf16 v[34:37], v[238:241], v[94:97], v[34:37]
	global_load_lds_dwordx4 v101, s[48:49]
	v_mfma_f32_16x16x32_bf16 v[18:21], v[242:245], v[94:97], v[18:21]
	v_mfma_f32_16x16x32_bf16 v[2:5], v[246:249], v[94:97], v[2:5]
	s_waitcnt vmcnt(8)
	s_barrier
	ds_read_b128 v[218:221], v102 offset:49152
	ds_read_b128 v[222:225], v102 offset:51200
	ds_read_b128 v[226:229], v102 offset:53248
	ds_read_b128 v[230:233], v102 offset:55296
	ds_read_b128 v[234:237], v103 offset:49152
	ds_read_b128 v[238:241], v103 offset:51200
	ds_read_b128 v[242:245], v103 offset:53248
	ds_read_b128 v[246:249], v103 offset:55296
	s_waitcnt lgkmcnt(4)
	v_mfma_f32_16x16x32_bf16 v[106:109], v[218:221], v[66:69], v[106:109]
	s_add_u32 m0, s4, 0x4000
	v_mfma_f32_16x16x32_bf16 v[122:125], v[222:225], v[66:69], v[122:125]
	global_load_lds_dwordx4 v98, s[6:7]
	v_mfma_f32_16x16x32_bf16 v[138:141], v[226:229], v[66:69], v[138:141]
	v_mfma_f32_16x16x32_bf16 v[162:165], v[230:233], v[66:69], v[162:165]
	v_mfma_f32_16x16x32_bf16 v[110:113], v[218:221], v[70:73], v[110:113]
	s_add_u32 m0, s4, 0x4400
	v_mfma_f32_16x16x32_bf16 v[126:129], v[222:225], v[70:73], v[126:129]
	global_load_lds_dwordx4 v99, s[6:7]
	v_mfma_f32_16x16x32_bf16 v[142:145], v[226:229], v[70:73], v[142:145]
	v_mfma_f32_16x16x32_bf16 v[166:169], v[230:233], v[70:73], v[166:169]
	v_mfma_f32_16x16x32_bf16 v[114:117], v[218:221], v[74:77], v[114:117]
	s_add_u32 m0, s4, 0x4800
	v_mfma_f32_16x16x32_bf16 v[130:133], v[222:225], v[74:77], v[130:133]
	global_load_lds_dwordx4 v100, s[6:7]
	v_mfma_f32_16x16x32_bf16 v[154:157], v[226:229], v[74:77], v[154:157]
	v_mfma_f32_16x16x32_bf16 v[170:173], v[230:233], v[74:77], v[170:173]
	v_mfma_f32_16x16x32_bf16 v[118:121], v[218:221], v[78:81], v[118:121]
	s_add_u32 m0, s4, 0x4c00
	v_mfma_f32_16x16x32_bf16 v[134:137], v[222:225], v[78:81], v[134:137]
	global_load_lds_dwordx4 v101, s[6:7]
	v_mfma_f32_16x16x32_bf16 v[158:161], v[226:229], v[78:81], v[158:161]
	v_mfma_f32_16x16x32_bf16 v[174:177], v[230:233], v[78:81], v[174:177]
	v_add_u32_e32 v98, 0x80, v98
	v_add_u32_e32 v99, 0x80, v99
	v_add_u32_e32 v100, 0x80, v100
	v_add_u32_e32 v101, 0x80, v101
	s_waitcnt lgkmcnt(0)
	v_mfma_f32_16x16x32_bf16 v[106:109], v[234:237], v[82:85], v[106:109]
	v_mfma_f32_16x16x32_bf16 v[122:125], v[238:241], v[82:85], v[122:125]
	v_mfma_f32_16x16x32_bf16 v[138:141], v[242:245], v[82:85], v[138:141]
	v_mfma_f32_16x16x32_bf16 v[162:165], v[246:249], v[82:85], v[162:165]
	v_mfma_f32_16x16x32_bf16 v[110:113], v[234:237], v[86:89], v[110:113]
	v_mfma_f32_16x16x32_bf16 v[126:129], v[238:241], v[86:89], v[126:129]
	v_mfma_f32_16x16x32_bf16 v[142:145], v[242:245], v[86:89], v[142:145]
	v_mfma_f32_16x16x32_bf16 v[166:169], v[246:249], v[86:89], v[166:169]
	v_mfma_f32_16x16x32_bf16 v[114:117], v[234:237], v[90:93], v[114:117]
	v_mfma_f32_16x16x32_bf16 v[130:133], v[238:241], v[90:93], v[130:133]
	v_mfma_f32_16x16x32_bf16 v[154:157], v[242:245], v[90:93], v[154:157]
	v_mfma_f32_16x16x32_bf16 v[170:173], v[246:249], v[90:93], v[170:173]
	v_mfma_f32_16x16x32_bf16 v[118:121], v[234:237], v[94:97], v[118:121]
	v_mfma_f32_16x16x32_bf16 v[134:137], v[238:241], v[94:97], v[134:137]
	v_mfma_f32_16x16x32_bf16 v[158:161], v[242:245], v[94:97], v[158:161]
	v_mfma_f32_16x16x32_bf16 v[174:177], v[246:249], v[94:97], v[174:177]
	s_waitcnt vmcnt(4)
	s_barrier
	ds_read_b128 v[218:221], v102 offset:0
	ds_read_b128 v[222:225], v102 offset:2048
	ds_read_b128 v[226:229], v102 offset:4096
	ds_read_b128 v[230:233], v102 offset:6144
	ds_read_b128 v[66:69], v250 offset:49152
	ds_read_b128 v[70:73], v250 offset:51200
	ds_read_b128 v[74:77], v250 offset:53248
	ds_read_b128 v[78:81], v250 offset:55296
	ds_read_b128 v[234:237], v103 offset:0
	ds_read_b128 v[238:241], v103 offset:2048
	ds_read_b128 v[242:245], v103 offset:4096
	ds_read_b128 v[246:249], v103 offset:6144
	ds_read_b128 v[82:85], v251 offset:49152
	ds_read_b128 v[86:89], v251 offset:51200
	ds_read_b128 v[90:93], v251 offset:53248
	ds_read_b128 v[94:97], v251 offset:55296
	s_waitcnt lgkmcnt(8)
	v_mfma_f32_16x16x32_bf16 v[62:65], v[218:221], v[66:69], v[62:65]
	s_add_u32 m0, s4, 0xc000
	v_mfma_f32_16x16x32_bf16 v[46:49], v[222:225], v[66:69], v[46:49]
	global_load_lds_dwordx4 v98, s[28:29]
	v_mfma_f32_16x16x32_bf16 v[30:33], v[226:229], v[66:69], v[30:33]
	v_mfma_f32_16x16x32_bf16 v[14:17], v[230:233], v[66:69], v[14:17]
	v_mfma_f32_16x16x32_bf16 v[58:61], v[218:221], v[70:73], v[58:61]
	s_add_u32 m0, s4, 0xc400
	v_mfma_f32_16x16x32_bf16 v[42:45], v[222:225], v[70:73], v[42:45]
	global_load_lds_dwordx4 v99, s[28:29]
	v_mfma_f32_16x16x32_bf16 v[26:29], v[226:229], v[70:73], v[26:29]
	v_mfma_f32_16x16x32_bf16 v[10:13], v[230:233], v[70:73], v[10:13]
	v_mfma_f32_16x16x32_bf16 v[54:57], v[218:221], v[74:77], v[54:57]
	s_add_u32 m0, s4, 0xc800
	v_mfma_f32_16x16x32_bf16 v[38:41], v[222:225], v[74:77], v[38:41]
	global_load_lds_dwordx4 v100, s[28:29]
	v_mfma_f32_16x16x32_bf16 v[22:25], v[226:229], v[74:77], v[22:25]
	v_mfma_f32_16x16x32_bf16 v[6:9], v[230:233], v[74:77], v[6:9]
	v_mfma_f32_16x16x32_bf16 v[50:53], v[218:221], v[78:81], v[50:53]
	s_add_u32 m0, s4, 0xcc00
	v_mfma_f32_16x16x32_bf16 v[34:37], v[222:225], v[78:81], v[34:37]
	global_load_lds_dwordx4 v101, s[28:29]
	v_mfma_f32_16x16x32_bf16 v[18:21], v[226:229], v[78:81], v[18:21]
	v_mfma_f32_16x16x32_bf16 v[2:5], v[230:233], v[78:81], v[2:5]
	s_waitcnt lgkmcnt(0)
	v_mfma_f32_16x16x32_bf16 v[62:65], v[234:237], v[82:85], v[62:65]
	s_add_u32 m0, s4, 0x8000
	v_mfma_f32_16x16x32_bf16 v[46:49], v[238:241], v[82:85], v[46:49]
	global_load_lds_dwordx4 v98, s[48:49]
	v_mfma_f32_16x16x32_bf16 v[30:33], v[242:245], v[82:85], v[30:33]
	v_mfma_f32_16x16x32_bf16 v[14:17], v[246:249], v[82:85], v[14:17]
	v_mfma_f32_16x16x32_bf16 v[58:61], v[234:237], v[86:89], v[58:61]
	s_add_u32 m0, s4, 0x8400
	v_mfma_f32_16x16x32_bf16 v[42:45], v[238:241], v[86:89], v[42:45]
	global_load_lds_dwordx4 v99, s[48:49]
	v_mfma_f32_16x16x32_bf16 v[26:29], v[242:245], v[86:89], v[26:29]
	v_mfma_f32_16x16x32_bf16 v[10:13], v[246:249], v[86:89], v[10:13]
	v_mfma_f32_16x16x32_bf16 v[54:57], v[234:237], v[90:93], v[54:57]
	s_add_u32 m0, s4, 0x8800
	v_mfma_f32_16x16x32_bf16 v[38:41], v[238:241], v[90:93], v[38:41]
	global_load_lds_dwordx4 v100, s[48:49]
	v_mfma_f32_16x16x32_bf16 v[22:25], v[242:245], v[90:93], v[22:25]
	v_mfma_f32_16x16x32_bf16 v[6:9], v[246:249], v[90:93], v[6:9]
	v_mfma_f32_16x16x32_bf16 v[50:53], v[234:237], v[94:97], v[50:53]
	s_add_u32 m0, s4, 0x8c00
	v_mfma_f32_16x16x32_bf16 v[34:37], v[238:241], v[94:97], v[34:37]
	global_load_lds_dwordx4 v101, s[48:49]
	v_mfma_f32_16x16x32_bf16 v[18:21], v[242:245], v[94:97], v[18:21]
	v_mfma_f32_16x16x32_bf16 v[2:5], v[246:249], v[94:97], v[2:5]
	s_waitcnt vmcnt(8)
	s_barrier
	ds_read_b128 v[218:221], v102 offset:16384
	ds_read_b128 v[222:225], v102 offset:18432
	ds_read_b128 v[226:229], v102 offset:20480
	ds_read_b128 v[230:233], v102 offset:22528
	ds_read_b128 v[234:237], v103 offset:16384
	ds_read_b128 v[238:241], v103 offset:18432
	ds_read_b128 v[242:245], v103 offset:20480
	ds_read_b128 v[246:249], v103 offset:22528
	s_waitcnt lgkmcnt(4)
	v_mfma_f32_16x16x32_bf16 v[106:109], v[218:221], v[66:69], v[106:109]
	s_add_u32 m0, s4, 0x0
	v_mfma_f32_16x16x32_bf16 v[122:125], v[222:225], v[66:69], v[122:125]
	global_load_lds_dwordx4 v98, s[6:7]
	v_mfma_f32_16x16x32_bf16 v[138:141], v[226:229], v[66:69], v[138:141]
	v_mfma_f32_16x16x32_bf16 v[162:165], v[230:233], v[66:69], v[162:165]
	v_mfma_f32_16x16x32_bf16 v[110:113], v[218:221], v[70:73], v[110:113]
	s_add_u32 m0, s4, 0x400
	v_mfma_f32_16x16x32_bf16 v[126:129], v[222:225], v[70:73], v[126:129]
	global_load_lds_dwordx4 v99, s[6:7]
	v_mfma_f32_16x16x32_bf16 v[142:145], v[226:229], v[70:73], v[142:145]
	v_mfma_f32_16x16x32_bf16 v[166:169], v[230:233], v[70:73], v[166:169]
	v_mfma_f32_16x16x32_bf16 v[114:117], v[218:221], v[74:77], v[114:117]
	s_add_u32 m0, s4, 0x800
	v_mfma_f32_16x16x32_bf16 v[130:133], v[222:225], v[74:77], v[130:133]
	global_load_lds_dwordx4 v100, s[6:7]
	v_mfma_f32_16x16x32_bf16 v[154:157], v[226:229], v[74:77], v[154:157]
	v_mfma_f32_16x16x32_bf16 v[170:173], v[230:233], v[74:77], v[170:173]
	v_mfma_f32_16x16x32_bf16 v[118:121], v[218:221], v[78:81], v[118:121]
	s_add_u32 m0, s4, 0xc00
	v_mfma_f32_16x16x32_bf16 v[134:137], v[222:225], v[78:81], v[134:137]
	global_load_lds_dwordx4 v101, s[6:7]
	v_mfma_f32_16x16x32_bf16 v[158:161], v[226:229], v[78:81], v[158:161]
	v_mfma_f32_16x16x32_bf16 v[174:177], v[230:233], v[78:81], v[174:177]
	v_add_u32_e32 v98, 0x80, v98
	v_add_u32_e32 v99, 0x80, v99
	v_add_u32_e32 v100, 0x80, v100
	v_add_u32_e32 v101, 0x80, v101
	s_waitcnt lgkmcnt(0)
	v_mfma_f32_16x16x32_bf16 v[106:109], v[234:237], v[82:85], v[106:109]
	v_mfma_f32_16x16x32_bf16 v[122:125], v[238:241], v[82:85], v[122:125]
	v_mfma_f32_16x16x32_bf16 v[138:141], v[242:245], v[82:85], v[138:141]
	v_mfma_f32_16x16x32_bf16 v[162:165], v[246:249], v[82:85], v[162:165]
	v_mfma_f32_16x16x32_bf16 v[110:113], v[234:237], v[86:89], v[110:113]
	v_mfma_f32_16x16x32_bf16 v[126:129], v[238:241], v[86:89], v[126:129]
	v_mfma_f32_16x16x32_bf16 v[142:145], v[242:245], v[86:89], v[142:145]
	v_mfma_f32_16x16x32_bf16 v[166:169], v[246:249], v[86:89], v[166:169]
	v_mfma_f32_16x16x32_bf16 v[114:117], v[234:237], v[90:93], v[114:117]
	v_mfma_f32_16x16x32_bf16 v[130:133], v[238:241], v[90:93], v[130:133]
	v_mfma_f32_16x16x32_bf16 v[154:157], v[242:245], v[90:93], v[154:157]
	v_mfma_f32_16x16x32_bf16 v[170:173], v[246:249], v[90:93], v[170:173]
	v_mfma_f32_16x16x32_bf16 v[118:121], v[234:237], v[94:97], v[118:121]
	v_mfma_f32_16x16x32_bf16 v[134:137], v[238:241], v[94:97], v[134:137]
	v_mfma_f32_16x16x32_bf16 v[158:161], v[242:245], v[94:97], v[158:161]
	v_mfma_f32_16x16x32_bf16 v[174:177], v[246:249], v[94:97], v[174:177]
	s_waitcnt vmcnt(4)
	s_barrier
	ds_read_b128 v[218:221], v102 offset:49152
	ds_read_b128 v[222:225], v102 offset:51200
	ds_read_b128 v[226:229], v102 offset:53248
	ds_read_b128 v[230:233], v102 offset:55296
	ds_read_b128 v[66:69], v104 offset:32768
	ds_read_b128 v[70:73], v104 offset:34816
	ds_read_b128 v[74:77], v104 offset:36864
	ds_read_b128 v[78:81], v104 offset:38912
	ds_read_b128 v[234:237], v103 offset:49152
	ds_read_b128 v[238:241], v103 offset:51200
	ds_read_b128 v[242:245], v103 offset:53248
	ds_read_b128 v[246:249], v103 offset:55296
	ds_read_b128 v[82:85], v105 offset:32768
	ds_read_b128 v[86:89], v105 offset:34816
	ds_read_b128 v[90:93], v105 offset:36864
	ds_read_b128 v[94:97], v105 offset:38912
	s_waitcnt lgkmcnt(8)
	v_mfma_f32_16x16x32_bf16 v[62:65], v[218:221], v[66:69], v[62:65]
	s_add_u32 m0, s4, 0x4000
	v_mfma_f32_16x16x32_bf16 v[46:49], v[222:225], v[66:69], v[46:49]
	global_load_lds_dwordx4 v98, s[28:29]
	v_mfma_f32_16x16x32_bf16 v[30:33], v[226:229], v[66:69], v[30:33]
	v_mfma_f32_16x16x32_bf16 v[14:17], v[230:233], v[66:69], v[14:17]
	v_mfma_f32_16x16x32_bf16 v[58:61], v[218:221], v[70:73], v[58:61]
	s_add_u32 m0, s4, 0x4400
	v_mfma_f32_16x16x32_bf16 v[42:45], v[222:225], v[70:73], v[42:45]
	global_load_lds_dwordx4 v99, s[28:29]
	v_mfma_f32_16x16x32_bf16 v[26:29], v[226:229], v[70:73], v[26:29]
	v_mfma_f32_16x16x32_bf16 v[10:13], v[230:233], v[70:73], v[10:13]
	v_mfma_f32_16x16x32_bf16 v[54:57], v[218:221], v[74:77], v[54:57]
	s_add_u32 m0, s4, 0x4800
	v_mfma_f32_16x16x32_bf16 v[38:41], v[222:225], v[74:77], v[38:41]
	global_load_lds_dwordx4 v100, s[28:29]
	v_mfma_f32_16x16x32_bf16 v[22:25], v[226:229], v[74:77], v[22:25]
	v_mfma_f32_16x16x32_bf16 v[6:9], v[230:233], v[74:77], v[6:9]
	v_mfma_f32_16x16x32_bf16 v[50:53], v[218:221], v[78:81], v[50:53]
	s_add_u32 m0, s4, 0x4c00
	v_mfma_f32_16x16x32_bf16 v[34:37], v[222:225], v[78:81], v[34:37]
	global_load_lds_dwordx4 v101, s[28:29]
	v_mfma_f32_16x16x32_bf16 v[18:21], v[226:229], v[78:81], v[18:21]
	v_mfma_f32_16x16x32_bf16 v[2:5], v[230:233], v[78:81], v[2:5]
	s_waitcnt lgkmcnt(0)
	v_mfma_f32_16x16x32_bf16 v[62:65], v[234:237], v[82:85], v[62:65]
	s_add_u32 m0, s4, 0x10000
	v_mfma_f32_16x16x32_bf16 v[46:49], v[238:241], v[82:85], v[46:49]
	global_load_lds_dwordx4 v98, s[48:49]
	v_mfma_f32_16x16x32_bf16 v[30:33], v[242:245], v[82:85], v[30:33]
	v_mfma_f32_16x16x32_bf16 v[14:17], v[246:249], v[82:85], v[14:17]
	v_mfma_f32_16x16x32_bf16 v[58:61], v[234:237], v[86:89], v[58:61]
	s_add_u32 m0, s4, 0x10400
	v_mfma_f32_16x16x32_bf16 v[42:45], v[238:241], v[86:89], v[42:45]
	global_load_lds_dwordx4 v99, s[48:49]
	v_mfma_f32_16x16x32_bf16 v[26:29], v[242:245], v[86:89], v[26:29]
	v_mfma_f32_16x16x32_bf16 v[10:13], v[246:249], v[86:89], v[10:13]
	v_mfma_f32_16x16x32_bf16 v[54:57], v[234:237], v[90:93], v[54:57]
	s_add_u32 m0, s4, 0x10800
	v_mfma_f32_16x16x32_bf16 v[38:41], v[238:241], v[90:93], v[38:41]
	global_load_lds_dwordx4 v100, s[48:49]
	v_mfma_f32_16x16x32_bf16 v[22:25], v[242:245], v[90:93], v[22:25]
	v_mfma_f32_16x16x32_bf16 v[6:9], v[246:249], v[90:93], v[6:9]
	v_mfma_f32_16x16x32_bf16 v[50:53], v[234:237], v[94:97], v[50:53]
	s_add_u32 m0, s4, 0x10c00
	v_mfma_f32_16x16x32_bf16 v[34:37], v[238:241], v[94:97], v[34:37]
	global_load_lds_dwordx4 v101, s[48:49]
	v_mfma_f32_16x16x32_bf16 v[18:21], v[242:245], v[94:97], v[18:21]
	v_mfma_f32_16x16x32_bf16 v[2:5], v[246:249], v[94:97], v[2:5]
	s_waitcnt vmcnt(8)
	s_barrier
	ds_read_b128 v[218:221], v102 offset:0
	ds_read_b128 v[222:225], v102 offset:2048
	ds_read_b128 v[226:229], v102 offset:4096
	ds_read_b128 v[230:233], v102 offset:6144
	ds_read_b128 v[234:237], v103 offset:0
	ds_read_b128 v[238:241], v103 offset:2048
	ds_read_b128 v[242:245], v103 offset:4096
	ds_read_b128 v[246:249], v103 offset:6144
	s_waitcnt lgkmcnt(4)
	v_mfma_f32_16x16x32_bf16 v[106:109], v[218:221], v[66:69], v[106:109]
	s_add_u32 m0, s4, 0xc000
	v_mfma_f32_16x16x32_bf16 v[122:125], v[222:225], v[66:69], v[122:125]
	global_load_lds_dwordx4 v98, s[6:7]
	v_mfma_f32_16x16x32_bf16 v[138:141], v[226:229], v[66:69], v[138:141]
	v_mfma_f32_16x16x32_bf16 v[162:165], v[230:233], v[66:69], v[162:165]
	v_mfma_f32_16x16x32_bf16 v[110:113], v[218:221], v[70:73], v[110:113]
	s_add_u32 m0, s4, 0xc400
	v_mfma_f32_16x16x32_bf16 v[126:129], v[222:225], v[70:73], v[126:129]
	global_load_lds_dwordx4 v99, s[6:7]
	v_mfma_f32_16x16x32_bf16 v[142:145], v[226:229], v[70:73], v[142:145]
	v_mfma_f32_16x16x32_bf16 v[166:169], v[230:233], v[70:73], v[166:169]
	v_mfma_f32_16x16x32_bf16 v[114:117], v[218:221], v[74:77], v[114:117]
	s_add_u32 m0, s4, 0xc800
	v_mfma_f32_16x16x32_bf16 v[130:133], v[222:225], v[74:77], v[130:133]
	global_load_lds_dwordx4 v100, s[6:7]
	v_mfma_f32_16x16x32_bf16 v[154:157], v[226:229], v[74:77], v[154:157]
	v_mfma_f32_16x16x32_bf16 v[170:173], v[230:233], v[74:77], v[170:173]
	v_mfma_f32_16x16x32_bf16 v[118:121], v[218:221], v[78:81], v[118:121]
	s_add_u32 m0, s4, 0xcc00
	v_mfma_f32_16x16x32_bf16 v[134:137], v[222:225], v[78:81], v[134:137]
	global_load_lds_dwordx4 v101, s[6:7]
	v_mfma_f32_16x16x32_bf16 v[158:161], v[226:229], v[78:81], v[158:161]
	v_mfma_f32_16x16x32_bf16 v[174:177], v[230:233], v[78:81], v[174:177]
	v_add_u32_e32 v98, 0x80, v98
	v_add_u32_e32 v99, 0x80, v99
	v_add_u32_e32 v100, 0x80, v100
	v_add_u32_e32 v101, 0x80, v101
	s_waitcnt lgkmcnt(0)
	v_mfma_f32_16x16x32_bf16 v[106:109], v[234:237], v[82:85], v[106:109]
	v_mfma_f32_16x16x32_bf16 v[122:125], v[238:241], v[82:85], v[122:125]
	v_mfma_f32_16x16x32_bf16 v[138:141], v[242:245], v[82:85], v[138:141]
	v_mfma_f32_16x16x32_bf16 v[162:165], v[246:249], v[82:85], v[162:165]
	v_mfma_f32_16x16x32_bf16 v[110:113], v[234:237], v[86:89], v[110:113]
	v_mfma_f32_16x16x32_bf16 v[126:129], v[238:241], v[86:89], v[126:129]
	v_mfma_f32_16x16x32_bf16 v[142:145], v[242:245], v[86:89], v[142:145]
	v_mfma_f32_16x16x32_bf16 v[166:169], v[246:249], v[86:89], v[166:169]
	v_mfma_f32_16x16x32_bf16 v[114:117], v[234:237], v[90:93], v[114:117]
	v_mfma_f32_16x16x32_bf16 v[130:133], v[238:241], v[90:93], v[130:133]
	v_mfma_f32_16x16x32_bf16 v[154:157], v[242:245], v[90:93], v[154:157]
	v_mfma_f32_16x16x32_bf16 v[170:173], v[246:249], v[90:93], v[170:173]
	v_mfma_f32_16x16x32_bf16 v[118:121], v[234:237], v[94:97], v[118:121]
	v_mfma_f32_16x16x32_bf16 v[134:137], v[238:241], v[94:97], v[134:137]
	v_mfma_f32_16x16x32_bf16 v[158:161], v[242:245], v[94:97], v[158:161]
	v_mfma_f32_16x16x32_bf16 v[174:177], v[246:249], v[94:97], v[174:177]
	s_waitcnt vmcnt(4)
	s_barrier
	ds_read_b128 v[218:221], v102 offset:16384
	ds_read_b128 v[222:225], v102 offset:18432
	ds_read_b128 v[226:229], v102 offset:20480
	ds_read_b128 v[230:233], v102 offset:22528
	ds_read_b128 v[66:69], v250 offset:49152
	ds_read_b128 v[70:73], v250 offset:51200
	ds_read_b128 v[74:77], v250 offset:53248
	ds_read_b128 v[78:81], v250 offset:55296
	ds_read_b128 v[234:237], v103 offset:16384
	ds_read_b128 v[238:241], v103 offset:18432
	ds_read_b128 v[242:245], v103 offset:20480
	ds_read_b128 v[246:249], v103 offset:22528
	ds_read_b128 v[82:85], v251 offset:49152
	ds_read_b128 v[86:89], v251 offset:51200
	ds_read_b128 v[90:93], v251 offset:53248
	ds_read_b128 v[94:97], v251 offset:55296
	s_waitcnt lgkmcnt(8)
	v_mfma_f32_16x16x32_bf16 v[62:65], v[218:221], v[66:69], v[62:65]
	s_add_u32 m0, s4, 0x0
	v_mfma_f32_16x16x32_bf16 v[46:49], v[222:225], v[66:69], v[46:49]
	global_load_lds_dwordx4 v98, s[28:29]
	v_mfma_f32_16x16x32_bf16 v[30:33], v[226:229], v[66:69], v[30:33]
	v_mfma_f32_16x16x32_bf16 v[14:17], v[230:233], v[66:69], v[14:17]
	v_mfma_f32_16x16x32_bf16 v[58:61], v[218:221], v[70:73], v[58:61]
	s_add_u32 m0, s4, 0x400
	v_mfma_f32_16x16x32_bf16 v[42:45], v[222:225], v[70:73], v[42:45]
	global_load_lds_dwordx4 v99, s[28:29]
	v_mfma_f32_16x16x32_bf16 v[26:29], v[226:229], v[70:73], v[26:29]
	v_mfma_f32_16x16x32_bf16 v[10:13], v[230:233], v[70:73], v[10:13]
	v_mfma_f32_16x16x32_bf16 v[54:57], v[218:221], v[74:77], v[54:57]
	s_add_u32 m0, s4, 0x800
	v_mfma_f32_16x16x32_bf16 v[38:41], v[222:225], v[74:77], v[38:41]
	global_load_lds_dwordx4 v100, s[28:29]
	v_mfma_f32_16x16x32_bf16 v[22:25], v[226:229], v[74:77], v[22:25]
	v_mfma_f32_16x16x32_bf16 v[6:9], v[230:233], v[74:77], v[6:9]
	v_mfma_f32_16x16x32_bf16 v[50:53], v[218:221], v[78:81], v[50:53]
	s_add_u32 m0, s4, 0xc00
	v_mfma_f32_16x16x32_bf16 v[34:37], v[222:225], v[78:81], v[34:37]
	global_load_lds_dwordx4 v101, s[28:29]
	v_mfma_f32_16x16x32_bf16 v[18:21], v[226:229], v[78:81], v[18:21]
	v_mfma_f32_16x16x32_bf16 v[2:5], v[230:233], v[78:81], v[2:5]
	s_waitcnt lgkmcnt(0)
	v_mfma_f32_16x16x32_bf16 v[62:65], v[234:237], v[82:85], v[62:65]
	s_add_u32 m0, s4, 0x8000
	v_mfma_f32_16x16x32_bf16 v[46:49], v[238:241], v[82:85], v[46:49]
	global_load_lds_dwordx4 v98, s[48:49]
	v_mfma_f32_16x16x32_bf16 v[30:33], v[242:245], v[82:85], v[30:33]
	v_mfma_f32_16x16x32_bf16 v[14:17], v[246:249], v[82:85], v[14:17]
	v_mfma_f32_16x16x32_bf16 v[58:61], v[234:237], v[86:89], v[58:61]
	s_add_u32 m0, s4, 0x8400
	v_mfma_f32_16x16x32_bf16 v[42:45], v[238:241], v[86:89], v[42:45]
	global_load_lds_dwordx4 v99, s[48:49]
	v_mfma_f32_16x16x32_bf16 v[26:29], v[242:245], v[86:89], v[26:29]
	v_mfma_f32_16x16x32_bf16 v[10:13], v[246:249], v[86:89], v[10:13]
	v_mfma_f32_16x16x32_bf16 v[54:57], v[234:237], v[90:93], v[54:57]
	s_add_u32 m0, s4, 0x8800
	v_mfma_f32_16x16x32_bf16 v[38:41], v[238:241], v[90:93], v[38:41]
	global_load_lds_dwordx4 v100, s[48:49]
	v_mfma_f32_16x16x32_bf16 v[22:25], v[242:245], v[90:93], v[22:25]
	v_mfma_f32_16x16x32_bf16 v[6:9], v[246:249], v[90:93], v[6:9]
	v_mfma_f32_16x16x32_bf16 v[50:53], v[234:237], v[94:97], v[50:53]
	s_add_u32 m0, s4, 0x8c00
	v_mfma_f32_16x16x32_bf16 v[34:37], v[238:241], v[94:97], v[34:37]
	global_load_lds_dwordx4 v101, s[48:49]
	v_mfma_f32_16x16x32_bf16 v[18:21], v[242:245], v[94:97], v[18:21]
	v_mfma_f32_16x16x32_bf16 v[2:5], v[246:249], v[94:97], v[2:5]
	s_waitcnt vmcnt(8)
	s_barrier
	ds_read_b128 v[218:221], v102 offset:49152
	ds_read_b128 v[222:225], v102 offset:51200
	ds_read_b128 v[226:229], v102 offset:53248
	ds_read_b128 v[230:233], v102 offset:55296
	ds_read_b128 v[234:237], v103 offset:49152
	ds_read_b128 v[238:241], v103 offset:51200
	ds_read_b128 v[242:245], v103 offset:53248
	ds_read_b128 v[246:249], v103 offset:55296
	s_waitcnt lgkmcnt(4)
	v_mfma_f32_16x16x32_bf16 v[106:109], v[218:221], v[66:69], v[106:109]
	s_add_u32 m0, s4, 0x4000
	v_mfma_f32_16x16x32_bf16 v[122:125], v[222:225], v[66:69], v[122:125]
	global_load_lds_dwordx4 v98, s[6:7]
	v_mfma_f32_16x16x32_bf16 v[138:141], v[226:229], v[66:69], v[138:141]
	v_mfma_f32_16x16x32_bf16 v[162:165], v[230:233], v[66:69], v[162:165]
	v_mfma_f32_16x16x32_bf16 v[110:113], v[218:221], v[70:73], v[110:113]
	s_add_u32 m0, s4, 0x4400
	v_mfma_f32_16x16x32_bf16 v[126:129], v[222:225], v[70:73], v[126:129]
	global_load_lds_dwordx4 v99, s[6:7]
	v_mfma_f32_16x16x32_bf16 v[142:145], v[226:229], v[70:73], v[142:145]
	v_mfma_f32_16x16x32_bf16 v[166:169], v[230:233], v[70:73], v[166:169]
	v_mfma_f32_16x16x32_bf16 v[114:117], v[218:221], v[74:77], v[114:117]
	s_add_u32 m0, s4, 0x4800
	v_mfma_f32_16x16x32_bf16 v[130:133], v[222:225], v[74:77], v[130:133]
	global_load_lds_dwordx4 v100, s[6:7]
	v_mfma_f32_16x16x32_bf16 v[154:157], v[226:229], v[74:77], v[154:157]
	v_mfma_f32_16x16x32_bf16 v[170:173], v[230:233], v[74:77], v[170:173]
	v_mfma_f32_16x16x32_bf16 v[118:121], v[218:221], v[78:81], v[118:121]
	s_add_u32 m0, s4, 0x4c00
	v_mfma_f32_16x16x32_bf16 v[134:137], v[222:225], v[78:81], v[134:137]
	global_load_lds_dwordx4 v101, s[6:7]
	v_mfma_f32_16x16x32_bf16 v[158:161], v[226:229], v[78:81], v[158:161]
	v_mfma_f32_16x16x32_bf16 v[174:177], v[230:233], v[78:81], v[174:177]
	v_add_u32_e32 v98, 0x80, v98
	v_add_u32_e32 v99, 0x80, v99
	v_add_u32_e32 v100, 0x80, v100
	v_add_u32_e32 v101, 0x80, v101
	s_waitcnt lgkmcnt(0)
	v_mfma_f32_16x16x32_bf16 v[106:109], v[234:237], v[82:85], v[106:109]
	v_mfma_f32_16x16x32_bf16 v[122:125], v[238:241], v[82:85], v[122:125]
	v_mfma_f32_16x16x32_bf16 v[138:141], v[242:245], v[82:85], v[138:141]
	v_mfma_f32_16x16x32_bf16 v[162:165], v[246:249], v[82:85], v[162:165]
	v_mfma_f32_16x16x32_bf16 v[110:113], v[234:237], v[86:89], v[110:113]
	v_mfma_f32_16x16x32_bf16 v[126:129], v[238:241], v[86:89], v[126:129]
	v_mfma_f32_16x16x32_bf16 v[142:145], v[242:245], v[86:89], v[142:145]
	v_mfma_f32_16x16x32_bf16 v[166:169], v[246:249], v[86:89], v[166:169]
	v_mfma_f32_16x16x32_bf16 v[114:117], v[234:237], v[90:93], v[114:117]
	v_mfma_f32_16x16x32_bf16 v[130:133], v[238:241], v[90:93], v[130:133]
	v_mfma_f32_16x16x32_bf16 v[154:157], v[242:245], v[90:93], v[154:157]
	v_mfma_f32_16x16x32_bf16 v[170:173], v[246:249], v[90:93], v[170:173]
	v_mfma_f32_16x16x32_bf16 v[118:121], v[234:237], v[94:97], v[118:121]
	v_mfma_f32_16x16x32_bf16 v[134:137], v[238:241], v[94:97], v[134:137]
	v_mfma_f32_16x16x32_bf16 v[158:161], v[242:245], v[94:97], v[158:161]
	v_mfma_f32_16x16x32_bf16 v[174:177], v[246:249], v[94:97], v[174:177]
	s_waitcnt vmcnt(4)
	s_barrier
	ds_read_b128 v[218:221], v102 offset:0
	ds_read_b128 v[222:225], v102 offset:2048
	ds_read_b128 v[226:229], v102 offset:4096
	ds_read_b128 v[230:233], v102 offset:6144
	ds_read_b128 v[66:69], v104 offset:32768
	ds_read_b128 v[70:73], v104 offset:34816
	ds_read_b128 v[74:77], v104 offset:36864
	ds_read_b128 v[78:81], v104 offset:38912
	ds_read_b128 v[234:237], v103 offset:0
	ds_read_b128 v[238:241], v103 offset:2048
	ds_read_b128 v[242:245], v103 offset:4096
	ds_read_b128 v[246:249], v103 offset:6144
	ds_read_b128 v[82:85], v105 offset:32768
	ds_read_b128 v[86:89], v105 offset:34816
	ds_read_b128 v[90:93], v105 offset:36864
	ds_read_b128 v[94:97], v105 offset:38912
	s_waitcnt lgkmcnt(8)
	v_mfma_f32_16x16x32_bf16 v[62:65], v[218:221], v[66:69], v[62:65]
	s_add_u32 m0, s4, 0xc000
	v_mfma_f32_16x16x32_bf16 v[46:49], v[222:225], v[66:69], v[46:49]
	global_load_lds_dwordx4 v98, s[28:29]
	v_mfma_f32_16x16x32_bf16 v[30:33], v[226:229], v[66:69], v[30:33]
	v_mfma_f32_16x16x32_bf16 v[14:17], v[230:233], v[66:69], v[14:17]
	v_mfma_f32_16x16x32_bf16 v[58:61], v[218:221], v[70:73], v[58:61]
	s_add_u32 m0, s4, 0xc400
	v_mfma_f32_16x16x32_bf16 v[42:45], v[222:225], v[70:73], v[42:45]
	global_load_lds_dwordx4 v99, s[28:29]
	v_mfma_f32_16x16x32_bf16 v[26:29], v[226:229], v[70:73], v[26:29]
	v_mfma_f32_16x16x32_bf16 v[10:13], v[230:233], v[70:73], v[10:13]
	v_mfma_f32_16x16x32_bf16 v[54:57], v[218:221], v[74:77], v[54:57]
	s_add_u32 m0, s4, 0xc800
	v_mfma_f32_16x16x32_bf16 v[38:41], v[222:225], v[74:77], v[38:41]
	global_load_lds_dwordx4 v100, s[28:29]
	v_mfma_f32_16x16x32_bf16 v[22:25], v[226:229], v[74:77], v[22:25]
	v_mfma_f32_16x16x32_bf16 v[6:9], v[230:233], v[74:77], v[6:9]
	v_mfma_f32_16x16x32_bf16 v[50:53], v[218:221], v[78:81], v[50:53]
	s_add_u32 m0, s4, 0xcc00
	v_mfma_f32_16x16x32_bf16 v[34:37], v[222:225], v[78:81], v[34:37]
	global_load_lds_dwordx4 v101, s[28:29]
	v_mfma_f32_16x16x32_bf16 v[18:21], v[226:229], v[78:81], v[18:21]
	v_mfma_f32_16x16x32_bf16 v[2:5], v[230:233], v[78:81], v[2:5]
	s_waitcnt lgkmcnt(0)
	v_mfma_f32_16x16x32_bf16 v[62:65], v[234:237], v[82:85], v[62:65]
	s_add_u32 m0, s4, 0x10000
	v_mfma_f32_16x16x32_bf16 v[46:49], v[238:241], v[82:85], v[46:49]
	global_load_lds_dwordx4 v98, s[48:49]
	v_mfma_f32_16x16x32_bf16 v[30:33], v[242:245], v[82:85], v[30:33]
	v_mfma_f32_16x16x32_bf16 v[14:17], v[246:249], v[82:85], v[14:17]
	v_mfma_f32_16x16x32_bf16 v[58:61], v[234:237], v[86:89], v[58:61]
	s_add_u32 m0, s4, 0x10400
	v_mfma_f32_16x16x32_bf16 v[42:45], v[238:241], v[86:89], v[42:45]
	global_load_lds_dwordx4 v99, s[48:49]
	v_mfma_f32_16x16x32_bf16 v[26:29], v[242:245], v[86:89], v[26:29]
	v_mfma_f32_16x16x32_bf16 v[10:13], v[246:249], v[86:89], v[10:13]
	v_mfma_f32_16x16x32_bf16 v[54:57], v[234:237], v[90:93], v[54:57]
	s_add_u32 m0, s4, 0x10800
	v_mfma_f32_16x16x32_bf16 v[38:41], v[238:241], v[90:93], v[38:41]
	global_load_lds_dwordx4 v100, s[48:49]
	v_mfma_f32_16x16x32_bf16 v[22:25], v[242:245], v[90:93], v[22:25]
	v_mfma_f32_16x16x32_bf16 v[6:9], v[246:249], v[90:93], v[6:9]
	v_mfma_f32_16x16x32_bf16 v[50:53], v[234:237], v[94:97], v[50:53]
	s_add_u32 m0, s4, 0x10c00
	v_mfma_f32_16x16x32_bf16 v[34:37], v[238:241], v[94:97], v[34:37]
	global_load_lds_dwordx4 v101, s[48:49]
	v_mfma_f32_16x16x32_bf16 v[18:21], v[242:245], v[94:97], v[18:21]
	v_mfma_f32_16x16x32_bf16 v[2:5], v[246:249], v[94:97], v[2:5]
	s_waitcnt vmcnt(8)
	s_barrier
	ds_read_b128 v[218:221], v102 offset:16384
	ds_read_b128 v[222:225], v102 offset:18432
	ds_read_b128 v[226:229], v102 offset:20480
	ds_read_b128 v[230:233], v102 offset:22528
	ds_read_b128 v[234:237], v103 offset:16384
	ds_read_b128 v[238:241], v103 offset:18432
	ds_read_b128 v[242:245], v103 offset:20480
	ds_read_b128 v[246:249], v103 offset:22528
	s_waitcnt lgkmcnt(4)
	v_mfma_f32_16x16x32_bf16 v[106:109], v[218:221], v[66:69], v[106:109]
	s_add_u32 m0, s4, 0x0
	v_mfma_f32_16x16x32_bf16 v[122:125], v[222:225], v[66:69], v[122:125]
	global_load_lds_dwordx4 v98, s[6:7]
	v_mfma_f32_16x16x32_bf16 v[138:141], v[226:229], v[66:69], v[138:141]
	v_mfma_f32_16x16x32_bf16 v[162:165], v[230:233], v[66:69], v[162:165]
	v_mfma_f32_16x16x32_bf16 v[110:113], v[218:221], v[70:73], v[110:113]
	s_add_u32 m0, s4, 0x400
	v_mfma_f32_16x16x32_bf16 v[126:129], v[222:225], v[70:73], v[126:129]
	global_load_lds_dwordx4 v99, s[6:7]
	v_mfma_f32_16x16x32_bf16 v[142:145], v[226:229], v[70:73], v[142:145]
	v_mfma_f32_16x16x32_bf16 v[166:169], v[230:233], v[70:73], v[166:169]
	v_mfma_f32_16x16x32_bf16 v[114:117], v[218:221], v[74:77], v[114:117]
	s_add_u32 m0, s4, 0x800
	v_mfma_f32_16x16x32_bf16 v[130:133], v[222:225], v[74:77], v[130:133]
	global_load_lds_dwordx4 v100, s[6:7]
	v_mfma_f32_16x16x32_bf16 v[154:157], v[226:229], v[74:77], v[154:157]
	v_mfma_f32_16x16x32_bf16 v[170:173], v[230:233], v[74:77], v[170:173]
	v_mfma_f32_16x16x32_bf16 v[118:121], v[218:221], v[78:81], v[118:121]
	s_add_u32 m0, s4, 0xc00
	v_mfma_f32_16x16x32_bf16 v[134:137], v[222:225], v[78:81], v[134:137]
	global_load_lds_dwordx4 v101, s[6:7]
	v_mfma_f32_16x16x32_bf16 v[158:161], v[226:229], v[78:81], v[158:161]
	v_mfma_f32_16x16x32_bf16 v[174:177], v[230:233], v[78:81], v[174:177]
	v_add_u32_e32 v98, 0x80, v98
	v_add_u32_e32 v99, 0x80, v99
	v_add_u32_e32 v100, 0x80, v100
	v_add_u32_e32 v101, 0x80, v101
	s_waitcnt lgkmcnt(0)
	v_mfma_f32_16x16x32_bf16 v[106:109], v[234:237], v[82:85], v[106:109]
	v_mfma_f32_16x16x32_bf16 v[122:125], v[238:241], v[82:85], v[122:125]
	v_mfma_f32_16x16x32_bf16 v[138:141], v[242:245], v[82:85], v[138:141]
	v_mfma_f32_16x16x32_bf16 v[162:165], v[246:249], v[82:85], v[162:165]
	v_mfma_f32_16x16x32_bf16 v[110:113], v[234:237], v[86:89], v[110:113]
	v_mfma_f32_16x16x32_bf16 v[126:129], v[238:241], v[86:89], v[126:129]
	v_mfma_f32_16x16x32_bf16 v[142:145], v[242:245], v[86:89], v[142:145]
	v_mfma_f32_16x16x32_bf16 v[166:169], v[246:249], v[86:89], v[166:169]
	v_mfma_f32_16x16x32_bf16 v[114:117], v[234:237], v[90:93], v[114:117]
	v_mfma_f32_16x16x32_bf16 v[130:133], v[238:241], v[90:93], v[130:133]
	v_mfma_f32_16x16x32_bf16 v[154:157], v[242:245], v[90:93], v[154:157]
	v_mfma_f32_16x16x32_bf16 v[170:173], v[246:249], v[90:93], v[170:173]
	v_mfma_f32_16x16x32_bf16 v[118:121], v[234:237], v[94:97], v[118:121]
	v_mfma_f32_16x16x32_bf16 v[134:137], v[238:241], v[94:97], v[134:137]
	v_mfma_f32_16x16x32_bf16 v[158:161], v[242:245], v[94:97], v[158:161]
	v_mfma_f32_16x16x32_bf16 v[174:177], v[246:249], v[94:97], v[174:177]
	s_waitcnt vmcnt(4)
	s_barrier
	ds_read_b128 v[218:221], v102 offset:49152
	ds_read_b128 v[222:225], v102 offset:51200
	ds_read_b128 v[226:229], v102 offset:53248
	ds_read_b128 v[230:233], v102 offset:55296
	ds_read_b128 v[66:69], v250 offset:49152
	ds_read_b128 v[70:73], v250 offset:51200
	ds_read_b128 v[74:77], v250 offset:53248
	ds_read_b128 v[78:81], v250 offset:55296
	ds_read_b128 v[234:237], v103 offset:49152
	ds_read_b128 v[238:241], v103 offset:51200
	ds_read_b128 v[242:245], v103 offset:53248
	ds_read_b128 v[246:249], v103 offset:55296
	ds_read_b128 v[82:85], v251 offset:49152
	ds_read_b128 v[86:89], v251 offset:51200
	ds_read_b128 v[90:93], v251 offset:53248
	ds_read_b128 v[94:97], v251 offset:55296
	s_waitcnt lgkmcnt(8)
	v_mfma_f32_16x16x32_bf16 v[62:65], v[218:221], v[66:69], v[62:65]
	s_add_u32 m0, s4, 0x4000
	v_mfma_f32_16x16x32_bf16 v[46:49], v[222:225], v[66:69], v[46:49]
	global_load_lds_dwordx4 v98, s[28:29]
	v_mfma_f32_16x16x32_bf16 v[30:33], v[226:229], v[66:69], v[30:33]
	v_mfma_f32_16x16x32_bf16 v[14:17], v[230:233], v[66:69], v[14:17]
	v_mfma_f32_16x16x32_bf16 v[58:61], v[218:221], v[70:73], v[58:61]
	s_add_u32 m0, s4, 0x4400
	v_mfma_f32_16x16x32_bf16 v[42:45], v[222:225], v[70:73], v[42:45]
	global_load_lds_dwordx4 v99, s[28:29]
	v_mfma_f32_16x16x32_bf16 v[26:29], v[226:229], v[70:73], v[26:29]
	v_mfma_f32_16x16x32_bf16 v[10:13], v[230:233], v[70:73], v[10:13]
	v_mfma_f32_16x16x32_bf16 v[54:57], v[218:221], v[74:77], v[54:57]
	s_add_u32 m0, s4, 0x4800
	v_mfma_f32_16x16x32_bf16 v[38:41], v[222:225], v[74:77], v[38:41]
	global_load_lds_dwordx4 v100, s[28:29]
	v_mfma_f32_16x16x32_bf16 v[22:25], v[226:229], v[74:77], v[22:25]
	v_mfma_f32_16x16x32_bf16 v[6:9], v[230:233], v[74:77], v[6:9]
	v_mfma_f32_16x16x32_bf16 v[50:53], v[218:221], v[78:81], v[50:53]
	s_add_u32 m0, s4, 0x4c00
	v_mfma_f32_16x16x32_bf16 v[34:37], v[222:225], v[78:81], v[34:37]
	global_load_lds_dwordx4 v101, s[28:29]
	v_mfma_f32_16x16x32_bf16 v[18:21], v[226:229], v[78:81], v[18:21]
	v_mfma_f32_16x16x32_bf16 v[2:5], v[230:233], v[78:81], v[2:5]
	s_waitcnt lgkmcnt(0)
	v_mfma_f32_16x16x32_bf16 v[62:65], v[234:237], v[82:85], v[62:65]
	s_add_u32 m0, s4, 0x8000
	v_mfma_f32_16x16x32_bf16 v[46:49], v[238:241], v[82:85], v[46:49]
	global_load_lds_dwordx4 v98, s[48:49]
	v_mfma_f32_16x16x32_bf16 v[30:33], v[242:245], v[82:85], v[30:33]
	v_mfma_f32_16x16x32_bf16 v[14:17], v[246:249], v[82:85], v[14:17]
	v_mfma_f32_16x16x32_bf16 v[58:61], v[234:237], v[86:89], v[58:61]
	s_add_u32 m0, s4, 0x8400
	v_mfma_f32_16x16x32_bf16 v[42:45], v[238:241], v[86:89], v[42:45]
	global_load_lds_dwordx4 v99, s[48:49]
	v_mfma_f32_16x16x32_bf16 v[26:29], v[242:245], v[86:89], v[26:29]
	v_mfma_f32_16x16x32_bf16 v[10:13], v[246:249], v[86:89], v[10:13]
	v_mfma_f32_16x16x32_bf16 v[54:57], v[234:237], v[90:93], v[54:57]
	s_add_u32 m0, s4, 0x8800
	v_mfma_f32_16x16x32_bf16 v[38:41], v[238:241], v[90:93], v[38:41]
	global_load_lds_dwordx4 v100, s[48:49]
	v_mfma_f32_16x16x32_bf16 v[22:25], v[242:245], v[90:93], v[22:25]
	v_mfma_f32_16x16x32_bf16 v[6:9], v[246:249], v[90:93], v[6:9]
	v_mfma_f32_16x16x32_bf16 v[50:53], v[234:237], v[94:97], v[50:53]
	s_add_u32 m0, s4, 0x8c00
	v_mfma_f32_16x16x32_bf16 v[34:37], v[238:241], v[94:97], v[34:37]
	global_load_lds_dwordx4 v101, s[48:49]
	v_mfma_f32_16x16x32_bf16 v[18:21], v[242:245], v[94:97], v[18:21]
	v_mfma_f32_16x16x32_bf16 v[2:5], v[246:249], v[94:97], v[2:5]
	s_waitcnt vmcnt(8)
	s_barrier
	ds_read_b128 v[218:221], v102 offset:0
	ds_read_b128 v[222:225], v102 offset:2048
	ds_read_b128 v[226:229], v102 offset:4096
	ds_read_b128 v[230:233], v102 offset:6144
	ds_read_b128 v[234:237], v103 offset:0
	ds_read_b128 v[238:241], v103 offset:2048
	ds_read_b128 v[242:245], v103 offset:4096
	ds_read_b128 v[246:249], v103 offset:6144
	s_waitcnt lgkmcnt(4)
	v_mfma_f32_16x16x32_bf16 v[106:109], v[218:221], v[66:69], v[106:109]
	s_add_u32 m0, s4, 0xc000
	v_mfma_f32_16x16x32_bf16 v[122:125], v[222:225], v[66:69], v[122:125]
	global_load_lds_dwordx4 v98, s[6:7]
	v_mfma_f32_16x16x32_bf16 v[138:141], v[226:229], v[66:69], v[138:141]
	v_mfma_f32_16x16x32_bf16 v[162:165], v[230:233], v[66:69], v[162:165]
	v_mfma_f32_16x16x32_bf16 v[110:113], v[218:221], v[70:73], v[110:113]
	s_add_u32 m0, s4, 0xc400
	v_mfma_f32_16x16x32_bf16 v[126:129], v[222:225], v[70:73], v[126:129]
	global_load_lds_dwordx4 v99, s[6:7]
	v_mfma_f32_16x16x32_bf16 v[142:145], v[226:229], v[70:73], v[142:145]
	v_mfma_f32_16x16x32_bf16 v[166:169], v[230:233], v[70:73], v[166:169]
	v_mfma_f32_16x16x32_bf16 v[114:117], v[218:221], v[74:77], v[114:117]
	s_add_u32 m0, s4, 0xc800
	v_mfma_f32_16x16x32_bf16 v[130:133], v[222:225], v[74:77], v[130:133]
	global_load_lds_dwordx4 v100, s[6:7]
	v_mfma_f32_16x16x32_bf16 v[154:157], v[226:229], v[74:77], v[154:157]
	v_mfma_f32_16x16x32_bf16 v[170:173], v[230:233], v[74:77], v[170:173]
	v_mfma_f32_16x16x32_bf16 v[118:121], v[218:221], v[78:81], v[118:121]
	s_add_u32 m0, s4, 0xcc00
	v_mfma_f32_16x16x32_bf16 v[134:137], v[222:225], v[78:81], v[134:137]
	global_load_lds_dwordx4 v101, s[6:7]
	v_mfma_f32_16x16x32_bf16 v[158:161], v[226:229], v[78:81], v[158:161]
	v_mfma_f32_16x16x32_bf16 v[174:177], v[230:233], v[78:81], v[174:177]
	v_add_u32_e32 v98, 0x80, v98
	v_add_u32_e32 v99, 0x80, v99
	v_add_u32_e32 v100, 0x80, v100
	v_add_u32_e32 v101, 0x80, v101
	s_waitcnt lgkmcnt(0)
	v_mfma_f32_16x16x32_bf16 v[106:109], v[234:237], v[82:85], v[106:109]
	v_mfma_f32_16x16x32_bf16 v[122:125], v[238:241], v[82:85], v[122:125]
	v_mfma_f32_16x16x32_bf16 v[138:141], v[242:245], v[82:85], v[138:141]
	v_mfma_f32_16x16x32_bf16 v[162:165], v[246:249], v[82:85], v[162:165]
	v_mfma_f32_16x16x32_bf16 v[110:113], v[234:237], v[86:89], v[110:113]
	v_mfma_f32_16x16x32_bf16 v[126:129], v[238:241], v[86:89], v[126:129]
	v_mfma_f32_16x16x32_bf16 v[142:145], v[242:245], v[86:89], v[142:145]
	v_mfma_f32_16x16x32_bf16 v[166:169], v[246:249], v[86:89], v[166:169]
	v_mfma_f32_16x16x32_bf16 v[114:117], v[234:237], v[90:93], v[114:117]
	v_mfma_f32_16x16x32_bf16 v[130:133], v[238:241], v[90:93], v[130:133]
	v_mfma_f32_16x16x32_bf16 v[154:157], v[242:245], v[90:93], v[154:157]
	v_mfma_f32_16x16x32_bf16 v[170:173], v[246:249], v[90:93], v[170:173]
	v_mfma_f32_16x16x32_bf16 v[118:121], v[234:237], v[94:97], v[118:121]
	v_mfma_f32_16x16x32_bf16 v[134:137], v[238:241], v[94:97], v[134:137]
	v_mfma_f32_16x16x32_bf16 v[158:161], v[242:245], v[94:97], v[158:161]
	v_mfma_f32_16x16x32_bf16 v[174:177], v[246:249], v[94:97], v[174:177]
	s_waitcnt vmcnt(4)
	s_barrier
	ds_read_b128 v[218:221], v102 offset:16384
	ds_read_b128 v[222:225], v102 offset:18432
	ds_read_b128 v[226:229], v102 offset:20480
	ds_read_b128 v[230:233], v102 offset:22528
	ds_read_b128 v[66:69], v104 offset:32768
	ds_read_b128 v[70:73], v104 offset:34816
	ds_read_b128 v[74:77], v104 offset:36864
	ds_read_b128 v[78:81], v104 offset:38912
	ds_read_b128 v[234:237], v103 offset:16384
	ds_read_b128 v[238:241], v103 offset:18432
	ds_read_b128 v[242:245], v103 offset:20480
	ds_read_b128 v[246:249], v103 offset:22528
	ds_read_b128 v[82:85], v105 offset:32768
	ds_read_b128 v[86:89], v105 offset:34816
	ds_read_b128 v[90:93], v105 offset:36864
	ds_read_b128 v[94:97], v105 offset:38912
	s_waitcnt lgkmcnt(8)
	v_mfma_f32_16x16x32_bf16 v[62:65], v[218:221], v[66:69], v[62:65]
	s_add_u32 m0, s4, 0x0
	v_mfma_f32_16x16x32_bf16 v[46:49], v[222:225], v[66:69], v[46:49]
	global_load_lds_dwordx4 v98, s[28:29]
	v_mfma_f32_16x16x32_bf16 v[30:33], v[226:229], v[66:69], v[30:33]
	v_mfma_f32_16x16x32_bf16 v[14:17], v[230:233], v[66:69], v[14:17]
	v_mfma_f32_16x16x32_bf16 v[58:61], v[218:221], v[70:73], v[58:61]
	s_add_u32 m0, s4, 0x400
	v_mfma_f32_16x16x32_bf16 v[42:45], v[222:225], v[70:73], v[42:45]
	global_load_lds_dwordx4 v99, s[28:29]
	v_mfma_f32_16x16x32_bf16 v[26:29], v[226:229], v[70:73], v[26:29]
	v_mfma_f32_16x16x32_bf16 v[10:13], v[230:233], v[70:73], v[10:13]
	v_mfma_f32_16x16x32_bf16 v[54:57], v[218:221], v[74:77], v[54:57]
	s_add_u32 m0, s4, 0x800
	v_mfma_f32_16x16x32_bf16 v[38:41], v[222:225], v[74:77], v[38:41]
	global_load_lds_dwordx4 v100, s[28:29]
	v_mfma_f32_16x16x32_bf16 v[22:25], v[226:229], v[74:77], v[22:25]
	v_mfma_f32_16x16x32_bf16 v[6:9], v[230:233], v[74:77], v[6:9]
	v_mfma_f32_16x16x32_bf16 v[50:53], v[218:221], v[78:81], v[50:53]
	s_add_u32 m0, s4, 0xc00
	v_mfma_f32_16x16x32_bf16 v[34:37], v[222:225], v[78:81], v[34:37]
	global_load_lds_dwordx4 v101, s[28:29]
	v_mfma_f32_16x16x32_bf16 v[18:21], v[226:229], v[78:81], v[18:21]
	v_mfma_f32_16x16x32_bf16 v[2:5], v[230:233], v[78:81], v[2:5]
	s_waitcnt lgkmcnt(0)
	v_mfma_f32_16x16x32_bf16 v[62:65], v[234:237], v[82:85], v[62:65]
	s_add_u32 m0, s4, 0x10000
	v_mfma_f32_16x16x32_bf16 v[46:49], v[238:241], v[82:85], v[46:49]
	global_load_lds_dwordx4 v98, s[48:49]
	v_mfma_f32_16x16x32_bf16 v[30:33], v[242:245], v[82:85], v[30:33]
	v_mfma_f32_16x16x32_bf16 v[14:17], v[246:249], v[82:85], v[14:17]
	v_mfma_f32_16x16x32_bf16 v[58:61], v[234:237], v[86:89], v[58:61]
	s_add_u32 m0, s4, 0x10400
	v_mfma_f32_16x16x32_bf16 v[42:45], v[238:241], v[86:89], v[42:45]
	global_load_lds_dwordx4 v99, s[48:49]
	v_mfma_f32_16x16x32_bf16 v[26:29], v[242:245], v[86:89], v[26:29]
	v_mfma_f32_16x16x32_bf16 v[10:13], v[246:249], v[86:89], v[10:13]
	v_mfma_f32_16x16x32_bf16 v[54:57], v[234:237], v[90:93], v[54:57]
	s_add_u32 m0, s4, 0x10800
	v_mfma_f32_16x16x32_bf16 v[38:41], v[238:241], v[90:93], v[38:41]
	global_load_lds_dwordx4 v100, s[48:49]
	v_mfma_f32_16x16x32_bf16 v[22:25], v[242:245], v[90:93], v[22:25]
	v_mfma_f32_16x16x32_bf16 v[6:9], v[246:249], v[90:93], v[6:9]
	v_mfma_f32_16x16x32_bf16 v[50:53], v[234:237], v[94:97], v[50:53]
	s_add_u32 m0, s4, 0x10c00
	v_mfma_f32_16x16x32_bf16 v[34:37], v[238:241], v[94:97], v[34:37]
	global_load_lds_dwordx4 v101, s[48:49]
	v_mfma_f32_16x16x32_bf16 v[18:21], v[242:245], v[94:97], v[18:21]
	v_mfma_f32_16x16x32_bf16 v[2:5], v[246:249], v[94:97], v[2:5]
	s_waitcnt vmcnt(8)
	s_barrier
	ds_read_b128 v[218:221], v102 offset:49152
	ds_read_b128 v[222:225], v102 offset:51200
	ds_read_b128 v[226:229], v102 offset:53248
	ds_read_b128 v[230:233], v102 offset:55296
	ds_read_b128 v[234:237], v103 offset:49152
	ds_read_b128 v[238:241], v103 offset:51200
	ds_read_b128 v[242:245], v103 offset:53248
	ds_read_b128 v[246:249], v103 offset:55296
	s_waitcnt lgkmcnt(4)
	v_mfma_f32_16x16x32_bf16 v[106:109], v[218:221], v[66:69], v[106:109]
	s_add_u32 m0, s4, 0x4000
	v_mfma_f32_16x16x32_bf16 v[122:125], v[222:225], v[66:69], v[122:125]
	global_load_lds_dwordx4 v98, s[6:7]
	v_mfma_f32_16x16x32_bf16 v[138:141], v[226:229], v[66:69], v[138:141]
	v_mfma_f32_16x16x32_bf16 v[162:165], v[230:233], v[66:69], v[162:165]
	v_mfma_f32_16x16x32_bf16 v[110:113], v[218:221], v[70:73], v[110:113]
	s_add_u32 m0, s4, 0x4400
	v_mfma_f32_16x16x32_bf16 v[126:129], v[222:225], v[70:73], v[126:129]
	global_load_lds_dwordx4 v99, s[6:7]
	v_mfma_f32_16x16x32_bf16 v[142:145], v[226:229], v[70:73], v[142:145]
	v_mfma_f32_16x16x32_bf16 v[166:169], v[230:233], v[70:73], v[166:169]
	v_mfma_f32_16x16x32_bf16 v[114:117], v[218:221], v[74:77], v[114:117]
	s_add_u32 m0, s4, 0x4800
	v_mfma_f32_16x16x32_bf16 v[130:133], v[222:225], v[74:77], v[130:133]
	global_load_lds_dwordx4 v100, s[6:7]
	v_mfma_f32_16x16x32_bf16 v[154:157], v[226:229], v[74:77], v[154:157]
	v_mfma_f32_16x16x32_bf16 v[170:173], v[230:233], v[74:77], v[170:173]
	v_mfma_f32_16x16x32_bf16 v[118:121], v[218:221], v[78:81], v[118:121]
	s_add_u32 m0, s4, 0x4c00
	v_mfma_f32_16x16x32_bf16 v[134:137], v[222:225], v[78:81], v[134:137]
	global_load_lds_dwordx4 v101, s[6:7]
	v_mfma_f32_16x16x32_bf16 v[158:161], v[226:229], v[78:81], v[158:161]
	v_mfma_f32_16x16x32_bf16 v[174:177], v[230:233], v[78:81], v[174:177]
	v_add_u32_e32 v98, 0x80, v98
	v_add_u32_e32 v99, 0x80, v99
	v_add_u32_e32 v100, 0x80, v100
	v_add_u32_e32 v101, 0x80, v101
	s_waitcnt lgkmcnt(0)
	v_mfma_f32_16x16x32_bf16 v[106:109], v[234:237], v[82:85], v[106:109]
	v_mfma_f32_16x16x32_bf16 v[122:125], v[238:241], v[82:85], v[122:125]
	v_mfma_f32_16x16x32_bf16 v[138:141], v[242:245], v[82:85], v[138:141]
	v_mfma_f32_16x16x32_bf16 v[162:165], v[246:249], v[82:85], v[162:165]
	v_mfma_f32_16x16x32_bf16 v[110:113], v[234:237], v[86:89], v[110:113]
	v_mfma_f32_16x16x32_bf16 v[126:129], v[238:241], v[86:89], v[126:129]
	v_mfma_f32_16x16x32_bf16 v[142:145], v[242:245], v[86:89], v[142:145]
	v_mfma_f32_16x16x32_bf16 v[166:169], v[246:249], v[86:89], v[166:169]
	v_mfma_f32_16x16x32_bf16 v[114:117], v[234:237], v[90:93], v[114:117]
	v_mfma_f32_16x16x32_bf16 v[130:133], v[238:241], v[90:93], v[130:133]
	v_mfma_f32_16x16x32_bf16 v[154:157], v[242:245], v[90:93], v[154:157]
	v_mfma_f32_16x16x32_bf16 v[170:173], v[246:249], v[90:93], v[170:173]
	v_mfma_f32_16x16x32_bf16 v[118:121], v[234:237], v[94:97], v[118:121]
	v_mfma_f32_16x16x32_bf16 v[134:137], v[238:241], v[94:97], v[134:137]
	v_mfma_f32_16x16x32_bf16 v[158:161], v[242:245], v[94:97], v[158:161]
	v_mfma_f32_16x16x32_bf16 v[174:177], v[246:249], v[94:97], v[174:177]
	s_waitcnt vmcnt(4)
	s_barrier
	ds_read_b128 v[218:221], v102 offset:0
	ds_read_b128 v[222:225], v102 offset:2048
	ds_read_b128 v[226:229], v102 offset:4096
	ds_read_b128 v[230:233], v102 offset:6144
	ds_read_b128 v[66:69], v250 offset:49152
	ds_read_b128 v[70:73], v250 offset:51200
	ds_read_b128 v[74:77], v250 offset:53248
	ds_read_b128 v[78:81], v250 offset:55296
	ds_read_b128 v[234:237], v103 offset:0
	ds_read_b128 v[238:241], v103 offset:2048
	ds_read_b128 v[242:245], v103 offset:4096
	ds_read_b128 v[246:249], v103 offset:6144
	ds_read_b128 v[82:85], v251 offset:49152
	ds_read_b128 v[86:89], v251 offset:51200
	ds_read_b128 v[90:93], v251 offset:53248
	ds_read_b128 v[94:97], v251 offset:55296
	s_waitcnt lgkmcnt(8)
	v_mfma_f32_16x16x32_bf16 v[62:65], v[218:221], v[66:69], v[62:65]
	s_add_u32 m0, s4, 0xc000
	v_mfma_f32_16x16x32_bf16 v[46:49], v[222:225], v[66:69], v[46:49]
	global_load_lds_dwordx4 v98, s[28:29]
	v_mfma_f32_16x16x32_bf16 v[30:33], v[226:229], v[66:69], v[30:33]
	v_mfma_f32_16x16x32_bf16 v[14:17], v[230:233], v[66:69], v[14:17]
	v_mfma_f32_16x16x32_bf16 v[58:61], v[218:221], v[70:73], v[58:61]
	s_add_u32 m0, s4, 0xc400
	v_mfma_f32_16x16x32_bf16 v[42:45], v[222:225], v[70:73], v[42:45]
	global_load_lds_dwordx4 v99, s[28:29]
	v_mfma_f32_16x16x32_bf16 v[26:29], v[226:229], v[70:73], v[26:29]
	v_mfma_f32_16x16x32_bf16 v[10:13], v[230:233], v[70:73], v[10:13]
	v_mfma_f32_16x16x32_bf16 v[54:57], v[218:221], v[74:77], v[54:57]
	s_add_u32 m0, s4, 0xc800
	v_mfma_f32_16x16x32_bf16 v[38:41], v[222:225], v[74:77], v[38:41]
	global_load_lds_dwordx4 v100, s[28:29]
	v_mfma_f32_16x16x32_bf16 v[22:25], v[226:229], v[74:77], v[22:25]
	v_mfma_f32_16x16x32_bf16 v[6:9], v[230:233], v[74:77], v[6:9]
	v_mfma_f32_16x16x32_bf16 v[50:53], v[218:221], v[78:81], v[50:53]
	s_add_u32 m0, s4, 0xcc00
	v_mfma_f32_16x16x32_bf16 v[34:37], v[222:225], v[78:81], v[34:37]
	global_load_lds_dwordx4 v101, s[28:29]
	v_mfma_f32_16x16x32_bf16 v[18:21], v[226:229], v[78:81], v[18:21]
	v_mfma_f32_16x16x32_bf16 v[2:5], v[230:233], v[78:81], v[2:5]
	s_waitcnt lgkmcnt(0)
	v_mfma_f32_16x16x32_bf16 v[62:65], v[234:237], v[82:85], v[62:65]
	s_add_u32 m0, s4, 0x8000
	v_mfma_f32_16x16x32_bf16 v[46:49], v[238:241], v[82:85], v[46:49]
	global_load_lds_dwordx4 v98, s[48:49]
	v_mfma_f32_16x16x32_bf16 v[30:33], v[242:245], v[82:85], v[30:33]
	v_mfma_f32_16x16x32_bf16 v[14:17], v[246:249], v[82:85], v[14:17]
	v_mfma_f32_16x16x32_bf16 v[58:61], v[234:237], v[86:89], v[58:61]
	s_add_u32 m0, s4, 0x8400
	v_mfma_f32_16x16x32_bf16 v[42:45], v[238:241], v[86:89], v[42:45]
	global_load_lds_dwordx4 v99, s[48:49]
	v_mfma_f32_16x16x32_bf16 v[26:29], v[242:245], v[86:89], v[26:29]
	v_mfma_f32_16x16x32_bf16 v[10:13], v[246:249], v[86:89], v[10:13]
	v_mfma_f32_16x16x32_bf16 v[54:57], v[234:237], v[90:93], v[54:57]
	s_add_u32 m0, s4, 0x8800
	v_mfma_f32_16x16x32_bf16 v[38:41], v[238:241], v[90:93], v[38:41]
	global_load_lds_dwordx4 v100, s[48:49]
	v_mfma_f32_16x16x32_bf16 v[22:25], v[242:245], v[90:93], v[22:25]
	v_mfma_f32_16x16x32_bf16 v[6:9], v[246:249], v[90:93], v[6:9]
	v_mfma_f32_16x16x32_bf16 v[50:53], v[234:237], v[94:97], v[50:53]
	s_add_u32 m0, s4, 0x8c00
	v_mfma_f32_16x16x32_bf16 v[34:37], v[238:241], v[94:97], v[34:37]
	global_load_lds_dwordx4 v101, s[48:49]
	v_mfma_f32_16x16x32_bf16 v[18:21], v[242:245], v[94:97], v[18:21]
	v_mfma_f32_16x16x32_bf16 v[2:5], v[246:249], v[94:97], v[2:5]
	s_waitcnt vmcnt(8)
	s_barrier
	ds_read_b128 v[218:221], v102 offset:16384
	ds_read_b128 v[222:225], v102 offset:18432
	ds_read_b128 v[226:229], v102 offset:20480
	ds_read_b128 v[230:233], v102 offset:22528
	ds_read_b128 v[234:237], v103 offset:16384
	ds_read_b128 v[238:241], v103 offset:18432
	ds_read_b128 v[242:245], v103 offset:20480
	ds_read_b128 v[246:249], v103 offset:22528
	s_waitcnt lgkmcnt(4)
	v_mfma_f32_16x16x32_bf16 v[106:109], v[218:221], v[66:69], v[106:109]
	s_add_u32 m0, s4, 0x0
	v_mfma_f32_16x16x32_bf16 v[122:125], v[222:225], v[66:69], v[122:125]
	global_load_lds_dwordx4 v98, s[6:7]
	v_mfma_f32_16x16x32_bf16 v[138:141], v[226:229], v[66:69], v[138:141]
	v_mfma_f32_16x16x32_bf16 v[162:165], v[230:233], v[66:69], v[162:165]
	v_mfma_f32_16x16x32_bf16 v[110:113], v[218:221], v[70:73], v[110:113]
	s_add_u32 m0, s4, 0x400
	v_mfma_f32_16x16x32_bf16 v[126:129], v[222:225], v[70:73], v[126:129]
	global_load_lds_dwordx4 v99, s[6:7]
	v_mfma_f32_16x16x32_bf16 v[142:145], v[226:229], v[70:73], v[142:145]
	v_mfma_f32_16x16x32_bf16 v[166:169], v[230:233], v[70:73], v[166:169]
	v_mfma_f32_16x16x32_bf16 v[114:117], v[218:221], v[74:77], v[114:117]
	s_add_u32 m0, s4, 0x800
	v_mfma_f32_16x16x32_bf16 v[130:133], v[222:225], v[74:77], v[130:133]
	global_load_lds_dwordx4 v100, s[6:7]
	v_mfma_f32_16x16x32_bf16 v[154:157], v[226:229], v[74:77], v[154:157]
	v_mfma_f32_16x16x32_bf16 v[170:173], v[230:233], v[74:77], v[170:173]
	v_mfma_f32_16x16x32_bf16 v[118:121], v[218:221], v[78:81], v[118:121]
	s_add_u32 m0, s4, 0xc00
	v_mfma_f32_16x16x32_bf16 v[134:137], v[222:225], v[78:81], v[134:137]
	global_load_lds_dwordx4 v101, s[6:7]
	v_mfma_f32_16x16x32_bf16 v[158:161], v[226:229], v[78:81], v[158:161]
	v_mfma_f32_16x16x32_bf16 v[174:177], v[230:233], v[78:81], v[174:177]
	v_add_u32_e32 v98, 0x80, v98
	v_add_u32_e32 v99, 0x80, v99
	v_add_u32_e32 v100, 0x80, v100
	v_add_u32_e32 v101, 0x80, v101
	s_waitcnt lgkmcnt(0)
	v_mfma_f32_16x16x32_bf16 v[106:109], v[234:237], v[82:85], v[106:109]
	v_mfma_f32_16x16x32_bf16 v[122:125], v[238:241], v[82:85], v[122:125]
	v_mfma_f32_16x16x32_bf16 v[138:141], v[242:245], v[82:85], v[138:141]
	v_mfma_f32_16x16x32_bf16 v[162:165], v[246:249], v[82:85], v[162:165]
	v_mfma_f32_16x16x32_bf16 v[110:113], v[234:237], v[86:89], v[110:113]
	v_mfma_f32_16x16x32_bf16 v[126:129], v[238:241], v[86:89], v[126:129]
	v_mfma_f32_16x16x32_bf16 v[142:145], v[242:245], v[86:89], v[142:145]
	v_mfma_f32_16x16x32_bf16 v[166:169], v[246:249], v[86:89], v[166:169]
	v_mfma_f32_16x16x32_bf16 v[114:117], v[234:237], v[90:93], v[114:117]
	v_mfma_f32_16x16x32_bf16 v[130:133], v[238:241], v[90:93], v[130:133]
	v_mfma_f32_16x16x32_bf16 v[154:157], v[242:245], v[90:93], v[154:157]
	v_mfma_f32_16x16x32_bf16 v[170:173], v[246:249], v[90:93], v[170:173]
	v_mfma_f32_16x16x32_bf16 v[118:121], v[234:237], v[94:97], v[118:121]
	v_mfma_f32_16x16x32_bf16 v[134:137], v[238:241], v[94:97], v[134:137]
	v_mfma_f32_16x16x32_bf16 v[158:161], v[242:245], v[94:97], v[158:161]
	v_mfma_f32_16x16x32_bf16 v[174:177], v[246:249], v[94:97], v[174:177]
	s_waitcnt vmcnt(4)
	s_barrier
	ds_read_b128 v[218:221], v102 offset:49152
	ds_read_b128 v[222:225], v102 offset:51200
	ds_read_b128 v[226:229], v102 offset:53248
	ds_read_b128 v[230:233], v102 offset:55296
	ds_read_b128 v[66:69], v104 offset:32768
	ds_read_b128 v[70:73], v104 offset:34816
	ds_read_b128 v[74:77], v104 offset:36864
	ds_read_b128 v[78:81], v104 offset:38912
	ds_read_b128 v[234:237], v103 offset:49152
	ds_read_b128 v[238:241], v103 offset:51200
	ds_read_b128 v[242:245], v103 offset:53248
	ds_read_b128 v[246:249], v103 offset:55296
	ds_read_b128 v[82:85], v105 offset:32768
	ds_read_b128 v[86:89], v105 offset:34816
	ds_read_b128 v[90:93], v105 offset:36864
	ds_read_b128 v[94:97], v105 offset:38912
	s_waitcnt lgkmcnt(8)
	v_mfma_f32_16x16x32_bf16 v[62:65], v[218:221], v[66:69], v[62:65]
	v_mfma_f32_16x16x32_bf16 v[46:49], v[222:225], v[66:69], v[46:49]
	v_mfma_f32_16x16x32_bf16 v[30:33], v[226:229], v[66:69], v[30:33]
	v_mfma_f32_16x16x32_bf16 v[14:17], v[230:233], v[66:69], v[14:17]
	v_mfma_f32_16x16x32_bf16 v[58:61], v[218:221], v[70:73], v[58:61]
	v_mfma_f32_16x16x32_bf16 v[42:45], v[222:225], v[70:73], v[42:45]
	v_mfma_f32_16x16x32_bf16 v[26:29], v[226:229], v[70:73], v[26:29]
	v_mfma_f32_16x16x32_bf16 v[10:13], v[230:233], v[70:73], v[10:13]
	v_mfma_f32_16x16x32_bf16 v[54:57], v[218:221], v[74:77], v[54:57]
	v_mfma_f32_16x16x32_bf16 v[38:41], v[222:225], v[74:77], v[38:41]
	v_mfma_f32_16x16x32_bf16 v[22:25], v[226:229], v[74:77], v[22:25]
	v_mfma_f32_16x16x32_bf16 v[6:9], v[230:233], v[74:77], v[6:9]
	v_mfma_f32_16x16x32_bf16 v[50:53], v[218:221], v[78:81], v[50:53]
	v_mfma_f32_16x16x32_bf16 v[34:37], v[222:225], v[78:81], v[34:37]
	v_mfma_f32_16x16x32_bf16 v[18:21], v[226:229], v[78:81], v[18:21]
	v_mfma_f32_16x16x32_bf16 v[2:5], v[230:233], v[78:81], v[2:5]
	s_waitcnt lgkmcnt(0)
	v_mfma_f32_16x16x32_bf16 v[62:65], v[234:237], v[82:85], v[62:65]
	v_mfma_f32_16x16x32_bf16 v[46:49], v[238:241], v[82:85], v[46:49]
	v_mfma_f32_16x16x32_bf16 v[30:33], v[242:245], v[82:85], v[30:33]
	v_mfma_f32_16x16x32_bf16 v[14:17], v[246:249], v[82:85], v[14:17]
	v_mfma_f32_16x16x32_bf16 v[58:61], v[234:237], v[86:89], v[58:61]
	v_mfma_f32_16x16x32_bf16 v[42:45], v[238:241], v[86:89], v[42:45]
	v_mfma_f32_16x16x32_bf16 v[26:29], v[242:245], v[86:89], v[26:29]
	v_mfma_f32_16x16x32_bf16 v[10:13], v[246:249], v[86:89], v[10:13]
	v_mfma_f32_16x16x32_bf16 v[54:57], v[234:237], v[90:93], v[54:57]
	v_mfma_f32_16x16x32_bf16 v[38:41], v[238:241], v[90:93], v[38:41]
	v_mfma_f32_16x16x32_bf16 v[22:25], v[242:245], v[90:93], v[22:25]
	v_mfma_f32_16x16x32_bf16 v[6:9], v[246:249], v[90:93], v[6:9]
	v_mfma_f32_16x16x32_bf16 v[50:53], v[234:237], v[94:97], v[50:53]
	v_mfma_f32_16x16x32_bf16 v[34:37], v[238:241], v[94:97], v[34:37]
	v_mfma_f32_16x16x32_bf16 v[18:21], v[242:245], v[94:97], v[18:21]
	v_mfma_f32_16x16x32_bf16 v[2:5], v[246:249], v[94:97], v[2:5]
	s_waitcnt vmcnt(0)
	s_barrier
	ds_read_b128 v[218:221], v102 offset:0
	ds_read_b128 v[222:225], v102 offset:2048
	ds_read_b128 v[226:229], v102 offset:4096
	ds_read_b128 v[230:233], v102 offset:6144
	ds_read_b128 v[234:237], v103 offset:0
	ds_read_b128 v[238:241], v103 offset:2048
	ds_read_b128 v[242:245], v103 offset:4096
	ds_read_b128 v[246:249], v103 offset:6144
	s_waitcnt lgkmcnt(4)
	v_mfma_f32_16x16x32_bf16 v[106:109], v[218:221], v[66:69], v[106:109]
	v_mfma_f32_16x16x32_bf16 v[122:125], v[222:225], v[66:69], v[122:125]
	v_mfma_f32_16x16x32_bf16 v[138:141], v[226:229], v[66:69], v[138:141]
	v_mfma_f32_16x16x32_bf16 v[162:165], v[230:233], v[66:69], v[162:165]
	v_mfma_f32_16x16x32_bf16 v[110:113], v[218:221], v[70:73], v[110:113]
	v_mfma_f32_16x16x32_bf16 v[126:129], v[222:225], v[70:73], v[126:129]
	v_mfma_f32_16x16x32_bf16 v[142:145], v[226:229], v[70:73], v[142:145]
	v_mfma_f32_16x16x32_bf16 v[166:169], v[230:233], v[70:73], v[166:169]
	v_mfma_f32_16x16x32_bf16 v[114:117], v[218:221], v[74:77], v[114:117]
	v_mfma_f32_16x16x32_bf16 v[130:133], v[222:225], v[74:77], v[130:133]
	v_mfma_f32_16x16x32_bf16 v[154:157], v[226:229], v[74:77], v[154:157]
	v_mfma_f32_16x16x32_bf16 v[170:173], v[230:233], v[74:77], v[170:173]
	v_mfma_f32_16x16x32_bf16 v[118:121], v[218:221], v[78:81], v[118:121]
	v_mfma_f32_16x16x32_bf16 v[134:137], v[222:225], v[78:81], v[134:137]
	v_mfma_f32_16x16x32_bf16 v[158:161], v[226:229], v[78:81], v[158:161]
	v_mfma_f32_16x16x32_bf16 v[174:177], v[230:233], v[78:81], v[174:177]
	s_waitcnt lgkmcnt(0)
	v_mfma_f32_16x16x32_bf16 v[106:109], v[234:237], v[82:85], v[106:109]
	v_mfma_f32_16x16x32_bf16 v[122:125], v[238:241], v[82:85], v[122:125]
	v_mfma_f32_16x16x32_bf16 v[138:141], v[242:245], v[82:85], v[138:141]
	v_mfma_f32_16x16x32_bf16 v[162:165], v[246:249], v[82:85], v[162:165]
	v_mfma_f32_16x16x32_bf16 v[110:113], v[234:237], v[86:89], v[110:113]
	v_mfma_f32_16x16x32_bf16 v[126:129], v[238:241], v[86:89], v[126:129]
	v_mfma_f32_16x16x32_bf16 v[142:145], v[242:245], v[86:89], v[142:145]
	v_mfma_f32_16x16x32_bf16 v[166:169], v[246:249], v[86:89], v[166:169]
	v_mfma_f32_16x16x32_bf16 v[114:117], v[234:237], v[90:93], v[114:117]
	v_mfma_f32_16x16x32_bf16 v[130:133], v[238:241], v[90:93], v[130:133]
	v_mfma_f32_16x16x32_bf16 v[154:157], v[242:245], v[90:93], v[154:157]
	v_mfma_f32_16x16x32_bf16 v[170:173], v[246:249], v[90:93], v[170:173]
	v_mfma_f32_16x16x32_bf16 v[118:121], v[234:237], v[94:97], v[118:121]
	v_mfma_f32_16x16x32_bf16 v[134:137], v[238:241], v[94:97], v[134:137]
	v_mfma_f32_16x16x32_bf16 v[158:161], v[242:245], v[94:97], v[158:161]
	v_mfma_f32_16x16x32_bf16 v[174:177], v[246:249], v[94:97], v[174:177]
	s_nop 7
	s_barrier
	s_and_b32 s5, s100, 0xff
	s_cmp_lt_u32 s5, 4
	s_cbranch_scc0 .Lpk_tt_nopf
	s_add_i32 s5, s5, 1
	s_lshl_b32 s5, s5, 6
	v_readlane_b32 s6, v254, 7
	s_add_i32 s5, s5, s6
	s_mul_hi_u32 s6, s5, 0x924924a
	s_mul_i32 s7, s6, 28
	s_sub_u32 s5, s5, s7
	s_mul_hi_u32 s7, s5, 0x24924925
	s_mul_i32 s28, s7, 7
	s_sub_u32 s5, s5, s28
	s_and_b32 s28, s6, 3
	s_mul_i32 s28, s28, 7
	s_add_i32 s28, s28, s5
	s_lshl_b32 s48, s28, 18
	s_add_u32 s48, s12, s48
	s_addc_u32 s49, s13, 0
	s_lshr_b32 s6, s6, 2
	s_lshl_b32 s6, s6, 3
	v_readlane_b32 s5, v254, 6
	s_or_b32 s6, s6, s5
	s_lshl_b32 s6, s6, 3
	s_lshl_b32 s7, s7, 1
	s_add_i32 s6, s6, s7
	s_lshl_b32 s6, s6, 18
	s_add_u32 s28, s94, s6
	s_addc_u32 s29, s95, 0
	v_add_u32_e32 v98, 0xfffff800, v98
	v_add_u32_e32 v99, 0xfffff800, v99
	v_add_u32_e32 v100, 0xfffff800, v100
	v_add_u32_e32 v101, 0xfffff800, v101
	s_add_u32 m0, s4, 0xc000
	s_nop 0
	global_load_lds_dwordx4 v98, s[28:29]
	s_add_u32 m0, s4, 0xc400
	s_nop 0
	global_load_lds_dwordx4 v99, s[28:29]
	s_add_u32 m0, s4, 0xc800
	s_nop 0
	global_load_lds_dwordx4 v100, s[28:29]
	s_add_u32 m0, s4, 0xcc00
	s_nop 0
	global_load_lds_dwordx4 v101, s[28:29]
	s_add_u32 m0, s4, 0x10000
	s_nop 0
	global_load_lds_dwordx4 v98, s[48:49]
	s_add_u32 m0, s4, 0x10400
	s_nop 0
	global_load_lds_dwordx4 v99, s[48:49]
	s_add_u32 m0, s4, 0x10800
	s_nop 0
	global_load_lds_dwordx4 v100, s[48:49]
	s_add_u32 m0, s4, 0x10c00
	s_nop 0
	global_load_lds_dwordx4 v101, s[48:49]
	s_or_b32 s100, s100, 0x1000
	s_branch .Lpk_tt_end

.Lpk_tt_end:
	s_branch .LBB0_260
.Lpk_tt_unpark:
	s_barrier
	v_mov_b32_e32 v62, v106
	v_mov_b32_e32 v63, v107
	v_mov_b32_e32 v64, v108
	v_mov_b32_e32 v65, v109
	v_mov_b32_e32 v58, v110
	v_mov_b32_e32 v59, v111
	v_mov_b32_e32 v60, v112
	v_mov_b32_e32 v61, v113
	v_mov_b32_e32 v54, v114
	v_mov_b32_e32 v55, v115
	v_mov_b32_e32 v56, v116
	v_mov_b32_e32 v57, v117
	v_mov_b32_e32 v50, v118
	v_mov_b32_e32 v51, v119
	v_mov_b32_e32 v52, v120
	v_mov_b32_e32 v53, v121
	v_mov_b32_e32 v46, v122
	v_mov_b32_e32 v47, v123
	v_mov_b32_e32 v48, v124
	v_mov_b32_e32 v49, v125
	v_mov_b32_e32 v42, v126
	v_mov_b32_e32 v43, v127
	v_mov_b32_e32 v44, v128
	v_mov_b32_e32 v45, v129
	v_mov_b32_e32 v38, v130
	v_mov_b32_e32 v39, v131
	v_mov_b32_e32 v40, v132
	v_mov_b32_e32 v41, v133
	v_mov_b32_e32 v34, v134
	v_mov_b32_e32 v35, v135
	v_mov_b32_e32 v36, v136
	v_mov_b32_e32 v37, v137
	v_mov_b32_e32 v30, v138
	v_mov_b32_e32 v31, v139
	v_mov_b32_e32 v32, v140
	v_mov_b32_e32 v33, v141
	v_mov_b32_e32 v26, v142
	v_mov_b32_e32 v27, v143
	v_mov_b32_e32 v28, v144
	v_mov_b32_e32 v29, v145
	v_mov_b32_e32 v22, v154
	v_mov_b32_e32 v23, v155
	v_mov_b32_e32 v24, v156
	v_mov_b32_e32 v25, v157
	v_mov_b32_e32 v18, v158
	v_mov_b32_e32 v19, v159
	v_mov_b32_e32 v20, v160
	v_mov_b32_e32 v21, v161
	v_mov_b32_e32 v14, v162
	v_mov_b32_e32 v15, v163
	v_mov_b32_e32 v16, v164
	v_mov_b32_e32 v17, v165
	v_mov_b32_e32 v10, v166
	v_mov_b32_e32 v11, v167
	v_mov_b32_e32 v12, v168
	v_mov_b32_e32 v13, v169
	v_mov_b32_e32 v6, v170
	v_mov_b32_e32 v7, v171
	v_mov_b32_e32 v8, v172
	v_mov_b32_e32 v9, v173
	v_mov_b32_e32 v2, v174
	v_mov_b32_e32 v3, v175
	v_mov_b32_e32 v4, v176
	v_mov_b32_e32 v5, v177
	s_branch .LBB0_260
